# GEMM K-loops: LDS-DMA addresses via SGPR base + 32-bit VGPR offset (saddr form) instead of 64-bit VALU adds; plus br0 barrier removal
# speedup vs baseline: 1.0174x; 1.0174x over previous
; #define PG8_STAGE(bufoff, gbase, voff) do { _Pragma("unroll") for (int _i = 0; _i < 2; ++_i) \
;         __builtin_amdgcn_global_load_lds((const unsigned*)((const char*)(gbase) + (voff)[_i]), (LAS unsigned*)(lds + (bufoff) + ldsw + _i * 8192), 16, 0, 0); } while (0)
; #define PG8_LDA(dst, b, h) do { _Pragma("unroll") for (int m = 0; m < 4; ++m) _Pragma("unroll") for (int k = 0; k < 2; ++k) dst[m][k] = *(const LAS bf16x8*)(lds + PG8_SA(b, h) + aoff + m * 2048 + k * 1024); } while (0)
; #define PG8_LDB(dst, b, h) do { _Pragma("unroll") for (int n = 0; n < 2; ++n) _Pragma("unroll") for (int k = 0; k < 2; ++k) dst[n][k] = *(const LAS bf16x8*)(lds + PG8_SB(b, h) + boff + n * 2048 + k * 1024); } while (0)
; #define PG8_MMA(ai, bj, At, Bt) do { __builtin_amdgcn_s_setprio(1); _Pragma("unroll") for (int m = 0; m < 4; ++m) _Pragma("unroll") for (int n = 0; n < 2; ++n) _Pragma("unroll") for (int k = 0; k < 2; ++k) \
;         acc[ai][bj][m][n] = __builtin_amdgcn_mfma_f32_16x16x32_bf16(Bt[n][k], At[m][k], acc[ai][bj][m][n], 0, 0, 0); __builtin_amdgcn_s_setprio(0); } while (0)
; #define PG8_WAIT_L(n) asm volatile("s_waitcnt lgkmcnt(" #n ")" ::: "memory")
; #define PG8_BAR __builtin_amdgcn_s_barrier()
; #define PG8_SCHED __builtin_amdgcn_sched_barrier(0)
; template <class Epi>
; __device__ __forceinline__ void gemm_phase(LAS unsigned char* lds, const Gemm g, const StaticOrder& S, const Epi& E) {
;     ...
;         for (int t = 0; t < nt; t += 2) {
;             const bool last = (t == nt - 2);
;             const char* a1 = cA + (size_t)(t + 1) * kstep;
;             const char* a2 = last ? nA : cA + (size_t)(t + 2) * kstep; const char* b2 = last ? nB : cB + (size_t)(t + 2) * kstep;
;             const char* a3 = a2 + kstep; const char* b3 = b2 + kstep;
;             PG8_LDB(B0, 0, 0); PG8_SCHED; PG8_LDA(At, 0, 0); PG8_STAGE(PG8_SA(1, 1), a1 + hstep, voffA);
;             PG8_WAIT_L(8); PG8_BAR; PG8_WAIT_L(0); PG8_MMA(0, 0, At, B0); PG8_BAR; PG8_SCHED;
;             PG8_LDB(B1, 0, 1); PG8_STAGE(PG8_SB(0, 0), b2, voffB);
;             PG8_BAR; PG8_WAIT_L(0); PG8_MMA(0, 1, At, B1); PG8_BAR;
;             PG8_LDA(At, 0, 1); PG8_STAGE(PG8_SA(0, 0), a2, voffA);
;             PG8_BAR; PG8_WAIT_L(0); PG8_MMA(1, 0, At, B0); PG8_BAR; PG8_SCHED;
.LBB0_64:
	s_add_u32 s58, s56, 0xfff80080
	s_addc_u32 s59, s57, -1
	s_add_i32 s86, 0, 0x10000
	v_add_u32_e32 v140, s86, v143
	ds_read_b128 v[154:157], v140
	ds_read_b128 v[158:161], v140 offset:1024
	ds_read_b128 v[162:165], v140 offset:2048
	ds_read_b128 v[166:169], v140 offset:3072
	s_cmp_eq_u32 s85, 28
	s_cselect_b32 s61, s49, s59
	s_cselect_b32 s60, s81, s58
	s_cselect_b32 s59, s47, s84
	s_cselect_b32 s58, s82, s83
	s_add_i32 m0, s55, 0xc000
	ds_read_b128 v[170:173], v151
	ds_read_b128 v[174:177], v151 offset:1024
	ds_read_b128 v[178:181], v151 offset:2048
	ds_read_b128 v[182:185], v151 offset:3072
	ds_read_b128 v[186:189], v151 offset:4096
	ds_read_b128 v[190:193], v151 offset:5120
	ds_read_b128 v[194:197], v151 offset:6144
	ds_read_b128 v[198:201], v151 offset:7168
	global_load_lds_dwordx4 v136, s[56:57]
	s_add_i32 m0, s55, 0xe000
	s_nop 0
	global_load_lds_dwordx4 v138, s[56:57]
	s_waitcnt lgkmcnt(8)
	s_barrier
	s_waitcnt lgkmcnt(0)
	s_setprio 1
	s_waitcnt lgkmcnt(0)
	v_mfma_f32_16x16x32_bf16 v[126:129], v[154:157], v[170:173], v[126:129]
	v_mfma_f32_16x16x32_bf16 v[122:125], v[162:165], v[170:173], v[122:125]
	v_mfma_f32_16x16x32_bf16 v[110:113], v[154:157], v[178:181], v[110:113]
	v_mfma_f32_16x16x32_bf16 v[106:109], v[162:165], v[178:181], v[106:109]
	v_mfma_f32_16x16x32_bf16 v[94:97], v[154:157], v[186:189], v[94:97]
	v_mfma_f32_16x16x32_bf16 v[90:93], v[162:165], v[186:189], v[90:93]
	v_mfma_f32_16x16x32_bf16 v[78:81], v[154:157], v[194:197], v[78:81]
	v_mfma_f32_16x16x32_bf16 v[74:77], v[162:165], v[194:197], v[74:77]
	v_mfma_f32_16x16x32_bf16 v[126:129], v[158:161], v[174:177], v[126:129]
	v_mfma_f32_16x16x32_bf16 v[122:125], v[166:169], v[174:177], v[122:125]
	v_mfma_f32_16x16x32_bf16 v[110:113], v[158:161], v[182:185], v[110:113]
	v_mfma_f32_16x16x32_bf16 v[106:109], v[166:169], v[182:185], v[106:109]
	v_mfma_f32_16x16x32_bf16 v[94:97], v[158:161], v[190:193], v[94:97]
	v_mfma_f32_16x16x32_bf16 v[90:93], v[166:169], v[190:193], v[90:93]
	v_mfma_f32_16x16x32_bf16 v[78:81], v[158:161], v[198:201], v[78:81]
	v_mfma_f32_16x16x32_bf16 v[74:77], v[166:169], v[198:201], v[74:77]
	s_setprio 0
	s_barrier
	s_add_i32 s88, 0, 0x14000
	s_add_i32 s86, s86, s69
	v_add_u32_e32 v140, s88, v143
	s_add_u32 s98, s58, s22
	s_addc_u32 s99, s59, s23
	s_mov_b32 m0, s86
	ds_read_b128 v[208:211], v140
	ds_read_b128 v[212:215], v140 offset:1024
	ds_read_b128 v[216:219], v140 offset:2048
	ds_read_b128 v[220:223], v140 offset:3072
	global_load_lds_dwordx4 v0, s[58:59]
	s_add_i32 m0, s86, 0x2000
	s_nop 0
	global_load_lds_dwordx4 v130, s[58:59]
	s_barrier
	s_waitcnt lgkmcnt(0)
	s_setprio 1
	s_waitcnt lgkmcnt(0)
	v_mfma_f32_16x16x32_bf16 v[118:121], v[208:211], v[170:173], v[118:121]
	v_mfma_f32_16x16x32_bf16 v[114:117], v[216:219], v[170:173], v[114:117]
	v_mfma_f32_16x16x32_bf16 v[102:105], v[208:211], v[178:181], v[102:105]
	v_mfma_f32_16x16x32_bf16 v[98:101], v[216:219], v[178:181], v[98:101]
	v_mfma_f32_16x16x32_bf16 v[86:89], v[208:211], v[186:189], v[86:89]
	v_mfma_f32_16x16x32_bf16 v[82:85], v[216:219], v[186:189], v[82:85]
	v_mfma_f32_16x16x32_bf16 v[70:73], v[208:211], v[194:197], v[70:73]
	v_mfma_f32_16x16x32_bf16 v[66:69], v[216:219], v[194:197], v[66:69]
	v_mfma_f32_16x16x32_bf16 v[118:121], v[212:215], v[174:177], v[118:121]
	v_mfma_f32_16x16x32_bf16 v[114:117], v[220:223], v[174:177], v[114:117]
	v_mfma_f32_16x16x32_bf16 v[102:105], v[212:215], v[182:185], v[102:105]
	v_mfma_f32_16x16x32_bf16 v[98:101], v[220:223], v[182:185], v[98:101]
	v_mfma_f32_16x16x32_bf16 v[86:89], v[212:215], v[190:193], v[86:89]
	v_mfma_f32_16x16x32_bf16 v[82:85], v[220:223], v[190:193], v[82:85]
	v_mfma_f32_16x16x32_bf16 v[70:73], v[212:215], v[198:201], v[70:73]
	v_mfma_f32_16x16x32_bf16 v[66:69], v[220:223], v[198:201], v[66:69]
	s_setprio 0
	s_mov_b32 m0, s55
	s_add_u32 s100, s60, s22
	s_addc_u32 s101, s61, s23
	s_barrier
	ds_read_b128 v[170:173], v151 offset:16384
	ds_read_b128 v[174:177], v151 offset:17408
	ds_read_b128 v[178:181], v151 offset:18432
	ds_read_b128 v[182:185], v151 offset:19456
	ds_read_b128 v[186:189], v151 offset:20480
	ds_read_b128 v[190:193], v151 offset:21504
	ds_read_b128 v[194:197], v151 offset:22528
	ds_read_b128 v[198:201], v151 offset:23552
	global_load_lds_dwordx4 v134, s[60:61]
	s_mov_b32 m0, s72
	s_nop 0
	global_load_lds_dwordx4 v132, s[60:61]
	s_barrier
	s_waitcnt lgkmcnt(0)
	s_setprio 1
	s_waitcnt lgkmcnt(0)
	v_mfma_f32_16x16x32_bf16 v[62:65], v[154:157], v[170:173], v[62:65]
	v_mfma_f32_16x16x32_bf16 v[58:61], v[162:165], v[170:173], v[58:61]
	v_mfma_f32_16x16x32_bf16 v[54:57], v[154:157], v[178:181], v[54:57]
	v_mfma_f32_16x16x32_bf16 v[46:49], v[162:165], v[178:181], v[46:49]
	v_mfma_f32_16x16x32_bf16 v[38:41], v[154:157], v[186:189], v[38:41]
	v_mfma_f32_16x16x32_bf16 v[30:33], v[162:165], v[186:189], v[30:33]
	v_mfma_f32_16x16x32_bf16 v[22:25], v[154:157], v[194:197], v[22:25]
	v_mfma_f32_16x16x32_bf16 v[14:17], v[162:165], v[194:197], v[14:17]
	v_mfma_f32_16x16x32_bf16 v[62:65], v[158:161], v[174:177], v[62:65]
	v_mfma_f32_16x16x32_bf16 v[58:61], v[166:169], v[174:177], v[58:61]
	v_mfma_f32_16x16x32_bf16 v[54:57], v[158:161], v[182:185], v[54:57]
	v_mfma_f32_16x16x32_bf16 v[46:49], v[166:169], v[182:185], v[46:49]
	v_mfma_f32_16x16x32_bf16 v[38:41], v[158:161], v[190:193], v[38:41]
	v_mfma_f32_16x16x32_bf16 v[30:33], v[166:169], v[190:193], v[30:33]
	v_mfma_f32_16x16x32_bf16 v[22:25], v[158:161], v[198:201], v[22:25]
	v_mfma_f32_16x16x32_bf16 v[14:17], v[166:169], v[198:201], v[14:17]
	s_setprio 0
	s_barrier
; #define PG8_STAGE(bufoff, gbase, voff) do { _Pragma("unroll") for (int _i = 0; _i < 2; ++_i) \
;         __builtin_amdgcn_global_load_lds((const unsigned*)((const char*)(gbase) + (voff)[_i]), (LAS unsigned*)(lds + (bufoff) + ldsw + _i * 8192), 16, 0, 0); } while (0)
; #define PG8_LDA(dst, b, h) do { _Pragma("unroll") for (int m = 0; m < 4; ++m) _Pragma("unroll") for (int k = 0; k < 2; ++k) dst[m][k] = *(const LAS bf16x8*)(lds + PG8_SA(b, h) + aoff + m * 2048 + k * 1024); } while (0)
; #define PG8_LDB(dst, b, h) do { _Pragma("unroll") for (int n = 0; n < 2; ++n) _Pragma("unroll") for (int k = 0; k < 2; ++k) dst[n][k] = *(const LAS bf16x8*)(lds + PG8_SB(b, h) + boff + n * 2048 + k * 1024); } while (0)
; #define PG8_MMA(ai, bj, At, Bt) do { __builtin_amdgcn_s_setprio(1); _Pragma("unroll") for (int m = 0; m < 4; ++m) _Pragma("unroll") for (int n = 0; n < 2; ++n) _Pragma("unroll") for (int k = 0; k < 2; ++k) \
;         acc[ai][bj][m][n] = __builtin_amdgcn_mfma_f32_16x16x32_bf16(Bt[n][k], At[m][k], acc[ai][bj][m][n], 0, 0, 0); __builtin_amdgcn_s_setprio(0); } while (0)
; #define PG8_WAIT_V(n) asm volatile("s_waitcnt vmcnt(" #n ")" ::: "memory")
; #define PG8_WAIT_L(n) asm volatile("s_waitcnt lgkmcnt(" #n ")" ::: "memory")
; #define PG8_BAR __builtin_amdgcn_s_barrier()
; #define PG8_SCHED __builtin_amdgcn_sched_barrier(0)
; template <class Epi>
; __device__ __forceinline__ void gemm_phase(LAS unsigned char* lds, const Gemm g, const StaticOrder& S, const Epi& E) {
;     ...
;             PG8_STAGE(PG8_SB(0, 1), b2 + hstep, voffB);
;             PG8_WAIT_V(6); PG8_BAR; PG8_MMA(1, 1, At, B1); PG8_BAR;
;             PG8_LDB(B0, 1, 0); PG8_SCHED; PG8_LDA(At, 1, 0); PG8_STAGE(PG8_SA(0, 1), a2 + hstep, voffA);
;             PG8_WAIT_L(8); PG8_BAR; PG8_WAIT_L(0); PG8_MMA(0, 0, At, B0); PG8_BAR; PG8_SCHED;
;             PG8_LDB(B1, 1, 1); PG8_STAGE(PG8_SB(1, 0), b3, voffB);
;             PG8_BAR; PG8_WAIT_L(0); PG8_MMA(0, 1, At, B1); PG8_BAR;
;             PG8_LDA(At, 1, 1); PG8_STAGE(PG8_SA(1, 0), a3, voffA);
;             PG8_BAR; PG8_WAIT_L(0); PG8_MMA(1, 0, At, B0); PG8_BAR; PG8_SCHED;
	s_add_u32 s86, s58, 0x80000
	s_addc_u32 s87, s59, 0
	s_add_i32 s88, s88, s69
	s_mov_b32 m0, s88
	s_nop 0
	global_load_lds_dwordx4 v0, s[86:87]
	s_add_i32 m0, s88, 0x2000
	s_nop 0
	global_load_lds_dwordx4 v130, s[86:87]
	s_waitcnt vmcnt(6)
	s_barrier
	s_setprio 1
	v_mfma_f32_16x16x32_bf16 v[50:53], v[208:211], v[170:173], v[50:53]
	v_mfma_f32_16x16x32_bf16 v[42:45], v[216:219], v[170:173], v[42:45]
	v_mfma_f32_16x16x32_bf16 v[34:37], v[208:211], v[178:181], v[34:37]
	v_mfma_f32_16x16x32_bf16 v[26:29], v[216:219], v[178:181], v[26:29]
	v_mfma_f32_16x16x32_bf16 v[18:21], v[208:211], v[186:189], v[18:21]
	v_mfma_f32_16x16x32_bf16 v[10:13], v[216:219], v[186:189], v[10:13]
	v_mfma_f32_16x16x32_bf16 v[6:9], v[208:211], v[194:197], v[6:9]
	v_mfma_f32_16x16x32_bf16 v[2:5], v[216:219], v[194:197], v[2:5]
	v_mfma_f32_16x16x32_bf16 v[50:53], v[212:215], v[174:177], v[50:53]
	v_mfma_f32_16x16x32_bf16 v[42:45], v[220:223], v[174:177], v[42:45]
	v_mfma_f32_16x16x32_bf16 v[34:37], v[212:215], v[182:185], v[34:37]
	v_mfma_f32_16x16x32_bf16 v[26:29], v[220:223], v[182:185], v[26:29]
	v_mfma_f32_16x16x32_bf16 v[18:21], v[212:215], v[190:193], v[18:21]
	v_mfma_f32_16x16x32_bf16 v[10:13], v[220:223], v[190:193], v[10:13]
	v_mfma_f32_16x16x32_bf16 v[6:9], v[212:215], v[198:201], v[6:9]
	v_mfma_f32_16x16x32_bf16 v[2:5], v[220:223], v[198:201], v[2:5]
	s_setprio 0
	s_add_i32 s86, 0, 0x18000
	v_add_u32_e32 v140, s86, v143
	s_barrier
	ds_read_b128 v[154:157], v140
	ds_read_b128 v[158:161], v140 offset:1024
	ds_read_b128 v[162:165], v140 offset:2048
	ds_read_b128 v[166:169], v140 offset:3072
	s_add_u32 s60, s60, 0x80000
	s_addc_u32 s61, s61, 0
	s_mov_b32 m0, s73
	ds_read_b128 v[170:173], v151 offset:32768
	ds_read_b128 v[174:177], v151 offset:33792
	ds_read_b128 v[178:181], v151 offset:34816
	ds_read_b128 v[182:185], v151 offset:35840
	ds_read_b128 v[186:189], v151 offset:36864
	ds_read_b128 v[190:193], v151 offset:37888
	ds_read_b128 v[194:197], v151 offset:38912
	ds_read_b128 v[198:201], v151 offset:39936
	global_load_lds_dwordx4 v134, s[60:61]
	s_mov_b32 m0, s74
	s_nop 0
	global_load_lds_dwordx4 v132, s[60:61]
	s_waitcnt lgkmcnt(8)
	s_barrier
	s_waitcnt lgkmcnt(0)
	s_setprio 1
	s_waitcnt lgkmcnt(0)
	v_mfma_f32_16x16x32_bf16 v[126:129], v[154:157], v[170:173], v[126:129]
	v_mfma_f32_16x16x32_bf16 v[122:125], v[162:165], v[170:173], v[122:125]
	v_mfma_f32_16x16x32_bf16 v[110:113], v[154:157], v[178:181], v[110:113]
	v_mfma_f32_16x16x32_bf16 v[106:109], v[162:165], v[178:181], v[106:109]
	v_mfma_f32_16x16x32_bf16 v[94:97], v[154:157], v[186:189], v[94:97]
	v_mfma_f32_16x16x32_bf16 v[90:93], v[162:165], v[186:189], v[90:93]
	v_mfma_f32_16x16x32_bf16 v[78:81], v[154:157], v[194:197], v[78:81]
	v_mfma_f32_16x16x32_bf16 v[74:77], v[162:165], v[194:197], v[74:77]
	v_mfma_f32_16x16x32_bf16 v[126:129], v[158:161], v[174:177], v[126:129]
	v_mfma_f32_16x16x32_bf16 v[122:125], v[166:169], v[174:177], v[122:125]
	v_mfma_f32_16x16x32_bf16 v[110:113], v[158:161], v[182:185], v[110:113]
	v_mfma_f32_16x16x32_bf16 v[106:109], v[166:169], v[182:185], v[106:109]
	v_mfma_f32_16x16x32_bf16 v[94:97], v[158:161], v[190:193], v[94:97]
	v_mfma_f32_16x16x32_bf16 v[90:93], v[166:169], v[190:193], v[90:93]
	v_mfma_f32_16x16x32_bf16 v[78:81], v[158:161], v[198:201], v[78:81]
	v_mfma_f32_16x16x32_bf16 v[74:77], v[166:169], v[198:201], v[74:77]
	s_setprio 0
	s_barrier
	s_add_i32 s60, 0, 0x1c000
	s_add_i32 s61, s86, s69
	v_add_u32_e32 v140, s60, v143
	s_mov_b32 m0, s61
	ds_read_b128 v[208:211], v140
	ds_read_b128 v[212:215], v140 offset:1024
	ds_read_b128 v[216:219], v140 offset:2048
	ds_read_b128 v[220:223], v140 offset:3072
	global_load_lds_dwordx4 v0, s[98:99]
	s_add_i32 m0, s61, 0x2000
	s_nop 0
	global_load_lds_dwordx4 v130, s[98:99]
	s_barrier
	s_waitcnt lgkmcnt(0)
	s_setprio 1
	s_waitcnt lgkmcnt(0)
	v_mfma_f32_16x16x32_bf16 v[118:121], v[208:211], v[170:173], v[118:121]
	v_mfma_f32_16x16x32_bf16 v[114:117], v[216:219], v[170:173], v[114:117]
	v_mfma_f32_16x16x32_bf16 v[102:105], v[208:211], v[178:181], v[102:105]
	v_mfma_f32_16x16x32_bf16 v[98:101], v[216:219], v[178:181], v[98:101]
	v_mfma_f32_16x16x32_bf16 v[86:89], v[208:211], v[186:189], v[86:89]
	v_mfma_f32_16x16x32_bf16 v[82:85], v[216:219], v[186:189], v[82:85]
	v_mfma_f32_16x16x32_bf16 v[70:73], v[208:211], v[194:197], v[70:73]
	v_mfma_f32_16x16x32_bf16 v[66:69], v[216:219], v[194:197], v[66:69]
	v_mfma_f32_16x16x32_bf16 v[118:121], v[212:215], v[174:177], v[118:121]
	v_mfma_f32_16x16x32_bf16 v[114:117], v[220:223], v[174:177], v[114:117]
	v_mfma_f32_16x16x32_bf16 v[102:105], v[212:215], v[182:185], v[102:105]
	v_mfma_f32_16x16x32_bf16 v[98:101], v[220:223], v[182:185], v[98:101]
	v_mfma_f32_16x16x32_bf16 v[86:89], v[212:215], v[190:193], v[86:89]
	v_mfma_f32_16x16x32_bf16 v[82:85], v[220:223], v[190:193], v[82:85]
	v_mfma_f32_16x16x32_bf16 v[70:73], v[212:215], v[198:201], v[70:73]
	v_mfma_f32_16x16x32_bf16 v[66:69], v[220:223], v[198:201], v[66:69]
	s_setprio 0
	s_mov_b32 m0, s76
	s_barrier
	ds_read_b128 v[170:173], v151 offset:49152
	ds_read_b128 v[174:177], v151 offset:50176
	ds_read_b128 v[178:181], v151 offset:51200
	ds_read_b128 v[182:185], v151 offset:52224
	ds_read_b128 v[186:189], v151 offset:53248
	ds_read_b128 v[190:193], v151 offset:54272
	ds_read_b128 v[194:197], v151 offset:55296
	ds_read_b128 v[198:201], v151 offset:56320
	global_load_lds_dwordx4 v134, s[100:101]
	s_mov_b32 m0, s77
	s_nop 0
	global_load_lds_dwordx4 v132, s[100:101]
	s_barrier
; __device__ __forceinline__ unsigned pk2(float lo, float hi) { f32x2 v = {lo, hi}; bf16x2_t b = __builtin_convertvector(v, bf16x2_t); return __builtin_bit_cast(unsigned, b); }
; #define PG8_STAGE(bufoff, gbase, voff) do { _Pragma("unroll") for (int _i = 0; _i < 2; ++_i) \
;         __builtin_amdgcn_global_load_lds((const unsigned*)((const char*)(gbase) + (voff)[_i]), (LAS unsigned*)(lds + (bufoff) + ldsw + _i * 8192), 16, 0, 0); } while (0)
; #define PG8_WAIT_V(n) asm volatile("s_waitcnt vmcnt(" #n ")" ::: "memory")
; #define PG8_WAIT_L(n) asm volatile("s_waitcnt lgkmcnt(" #n ")" ::: "memory")
; #define PG8_BAR __builtin_amdgcn_s_barrier()
; #define PG8_SCHED __builtin_amdgcn_sched_barrier(0)
;     __device__ __forceinline__ void operator()(const AccT& acc, const Unit& u, int wr, int wc, int fr, int fq) const {
;     ...
;         if (ss) {
;             const int ln = (fq << 4) | fr;
;             float sa = ss[u.pm * BM + wr * 64 + ln], sb = ss[u.pm * BM + HALF + wr * 64 + ln];
;             sa = __builtin_amdgcn_rsqf(sa * (1.0f / DM) + EPS); sb = __builtin_amdgcn_rsqf(sb * (1.0f / DM) + EPS);
; #pragma unroll
;             for (int m = 0; m < 4; ++m) { rsv[m] = __shfl(sa, 16 * m + fr); rsv[4 + m] = __shfl(sb, 16 * m + fr); }
;         } else {
; #pragma unroll
;             for (int i = 0; i < 8; ++i) rsv[i] = 1.0f;
;         }
; #pragma unroll
;         for (int ai = 0; ai < 2; ++ai)
; #pragma unroll
;             for (int m = 0; m < 4; ++m) {
;                 const int row = row0 + ai * HALF + m * 16;
;                 const float rs = rsv[ai * 4 + m];
; #pragma unroll
;                 for (int bj = 0; bj < 2; ++bj) {
;                     const f32x4 v0 = acc[ai][bj][m][0] * rs, v1 = acc[ai][bj][m][1] * rs;
;                     u32x4 w; w.x = pk2(v0[0], v0[1]); w.y = pk2(v0[2], v0[3]); w.z = pk2(v1[0], v1[1]); w.w = pk2(v1[2], v1[3]);
;                     *(u32x4*)(out + (size_t)row * ldo + col0 + bj * HALF) = w;
; template <class Epi>
; __device__ __forceinline__ void gemm_phase(LAS unsigned char* lds, const Gemm g, const StaticOrder& S, const Epi& E) {
;     ...
;             PG8_BAR; PG8_WAIT_L(0); PG8_MMA(1, 0, At, B0); PG8_BAR; PG8_SCHED;
;             PG8_STAGE(PG8_SB(1, 1), b3 + hstep, voffB);
;             PG8_WAIT_V(6); PG8_BAR; PG8_MMA(1, 1, At, B1); PG8_BAR;
	s_waitcnt lgkmcnt(0)
	s_setprio 1
	s_waitcnt lgkmcnt(0)
	v_mfma_f32_16x16x32_bf16 v[62:65], v[154:157], v[170:173], v[62:65]
	v_mfma_f32_16x16x32_bf16 v[58:61], v[162:165], v[170:173], v[58:61]
	v_mfma_f32_16x16x32_bf16 v[54:57], v[154:157], v[178:181], v[54:57]
	v_mfma_f32_16x16x32_bf16 v[46:49], v[162:165], v[178:181], v[46:49]
	v_mfma_f32_16x16x32_bf16 v[38:41], v[154:157], v[186:189], v[38:41]
	v_mfma_f32_16x16x32_bf16 v[30:33], v[162:165], v[186:189], v[30:33]
	v_mfma_f32_16x16x32_bf16 v[22:25], v[154:157], v[194:197], v[22:25]
	v_mfma_f32_16x16x32_bf16 v[14:17], v[162:165], v[194:197], v[14:17]
	v_mfma_f32_16x16x32_bf16 v[62:65], v[158:161], v[174:177], v[62:65]
	v_mfma_f32_16x16x32_bf16 v[58:61], v[166:169], v[174:177], v[58:61]
	v_mfma_f32_16x16x32_bf16 v[54:57], v[158:161], v[182:185], v[54:57]
	v_mfma_f32_16x16x32_bf16 v[46:49], v[166:169], v[182:185], v[46:49]
	v_mfma_f32_16x16x32_bf16 v[38:41], v[158:161], v[190:193], v[38:41]
	v_mfma_f32_16x16x32_bf16 v[30:33], v[166:169], v[190:193], v[30:33]
	v_mfma_f32_16x16x32_bf16 v[22:25], v[158:161], v[198:201], v[22:25]
	v_mfma_f32_16x16x32_bf16 v[14:17], v[166:169], v[198:201], v[14:17]
	s_setprio 0
	s_barrier
	s_add_u32 s58, s58, 0x80080
	s_addc_u32 s59, s59, 0
	s_add_i32 s60, s60, s69
	s_mov_b32 m0, s60
	s_nop 0
	global_load_lds_dwordx4 v0, s[58:59]
	s_add_i32 m0, s60, 0x2000
	s_nop 0
	global_load_lds_dwordx4 v130, s[58:59]
	s_waitcnt vmcnt(6)
	s_barrier
	s_setprio 1
	v_mfma_f32_16x16x32_bf16 v[50:53], v[208:211], v[170:173], v[50:53]
	v_mfma_f32_16x16x32_bf16 v[42:45], v[216:219], v[170:173], v[42:45]
	v_mfma_f32_16x16x32_bf16 v[34:37], v[208:211], v[178:181], v[34:37]
	v_mfma_f32_16x16x32_bf16 v[26:29], v[216:219], v[178:181], v[26:29]
	v_mfma_f32_16x16x32_bf16 v[18:21], v[208:211], v[186:189], v[18:21]
	v_mfma_f32_16x16x32_bf16 v[10:13], v[216:219], v[186:189], v[10:13]
	v_mfma_f32_16x16x32_bf16 v[6:9], v[208:211], v[194:197], v[6:9]
	v_mfma_f32_16x16x32_bf16 v[2:5], v[216:219], v[194:197], v[2:5]
	v_mfma_f32_16x16x32_bf16 v[50:53], v[212:215], v[174:177], v[50:53]
	v_mfma_f32_16x16x32_bf16 v[42:45], v[220:223], v[174:177], v[42:45]
	v_mfma_f32_16x16x32_bf16 v[34:37], v[212:215], v[182:185], v[34:37]
	v_mfma_f32_16x16x32_bf16 v[26:29], v[220:223], v[182:185], v[26:29]
	v_mfma_f32_16x16x32_bf16 v[18:21], v[212:215], v[190:193], v[18:21]
	v_mfma_f32_16x16x32_bf16 v[10:13], v[220:223], v[190:193], v[10:13]
	v_mfma_f32_16x16x32_bf16 v[6:9], v[212:215], v[198:201], v[6:9]
	v_mfma_f32_16x16x32_bf16 v[2:5], v[220:223], v[198:201], v[2:5]
	s_setprio 0
	s_add_i32 s85, s85, 2
	s_add_u32 s56, s56, 0x100
	s_addc_u32 s57, s57, 0
	s_add_u32 s83, s83, 0x100
	s_addc_u32 s84, s84, 0
	s_cmp_gt_u32 s85, 29
	s_barrier
	s_cbranch_scc0 .LBB0_64
	s_lshl_b32 s47, s54, 8
	s_add_i32 s47, s47, s75
	v_or_b32_e32 v154, s47, v145
	v_ashrrev_i32_e32 v155, 31, v154
	v_lshl_add_u64 v[154:155], v[154:155], 2, s[2:3]
	global_load_dword v140, v[154:155], off
	v_add_u32_e32 v154, s47, v147
	v_ashrrev_i32_e32 v155, 31, v154
	v_lshl_add_u64 v[154:155], v[154:155], 2, s[2:3]
	global_load_dword v142, v[154:155], off
	v_lshl_or_b32 v158, s80, 8, v149
	v_ashrrev_i32_e32 v159, 31, v158
	s_and_b64 vcc, exec, s[36:37]
	s_mov_b32 s80, s46
	s_mov_b32 s54, s48
	s_mov_b64 s[58:59], s[52:53]
	s_waitcnt vmcnt(0)
	v_fmamk_f32 v140, v140, 0x3a000000, v233
	v_rsq_f32_e32 v140, v140
	v_fmamk_f32 v142, v142, 0x3a000000, v233
	ds_bpermute_b32 v154, v152, v140
	v_rsq_f32_e32 v153, v142
	ds_bpermute_b32 v156, v152, v140 offset:64
	ds_bpermute_b32 v150, v152, v140 offset:128
	ds_bpermute_b32 v148, v152, v140 offset:192
	ds_bpermute_b32 v146, v152, v153
	ds_bpermute_b32 v144, v152, v153 offset:64
	ds_bpermute_b32 v142, v152, v153 offset:128
	ds_bpermute_b32 v140, v152, v153 offset:192
	v_or_b32_e32 v153, s47, v141
	s_waitcnt lgkmcnt(0)
	v_pk_mul_f32 v[126:127], v[126:127], v[154:155] op_sel_hi:[1,0]
	v_pk_mul_f32 v[122:123], v[122:123], v[154:155] op_sel_hi:[1,0]
	v_pk_mul_f32 v[128:129], v[128:129], v[154:155] op_sel_hi:[1,0]
	v_pk_mul_f32 v[160:161], v[124:125], v[154:155] op_sel_hi:[1,0]
	v_cvt_pk_bf16_f32 v124, v126, v127
	v_cvt_pk_bf16_f32 v126, v122, v123
	v_mad_i64_i32 v[122:123], s[56:57], v153, s63, 0
	v_cvt_pk_bf16_f32 v125, v128, v129
	v_lshl_add_u64 v[128:129], v[122:123], 1, s[44:45]
	v_lshlrev_b64 v[122:123], 1, v[158:159]
	v_cvt_pk_bf16_f32 v127, v160, v161
	v_lshl_add_u64 v[128:129], v[128:129], 0, v[122:123]
	global_store_dwordx4 v[128:129], v[124:127], off
	v_pk_mul_f32 v[120:121], v[120:121], v[154:155] op_sel_hi:[1,0]
	v_pk_mul_f32 v[118:119], v[118:119], v[154:155] op_sel_hi:[1,0]
	v_pk_mul_f32 v[124:125], v[116:117], v[154:155] op_sel_hi:[1,0]
	v_pk_mul_f32 v[116:117], v[114:115], v[154:155] op_sel_hi:[1,0]
	v_cvt_pk_bf16_f32 v114, v118, v119
	v_cvt_pk_bf16_f32 v115, v120, v121
	v_cvt_pk_bf16_f32 v116, v116, v117
	v_cvt_pk_bf16_f32 v117, v124, v125
	global_store_dwordx4 v[128:129], v[114:117], off offset:256
	v_pk_mul_f32 v[110:111], v[110:111], v[156:157] op_sel_hi:[1,0]
	v_pk_mul_f32 v[112:113], v[112:113], v[156:157] op_sel_hi:[1,0]
	v_or_b32_e32 v116, 16, v153
	v_pk_mul_f32 v[114:115], v[108:109], v[156:157] op_sel_hi:[1,0]
	v_pk_mul_f32 v[108:109], v[106:107], v[156:157] op_sel_hi:[1,0]
	v_cvt_pk_bf16_f32 v106, v110, v111
	v_mad_i64_i32 v[110:111], s[56:57], v116, s63, 0
	v_lshl_add_u64 v[110:111], v[110:111], 1, s[44:45]
	v_cvt_pk_bf16_f32 v107, v112, v113
	v_cvt_pk_bf16_f32 v108, v108, v109
	v_cvt_pk_bf16_f32 v109, v114, v115
	v_lshl_add_u64 v[110:111], v[110:111], 0, v[122:123]
	global_store_dwordx4 v[110:111], v[106:109], off
	v_pk_mul_f32 v[104:105], v[104:105], v[156:157] op_sel_hi:[1,0]
; __device__ __forceinline__ unsigned pk2(float lo, float hi) { f32x2 v = {lo, hi}; bf16x2_t b = __builtin_convertvector(v, bf16x2_t); return __builtin_bit_cast(unsigned, b); }
; #define PG8_WAIT_V(n) asm volatile("s_waitcnt vmcnt(" #n ")" ::: "memory")
; #define PG8_BAR __builtin_amdgcn_s_barrier()
;     __device__ __forceinline__ void operator()(const AccT& acc, const Unit& u, int wr, int wc, int fr, int fq) const {
;     ...
;         for (int ai = 0; ai < 2; ++ai)
; #pragma unroll
;             for (int m = 0; m < 4; ++m) {
;                 const int row = row0 + ai * HALF + m * 16;
;                 const float rs = rsv[ai * 4 + m];
; #pragma unroll
;                 for (int bj = 0; bj < 2; ++bj) {
;                     const f32x4 v0 = acc[ai][bj][m][0] * rs, v1 = acc[ai][bj][m][1] * rs;
;                     u32x4 w; w.x = pk2(v0[0], v0[1]); w.y = pk2(v0[2], v0[3]); w.z = pk2(v1[0], v1[1]); w.w = pk2(v1[2], v1[3]);
;                     *(u32x4*)(out + (size_t)row * ldo + col0 + bj * HALF) = w;
;                 }
; template <class Epi>
; __device__ __forceinline__ void gemm_phase(LAS unsigned char* lds, const Gemm g, const StaticOrder& S, const Epi& E) {
;     ...
;         E(acc, cur, wr, wc, fr, fq);
;         if (!has_next) break;
; #pragma unroll
;         for (int a = 0; a < 2; ++a)
; #pragma unroll
;             for (int b = 0; b < 2; ++b)
; #pragma unroll
;                 for (int m = 0; m < 4; ++m)
; #pragma unroll
;                     for (int n = 0; n < 2; ++n) acc[a][b][m][n] = (f32x4){0.f, 0.f, 0.f, 0.f};
;         cur = nxt; cA = nA; cB = nB; ++ui;
;     }
;     PG8_WAIT_V(0);
;     if (wr == 0) PG8_BAR;
	v_pk_mul_f32 v[102:103], v[102:103], v[156:157] op_sel_hi:[1,0]
	v_pk_mul_f32 v[106:107], v[100:101], v[156:157] op_sel_hi:[1,0]
	v_pk_mul_f32 v[100:101], v[98:99], v[156:157] op_sel_hi:[1,0]
	v_cvt_pk_bf16_f32 v98, v102, v103
	v_cvt_pk_bf16_f32 v99, v104, v105
	v_cvt_pk_bf16_f32 v100, v100, v101
	v_cvt_pk_bf16_f32 v101, v106, v107
	global_store_dwordx4 v[110:111], v[98:101], off offset:256
	v_pk_mul_f32 v[94:95], v[94:95], v[150:151] op_sel_hi:[1,0]
	v_pk_mul_f32 v[96:97], v[96:97], v[150:151] op_sel_hi:[1,0]
	v_or_b32_e32 v100, 32, v153
	v_pk_mul_f32 v[98:99], v[92:93], v[150:151] op_sel_hi:[1,0]
	v_pk_mul_f32 v[92:93], v[90:91], v[150:151] op_sel_hi:[1,0]
	v_cvt_pk_bf16_f32 v90, v94, v95
	v_mad_i64_i32 v[94:95], s[56:57], v100, s63, 0
	v_lshl_add_u64 v[94:95], v[94:95], 1, s[44:45]
	v_cvt_pk_bf16_f32 v91, v96, v97
	v_cvt_pk_bf16_f32 v92, v92, v93
	v_cvt_pk_bf16_f32 v93, v98, v99
	v_lshl_add_u64 v[94:95], v[94:95], 0, v[122:123]
	global_store_dwordx4 v[94:95], v[90:93], off
	v_pk_mul_f32 v[88:89], v[88:89], v[150:151] op_sel_hi:[1,0]
	v_pk_mul_f32 v[86:87], v[86:87], v[150:151] op_sel_hi:[1,0]
	v_pk_mul_f32 v[90:91], v[84:85], v[150:151] op_sel_hi:[1,0]
	v_pk_mul_f32 v[84:85], v[82:83], v[150:151] op_sel_hi:[1,0]
	v_cvt_pk_bf16_f32 v82, v86, v87
	v_cvt_pk_bf16_f32 v83, v88, v89
	v_cvt_pk_bf16_f32 v84, v84, v85
	v_cvt_pk_bf16_f32 v85, v90, v91
	global_store_dwordx4 v[94:95], v[82:85], off offset:256
	v_pk_mul_f32 v[78:79], v[78:79], v[148:149] op_sel_hi:[1,0]
	v_pk_mul_f32 v[80:81], v[80:81], v[148:149] op_sel_hi:[1,0]
	v_or_b32_e32 v84, 48, v153
	v_pk_mul_f32 v[82:83], v[76:77], v[148:149] op_sel_hi:[1,0]
	v_pk_mul_f32 v[76:77], v[74:75], v[148:149] op_sel_hi:[1,0]
	v_cvt_pk_bf16_f32 v74, v78, v79
	v_mad_i64_i32 v[78:79], s[56:57], v84, s63, 0
	v_lshl_add_u64 v[78:79], v[78:79], 1, s[44:45]
	v_cvt_pk_bf16_f32 v75, v80, v81
	v_cvt_pk_bf16_f32 v76, v76, v77
	v_cvt_pk_bf16_f32 v77, v82, v83
	v_lshl_add_u64 v[78:79], v[78:79], 0, v[122:123]
	global_store_dwordx4 v[78:79], v[74:77], off
	v_pk_mul_f32 v[72:73], v[72:73], v[148:149] op_sel_hi:[1,0]
	v_pk_mul_f32 v[70:71], v[70:71], v[148:149] op_sel_hi:[1,0]
	v_pk_mul_f32 v[74:75], v[68:69], v[148:149] op_sel_hi:[1,0]
	v_pk_mul_f32 v[68:69], v[66:67], v[148:149] op_sel_hi:[1,0]
	v_cvt_pk_bf16_f32 v66, v70, v71
	v_cvt_pk_bf16_f32 v67, v72, v73
	v_cvt_pk_bf16_f32 v68, v68, v69
	v_cvt_pk_bf16_f32 v69, v74, v75
	global_store_dwordx4 v[78:79], v[66:69], off offset:256
	v_pk_mul_f32 v[62:63], v[62:63], v[146:147] op_sel_hi:[1,0]
	v_pk_mul_f32 v[64:65], v[64:65], v[146:147] op_sel_hi:[1,0]
	v_add_u32_e32 v68, 0x80, v153
	v_pk_mul_f32 v[66:67], v[60:61], v[146:147] op_sel_hi:[1,0]
	v_pk_mul_f32 v[60:61], v[58:59], v[146:147] op_sel_hi:[1,0]
	v_cvt_pk_bf16_f32 v58, v62, v63
	v_mad_i64_i32 v[62:63], s[56:57], v68, s63, 0
	v_lshl_add_u64 v[62:63], v[62:63], 1, s[44:45]
	v_cvt_pk_bf16_f32 v59, v64, v65
	v_cvt_pk_bf16_f32 v60, v60, v61
	v_cvt_pk_bf16_f32 v61, v66, v67
	v_lshl_add_u64 v[62:63], v[62:63], 0, v[122:123]
	global_store_dwordx4 v[62:63], v[58:61], off
	v_pk_mul_f32 v[52:53], v[52:53], v[146:147] op_sel_hi:[1,0]
	v_pk_mul_f32 v[50:51], v[50:51], v[146:147] op_sel_hi:[1,0]
	v_pk_mul_f32 v[58:59], v[44:45], v[146:147] op_sel_hi:[1,0]
	v_pk_mul_f32 v[44:45], v[42:43], v[146:147] op_sel_hi:[1,0]
	v_cvt_pk_bf16_f32 v42, v50, v51
	v_cvt_pk_bf16_f32 v43, v52, v53
	v_cvt_pk_bf16_f32 v44, v44, v45
	v_cvt_pk_bf16_f32 v45, v58, v59
	global_store_dwordx4 v[62:63], v[42:45], off offset:256
	v_add_u32_e32 v50, 0x90, v153
	v_pk_mul_f32 v[46:47], v[46:47], v[144:145] op_sel_hi:[1,0]
	v_pk_mul_f32 v[44:45], v[56:57], v[144:145] op_sel_hi:[1,0]
	v_pk_mul_f32 v[42:43], v[54:55], v[144:145] op_sel_hi:[1,0]
	v_pk_mul_f32 v[48:49], v[48:49], v[144:145] op_sel_hi:[1,0]
	v_cvt_pk_bf16_f32 v42, v42, v43
	v_cvt_pk_bf16_f32 v43, v44, v45
	v_cvt_pk_bf16_f32 v44, v46, v47
	v_mad_i64_i32 v[46:47], s[56:57], v50, s63, 0
	v_lshl_add_u64 v[46:47], v[46:47], 1, s[44:45]
	v_cvt_pk_bf16_f32 v45, v48, v49
	v_lshl_add_u64 v[46:47], v[46:47], 0, v[122:123]
	global_store_dwordx4 v[46:47], v[42:45], off
	v_pk_mul_f32 v[36:37], v[36:37], v[144:145] op_sel_hi:[1,0]
	v_pk_mul_f32 v[34:35], v[34:35], v[144:145] op_sel_hi:[1,0]
	v_pk_mul_f32 v[42:43], v[28:29], v[144:145] op_sel_hi:[1,0]
	v_pk_mul_f32 v[28:29], v[26:27], v[144:145] op_sel_hi:[1,0]
	v_cvt_pk_bf16_f32 v26, v34, v35
	v_cvt_pk_bf16_f32 v27, v36, v37
	v_cvt_pk_bf16_f32 v28, v28, v29
	v_cvt_pk_bf16_f32 v29, v42, v43
	global_store_dwordx4 v[46:47], v[26:29], off offset:256
	v_add_u32_e32 v34, 0xa0, v153
	v_pk_mul_f32 v[30:31], v[30:31], v[142:143] op_sel_hi:[1,0]
	v_pk_mul_f32 v[28:29], v[40:41], v[142:143] op_sel_hi:[1,0]
	v_pk_mul_f32 v[26:27], v[38:39], v[142:143] op_sel_hi:[1,0]
	v_pk_mul_f32 v[32:33], v[32:33], v[142:143] op_sel_hi:[1,0]
	v_cvt_pk_bf16_f32 v26, v26, v27
	v_cvt_pk_bf16_f32 v27, v28, v29
	v_cvt_pk_bf16_f32 v28, v30, v31
	v_mad_i64_i32 v[30:31], s[56:57], v34, s63, 0
	v_lshl_add_u64 v[30:31], v[30:31], 1, s[44:45]
	v_cvt_pk_bf16_f32 v29, v32, v33
	v_lshl_add_u64 v[30:31], v[30:31], 0, v[122:123]
	global_store_dwordx4 v[30:31], v[26:29], off
	v_pk_mul_f32 v[20:21], v[20:21], v[142:143] op_sel_hi:[1,0]
	v_pk_mul_f32 v[18:19], v[18:19], v[142:143] op_sel_hi:[1,0]
	v_pk_mul_f32 v[26:27], v[12:13], v[142:143] op_sel_hi:[1,0]
	v_pk_mul_f32 v[12:13], v[10:11], v[142:143] op_sel_hi:[1,0]
	v_cvt_pk_bf16_f32 v10, v18, v19
	v_cvt_pk_bf16_f32 v11, v20, v21
	v_cvt_pk_bf16_f32 v12, v12, v13
	v_cvt_pk_bf16_f32 v13, v26, v27
	global_store_dwordx4 v[30:31], v[10:13], off offset:256
	v_add_u32_e32 v18, 0xb0, v153
	v_pk_mul_f32 v[14:15], v[14:15], v[140:141] op_sel_hi:[1,0]
	v_pk_mul_f32 v[12:13], v[24:25], v[140:141] op_sel_hi:[1,0]
	v_pk_mul_f32 v[10:11], v[22:23], v[140:141] op_sel_hi:[1,0]
	v_pk_mul_f32 v[16:17], v[16:17], v[140:141] op_sel_hi:[1,0]
	v_cvt_pk_bf16_f32 v10, v10, v11
	v_cvt_pk_bf16_f32 v11, v12, v13
	v_cvt_pk_bf16_f32 v12, v14, v15
	v_mad_i64_i32 v[14:15], s[56:57], v18, s63, 0
	v_lshl_add_u64 v[14:15], v[14:15], 1, s[44:45]
	v_cvt_pk_bf16_f32 v13, v16, v17
	v_lshl_add_u64 v[14:15], v[14:15], 0, v[122:123]
	global_store_dwordx4 v[14:15], v[10:13], off
	v_pk_mul_f32 v[8:9], v[8:9], v[140:141] op_sel_hi:[1,0]
	v_pk_mul_f32 v[6:7], v[6:7], v[140:141] op_sel_hi:[1,0]
	v_pk_mul_f32 v[10:11], v[4:5], v[140:141] op_sel_hi:[1,0]
	v_pk_mul_f32 v[4:5], v[2:3], v[140:141] op_sel_hi:[1,0]
	v_cvt_pk_bf16_f32 v2, v6, v7
	v_cvt_pk_bf16_f32 v3, v8, v9
	v_cvt_pk_bf16_f32 v4, v4, v5
	v_cvt_pk_bf16_f32 v5, v10, v11
	s_mov_b64 s[56:57], s[50:51]
	global_store_dwordx4 v[14:15], v[2:5], off offset:256
	s_cbranch_vccz .LBB0_61
	s_waitcnt vmcnt(0)
	s_cmpk_gt_u32 s64, 0xff
	s_cbranch_scc1 .LBB0_68
	s_barrier

; #define PG8_STAGE(bufoff, gbase, voff) do { _Pragma("unroll") for (int _i = 0; _i < 2; ++_i) \
;         __builtin_amdgcn_global_load_lds((const unsigned*)((const char*)(gbase) + (voff)[_i]), (LAS unsigned*)(lds + (bufoff) + ldsw + _i * 8192), 16, 0, 0); } while (0)
; #define PG8_LDA(dst, b, h) do { _Pragma("unroll") for (int m = 0; m < 4; ++m) _Pragma("unroll") for (int k = 0; k < 2; ++k) dst[m][k] = *(const LAS bf16x8*)(lds + PG8_SA(b, h) + aoff + m * 2048 + k * 1024); } while (0)
; #define PG8_LDB(dst, b, h) do { _Pragma("unroll") for (int n = 0; n < 2; ++n) _Pragma("unroll") for (int k = 0; k < 2; ++k) dst[n][k] = *(const LAS bf16x8*)(lds + PG8_SB(b, h) + boff + n * 2048 + k * 1024); } while (0)
; #define PG8_MMA(ai, bj, At, Bt) do { __builtin_amdgcn_s_setprio(1); _Pragma("unroll") for (int m = 0; m < 4; ++m) _Pragma("unroll") for (int n = 0; n < 2; ++n) _Pragma("unroll") for (int k = 0; k < 2; ++k) \
;         acc[ai][bj][m][n] = __builtin_amdgcn_mfma_f32_16x16x32_bf16(Bt[n][k], At[m][k], acc[ai][bj][m][n], 0, 0, 0); __builtin_amdgcn_s_setprio(0); } while (0)
; #define PG8_WAIT_L(n) asm volatile("s_waitcnt lgkmcnt(" #n ")" ::: "memory")
; #define PG8_BAR __builtin_amdgcn_s_barrier()
; #define PG8_SCHED __builtin_amdgcn_sched_barrier(0)
; template <class Epi>
; __device__ __forceinline__ void gemm_phase(LAS unsigned char* lds, const Gemm g, const StaticOrder& S, const Epi& E) {
;     ...
;         for (int t = 0; t < nt; t += 2) {
;             const bool last = (t == nt - 2);
;             const char* a1 = cA + (size_t)(t + 1) * kstep;
;             const char* a2 = last ? nA : cA + (size_t)(t + 2) * kstep; const char* b2 = last ? nB : cB + (size_t)(t + 2) * kstep;
;             const char* a3 = a2 + kstep; const char* b3 = b2 + kstep;
;             PG8_LDB(B0, 0, 0); PG8_SCHED; PG8_LDA(At, 0, 0); PG8_STAGE(PG8_SA(1, 1), a1 + hstep, voffA);
;             PG8_WAIT_L(8); PG8_BAR; PG8_WAIT_L(0); PG8_MMA(0, 0, At, B0); PG8_BAR; PG8_SCHED;
;             PG8_LDB(B1, 0, 1); PG8_STAGE(PG8_SB(0, 0), b2, voffB);
;             PG8_BAR; PG8_WAIT_L(0); PG8_MMA(0, 1, At, B1); PG8_BAR;
;             PG8_LDA(At, 0, 1); PG8_STAGE(PG8_SA(0, 0), a2, voffA);
;             PG8_BAR; PG8_WAIT_L(0); PG8_MMA(1, 0, At, B0); PG8_BAR; PG8_SCHED;
.LBB0_77:
	s_add_u32 s56, s54, 0xfff80080
	s_addc_u32 s57, s55, -1
	s_add_i32 s81, 0, 0x10000
	v_add_u32_e32 v156, s81, v141
	ds_read_b128 v[144:147], v156
	ds_read_b128 v[148:151], v156 offset:1024
	ds_read_b128 v[152:155], v156 offset:2048
	ds_read_b128 v[156:159], v156 offset:3072
	s_cmp_eq_u32 s80, 28
	s_cselect_b32 s59, s49, s57
	s_cselect_b32 s58, s76, s56
	s_cselect_b32 s57, s47, s79
	s_cselect_b32 s56, s77, s78
	s_add_i32 m0, s65, 0xc000
	ds_read_b128 v[160:163], v143
	ds_read_b128 v[164:167], v143 offset:1024
	ds_read_b128 v[168:171], v143 offset:2048
	ds_read_b128 v[172:175], v143 offset:3072
	ds_read_b128 v[176:179], v143 offset:4096
	ds_read_b128 v[180:183], v143 offset:5120
	ds_read_b128 v[184:187], v143 offset:6144
	ds_read_b128 v[188:191], v143 offset:7168
	global_load_lds_dwordx4 v136, s[54:55]
	s_add_i32 m0, s65, 0xe000
	s_nop 0
	global_load_lds_dwordx4 v138, s[54:55]
	s_waitcnt lgkmcnt(8)
	s_barrier
	s_waitcnt lgkmcnt(0)
	s_setprio 1
	s_waitcnt lgkmcnt(0)
	v_mfma_f32_16x16x32_bf16 v[126:129], v[144:147], v[160:163], v[126:129]
	v_mfma_f32_16x16x32_bf16 v[122:125], v[152:155], v[160:163], v[122:125]
	v_mfma_f32_16x16x32_bf16 v[118:121], v[144:147], v[168:171], v[118:121]
	v_mfma_f32_16x16x32_bf16 v[114:117], v[152:155], v[168:171], v[114:117]
	v_mfma_f32_16x16x32_bf16 v[102:105], v[144:147], v[176:179], v[102:105]
	v_mfma_f32_16x16x32_bf16 v[98:101], v[152:155], v[176:179], v[98:101]
	v_mfma_f32_16x16x32_bf16 v[86:89], v[144:147], v[184:187], v[86:89]
	v_mfma_f32_16x16x32_bf16 v[82:85], v[152:155], v[184:187], v[82:85]
	v_mfma_f32_16x16x32_bf16 v[126:129], v[148:151], v[164:167], v[126:129]
	v_mfma_f32_16x16x32_bf16 v[122:125], v[156:159], v[164:167], v[122:125]
	v_mfma_f32_16x16x32_bf16 v[118:121], v[148:151], v[172:175], v[118:121]
	v_mfma_f32_16x16x32_bf16 v[114:117], v[156:159], v[172:175], v[114:117]
	v_mfma_f32_16x16x32_bf16 v[102:105], v[148:151], v[180:183], v[102:105]
	v_mfma_f32_16x16x32_bf16 v[98:101], v[156:159], v[180:183], v[98:101]
	v_mfma_f32_16x16x32_bf16 v[86:89], v[148:151], v[188:191], v[86:89]
	v_mfma_f32_16x16x32_bf16 v[82:85], v[156:159], v[188:191], v[82:85]
	s_setprio 0
	s_barrier
	s_add_i32 s84, 0, 0x14000
	v_add_u32_e32 v200, s84, v141
	s_add_i32 s81, s81, s64
	ds_read_b128 v[192:195], v200
	ds_read_b128 v[196:199], v200 offset:1024
	ds_read_b128 v[208:211], v200 offset:2048
	ds_read_b128 v[212:215], v200 offset:3072
	s_mov_b32 m0, s81
	s_add_u32 s98, s56, s22
	s_addc_u32 s99, s57, s23
	global_load_lds_dwordx4 v0, s[56:57]
	s_add_i32 m0, s81, 0x2000
	s_nop 0
	global_load_lds_dwordx4 v130, s[56:57]
	s_barrier
	s_waitcnt lgkmcnt(0)
	s_setprio 1
	s_waitcnt lgkmcnt(0)
	v_mfma_f32_16x16x32_bf16 v[110:113], v[192:195], v[160:163], v[110:113]
	v_mfma_f32_16x16x32_bf16 v[106:109], v[208:211], v[160:163], v[106:109]
	v_mfma_f32_16x16x32_bf16 v[94:97], v[192:195], v[168:171], v[94:97]
	v_mfma_f32_16x16x32_bf16 v[90:93], v[208:211], v[168:171], v[90:93]
	v_mfma_f32_16x16x32_bf16 v[78:81], v[192:195], v[176:179], v[78:81]
	v_mfma_f32_16x16x32_bf16 v[74:77], v[208:211], v[176:179], v[74:77]
	v_mfma_f32_16x16x32_bf16 v[70:73], v[192:195], v[184:187], v[70:73]
	v_mfma_f32_16x16x32_bf16 v[66:69], v[208:211], v[184:187], v[66:69]
	v_mfma_f32_16x16x32_bf16 v[110:113], v[196:199], v[164:167], v[110:113]
	v_mfma_f32_16x16x32_bf16 v[106:109], v[212:215], v[164:167], v[106:109]
	v_mfma_f32_16x16x32_bf16 v[94:97], v[196:199], v[172:175], v[94:97]
	v_mfma_f32_16x16x32_bf16 v[90:93], v[212:215], v[172:175], v[90:93]
	v_mfma_f32_16x16x32_bf16 v[78:81], v[196:199], v[180:183], v[78:81]
	v_mfma_f32_16x16x32_bf16 v[74:77], v[212:215], v[180:183], v[74:77]
	v_mfma_f32_16x16x32_bf16 v[70:73], v[196:199], v[188:191], v[70:73]
	v_mfma_f32_16x16x32_bf16 v[66:69], v[212:215], v[188:191], v[66:69]
	s_setprio 0
	s_mov_b32 m0, s65
	s_add_u32 s100, s58, s22
	s_addc_u32 s101, s59, s23
	s_barrier
	ds_read_b128 v[160:163], v143 offset:16384
	ds_read_b128 v[164:167], v143 offset:17408
	ds_read_b128 v[168:171], v143 offset:18432
	ds_read_b128 v[172:175], v143 offset:19456
	ds_read_b128 v[176:179], v143 offset:20480
	ds_read_b128 v[180:183], v143 offset:21504
	ds_read_b128 v[184:187], v143 offset:22528
	ds_read_b128 v[188:191], v143 offset:23552
	global_load_lds_dwordx4 v134, s[58:59]
	s_mov_b32 m0, s68
	s_nop 0
	global_load_lds_dwordx4 v132, s[58:59]
	s_barrier
	s_waitcnt lgkmcnt(0)
	s_setprio 1
	s_waitcnt lgkmcnt(0)
	v_mfma_f32_16x16x32_bf16 v[62:65], v[144:147], v[160:163], v[62:65]
	v_mfma_f32_16x16x32_bf16 v[58:61], v[152:155], v[160:163], v[58:61]
	v_mfma_f32_16x16x32_bf16 v[54:57], v[144:147], v[168:171], v[54:57]
	v_mfma_f32_16x16x32_bf16 v[50:53], v[152:155], v[168:171], v[50:53]
	v_mfma_f32_16x16x32_bf16 v[38:41], v[144:147], v[176:179], v[38:41]
	v_mfma_f32_16x16x32_bf16 v[34:37], v[152:155], v[176:179], v[34:37]
	v_mfma_f32_16x16x32_bf16 v[22:25], v[144:147], v[184:187], v[22:25]
	v_mfma_f32_16x16x32_bf16 v[18:21], v[152:155], v[184:187], v[18:21]
	v_mfma_f32_16x16x32_bf16 v[62:65], v[148:151], v[164:167], v[62:65]
	v_mfma_f32_16x16x32_bf16 v[58:61], v[156:159], v[164:167], v[58:61]
	v_mfma_f32_16x16x32_bf16 v[54:57], v[148:151], v[172:175], v[54:57]
	v_mfma_f32_16x16x32_bf16 v[50:53], v[156:159], v[172:175], v[50:53]
	v_mfma_f32_16x16x32_bf16 v[38:41], v[148:151], v[180:183], v[38:41]
	v_mfma_f32_16x16x32_bf16 v[34:37], v[156:159], v[180:183], v[34:37]
	v_mfma_f32_16x16x32_bf16 v[22:25], v[148:151], v[188:191], v[22:25]
	v_mfma_f32_16x16x32_bf16 v[18:21], v[156:159], v[188:191], v[18:21]
	s_setprio 0
	s_barrier
; #define PG8_STAGE(bufoff, gbase, voff) do { _Pragma("unroll") for (int _i = 0; _i < 2; ++_i) \
;         __builtin_amdgcn_global_load_lds((const unsigned*)((const char*)(gbase) + (voff)[_i]), (LAS unsigned*)(lds + (bufoff) + ldsw + _i * 8192), 16, 0, 0); } while (0)
; #define PG8_LDA(dst, b, h) do { _Pragma("unroll") for (int m = 0; m < 4; ++m) _Pragma("unroll") for (int k = 0; k < 2; ++k) dst[m][k] = *(const LAS bf16x8*)(lds + PG8_SA(b, h) + aoff + m * 2048 + k * 1024); } while (0)
; #define PG8_LDB(dst, b, h) do { _Pragma("unroll") for (int n = 0; n < 2; ++n) _Pragma("unroll") for (int k = 0; k < 2; ++k) dst[n][k] = *(const LAS bf16x8*)(lds + PG8_SB(b, h) + boff + n * 2048 + k * 1024); } while (0)
; #define PG8_MMA(ai, bj, At, Bt) do { __builtin_amdgcn_s_setprio(1); _Pragma("unroll") for (int m = 0; m < 4; ++m) _Pragma("unroll") for (int n = 0; n < 2; ++n) _Pragma("unroll") for (int k = 0; k < 2; ++k) \
;         acc[ai][bj][m][n] = __builtin_amdgcn_mfma_f32_16x16x32_bf16(Bt[n][k], At[m][k], acc[ai][bj][m][n], 0, 0, 0); __builtin_amdgcn_s_setprio(0); } while (0)
; #define PG8_WAIT_V(n) asm volatile("s_waitcnt vmcnt(" #n ")" ::: "memory")
; #define PG8_WAIT_L(n) asm volatile("s_waitcnt lgkmcnt(" #n ")" ::: "memory")
; #define PG8_BAR __builtin_amdgcn_s_barrier()
; #define PG8_SCHED __builtin_amdgcn_sched_barrier(0)
; template <class Epi>
; __device__ __forceinline__ void gemm_phase(LAS unsigned char* lds, const Gemm g, const StaticOrder& S, const Epi& E) {
;     ...
;             PG8_STAGE(PG8_SB(0, 1), b2 + hstep, voffB);
;             PG8_WAIT_V(6); PG8_BAR; PG8_MMA(1, 1, At, B1); PG8_BAR;
;             PG8_LDB(B0, 1, 0); PG8_SCHED; PG8_LDA(At, 1, 0); PG8_STAGE(PG8_SA(0, 1), a2 + hstep, voffA);
;             PG8_WAIT_L(8); PG8_BAR; PG8_WAIT_L(0); PG8_MMA(0, 0, At, B0); PG8_BAR; PG8_SCHED;
;             PG8_LDB(B1, 1, 1); PG8_STAGE(PG8_SB(1, 0), b3, voffB);
;             PG8_BAR; PG8_WAIT_L(0); PG8_MMA(0, 1, At, B1); PG8_BAR;
;             PG8_LDA(At, 1, 1); PG8_STAGE(PG8_SA(1, 0), a3, voffA);
;             PG8_BAR; PG8_WAIT_L(0); PG8_MMA(1, 0, At, B0); PG8_BAR; PG8_SCHED;
	s_add_u32 s82, s56, 0x80000
	s_addc_u32 s83, s57, 0
	s_add_i32 s81, s84, s64
	s_mov_b32 m0, s81
	s_nop 0
	global_load_lds_dwordx4 v0, s[82:83]
	s_add_i32 m0, s81, 0x2000
	s_nop 0
	global_load_lds_dwordx4 v130, s[82:83]
	s_waitcnt vmcnt(6)
	s_barrier
	s_setprio 1
	v_mfma_f32_16x16x32_bf16 v[46:49], v[192:195], v[160:163], v[46:49]
	v_mfma_f32_16x16x32_bf16 v[42:45], v[208:211], v[160:163], v[42:45]
	v_mfma_f32_16x16x32_bf16 v[30:33], v[192:195], v[168:171], v[30:33]
	v_mfma_f32_16x16x32_bf16 v[26:29], v[208:211], v[168:171], v[26:29]
	v_mfma_f32_16x16x32_bf16 v[14:17], v[192:195], v[176:179], v[14:17]
	v_mfma_f32_16x16x32_bf16 v[10:13], v[208:211], v[176:179], v[10:13]
	v_mfma_f32_16x16x32_bf16 v[6:9], v[192:195], v[184:187], v[6:9]
	v_mfma_f32_16x16x32_bf16 v[2:5], v[208:211], v[184:187], v[2:5]
	v_mfma_f32_16x16x32_bf16 v[46:49], v[196:199], v[164:167], v[46:49]
	v_mfma_f32_16x16x32_bf16 v[42:45], v[212:215], v[164:167], v[42:45]
	v_mfma_f32_16x16x32_bf16 v[30:33], v[196:199], v[172:175], v[30:33]
	v_mfma_f32_16x16x32_bf16 v[26:29], v[212:215], v[172:175], v[26:29]
	v_mfma_f32_16x16x32_bf16 v[14:17], v[196:199], v[180:183], v[14:17]
	v_mfma_f32_16x16x32_bf16 v[10:13], v[212:215], v[180:183], v[10:13]
	v_mfma_f32_16x16x32_bf16 v[6:9], v[196:199], v[188:191], v[6:9]
	v_mfma_f32_16x16x32_bf16 v[2:5], v[212:215], v[188:191], v[2:5]
	s_setprio 0
	s_add_i32 s81, 0, 0x18000
	v_add_u32_e32 v156, s81, v141
	s_barrier
	ds_read_b128 v[144:147], v156
	ds_read_b128 v[148:151], v156 offset:1024
	ds_read_b128 v[152:155], v156 offset:2048
	ds_read_b128 v[156:159], v156 offset:3072
	s_add_u32 s58, s58, 0x80000
	s_addc_u32 s59, s59, 0
	s_mov_b32 m0, s69
	ds_read_b128 v[160:163], v143 offset:32768
	ds_read_b128 v[164:167], v143 offset:33792
	ds_read_b128 v[168:171], v143 offset:34816
	ds_read_b128 v[172:175], v143 offset:35840
	ds_read_b128 v[176:179], v143 offset:36864
	ds_read_b128 v[180:183], v143 offset:37888
	ds_read_b128 v[184:187], v143 offset:38912
	ds_read_b128 v[188:191], v143 offset:39936
	global_load_lds_dwordx4 v134, s[58:59]
	s_mov_b32 m0, s70
	s_nop 0
	global_load_lds_dwordx4 v132, s[58:59]
	s_waitcnt lgkmcnt(8)
	s_barrier
	s_waitcnt lgkmcnt(0)
	s_setprio 1
	s_waitcnt lgkmcnt(0)
	v_mfma_f32_16x16x32_bf16 v[126:129], v[144:147], v[160:163], v[126:129]
	v_mfma_f32_16x16x32_bf16 v[122:125], v[152:155], v[160:163], v[122:125]
	v_mfma_f32_16x16x32_bf16 v[118:121], v[144:147], v[168:171], v[118:121]
	v_mfma_f32_16x16x32_bf16 v[114:117], v[152:155], v[168:171], v[114:117]
	v_mfma_f32_16x16x32_bf16 v[102:105], v[144:147], v[176:179], v[102:105]
	v_mfma_f32_16x16x32_bf16 v[98:101], v[152:155], v[176:179], v[98:101]
	v_mfma_f32_16x16x32_bf16 v[86:89], v[144:147], v[184:187], v[86:89]
	v_mfma_f32_16x16x32_bf16 v[82:85], v[152:155], v[184:187], v[82:85]
	v_mfma_f32_16x16x32_bf16 v[126:129], v[148:151], v[164:167], v[126:129]
	v_mfma_f32_16x16x32_bf16 v[122:125], v[156:159], v[164:167], v[122:125]
	v_mfma_f32_16x16x32_bf16 v[118:121], v[148:151], v[172:175], v[118:121]
	v_mfma_f32_16x16x32_bf16 v[114:117], v[156:159], v[172:175], v[114:117]
	v_mfma_f32_16x16x32_bf16 v[102:105], v[148:151], v[180:183], v[102:105]
	v_mfma_f32_16x16x32_bf16 v[98:101], v[156:159], v[180:183], v[98:101]
	v_mfma_f32_16x16x32_bf16 v[86:89], v[148:151], v[188:191], v[86:89]
	v_mfma_f32_16x16x32_bf16 v[82:85], v[156:159], v[188:191], v[82:85]
	s_setprio 0
	s_barrier
	s_add_i32 s58, 0, 0x1c000
	s_add_i32 s59, s81, s64
	v_add_u32_e32 v212, s58, v141
	s_mov_b32 m0, s59
	ds_read_b128 v[192:195], v212
	ds_read_b128 v[196:199], v212 offset:1024
	ds_read_b128 v[208:211], v212 offset:2048
	ds_read_b128 v[212:215], v212 offset:3072
	global_load_lds_dwordx4 v0, s[98:99]
	s_add_i32 m0, s59, 0x2000
	s_nop 0
	global_load_lds_dwordx4 v130, s[98:99]
	s_barrier
	s_waitcnt lgkmcnt(0)
	s_setprio 1
	s_waitcnt lgkmcnt(0)
	v_mfma_f32_16x16x32_bf16 v[110:113], v[192:195], v[160:163], v[110:113]
	v_mfma_f32_16x16x32_bf16 v[106:109], v[208:211], v[160:163], v[106:109]
	v_mfma_f32_16x16x32_bf16 v[94:97], v[192:195], v[168:171], v[94:97]
	v_mfma_f32_16x16x32_bf16 v[90:93], v[208:211], v[168:171], v[90:93]
	v_mfma_f32_16x16x32_bf16 v[78:81], v[192:195], v[176:179], v[78:81]
	v_mfma_f32_16x16x32_bf16 v[74:77], v[208:211], v[176:179], v[74:77]
	v_mfma_f32_16x16x32_bf16 v[70:73], v[192:195], v[184:187], v[70:73]
	v_mfma_f32_16x16x32_bf16 v[66:69], v[208:211], v[184:187], v[66:69]
	v_mfma_f32_16x16x32_bf16 v[110:113], v[196:199], v[164:167], v[110:113]
	v_mfma_f32_16x16x32_bf16 v[106:109], v[212:215], v[164:167], v[106:109]
	v_mfma_f32_16x16x32_bf16 v[94:97], v[196:199], v[172:175], v[94:97]
	v_mfma_f32_16x16x32_bf16 v[90:93], v[212:215], v[172:175], v[90:93]
	v_mfma_f32_16x16x32_bf16 v[78:81], v[196:199], v[180:183], v[78:81]
	v_mfma_f32_16x16x32_bf16 v[74:77], v[212:215], v[180:183], v[74:77]
	v_mfma_f32_16x16x32_bf16 v[70:73], v[196:199], v[188:191], v[70:73]
	v_mfma_f32_16x16x32_bf16 v[66:69], v[212:215], v[188:191], v[66:69]
	s_setprio 0
	s_mov_b32 m0, s71
	s_barrier
	ds_read_b128 v[160:163], v143 offset:49152
	ds_read_b128 v[164:167], v143 offset:50176
	ds_read_b128 v[168:171], v143 offset:51200
	ds_read_b128 v[172:175], v143 offset:52224
	ds_read_b128 v[176:179], v143 offset:53248
	ds_read_b128 v[180:183], v143 offset:54272
	ds_read_b128 v[184:187], v143 offset:55296
	ds_read_b128 v[188:191], v143 offset:56320
	global_load_lds_dwordx4 v134, s[100:101]
	s_mov_b32 m0, s72
	s_nop 0
	global_load_lds_dwordx4 v132, s[100:101]
	s_barrier
; #define PG8_STAGE(bufoff, gbase, voff) do { _Pragma("unroll") for (int _i = 0; _i < 2; ++_i) \
;         __builtin_amdgcn_global_load_lds((const unsigned*)((const char*)(gbase) + (voff)[_i]), (LAS unsigned*)(lds + (bufoff) + ldsw + _i * 8192), 16, 0, 0); } while (0)
; #define PG8_MMA(ai, bj, At, Bt) do { __builtin_amdgcn_s_setprio(1); _Pragma("unroll") for (int m = 0; m < 4; ++m) _Pragma("unroll") for (int n = 0; n < 2; ++n) _Pragma("unroll") for (int k = 0; k < 2; ++k) \
;         acc[ai][bj][m][n] = __builtin_amdgcn_mfma_f32_16x16x32_bf16(Bt[n][k], At[m][k], acc[ai][bj][m][n], 0, 0, 0); __builtin_amdgcn_s_setprio(0); } while (0)
; #define PG8_WAIT_V(n) asm volatile("s_waitcnt vmcnt(" #n ")" ::: "memory")
; #define PG8_WAIT_L(n) asm volatile("s_waitcnt lgkmcnt(" #n ")" ::: "memory")
; #define PG8_BAR __builtin_amdgcn_s_barrier()
; #define PG8_SCHED __builtin_amdgcn_sched_barrier(0)
; template <class Epi>
; __device__ __forceinline__ void gemm_phase(LAS unsigned char* lds, const Gemm g, const StaticOrder& S, const Epi& E) {
;     ...
;             PG8_BAR; PG8_WAIT_L(0); PG8_MMA(1, 0, At, B0); PG8_BAR; PG8_SCHED;
;             PG8_STAGE(PG8_SB(1, 1), b3 + hstep, voffB);
;             PG8_WAIT_V(6); PG8_BAR; PG8_MMA(1, 1, At, B1); PG8_BAR;
;         }
	s_waitcnt lgkmcnt(0)
	s_setprio 1
	s_waitcnt lgkmcnt(0)
	v_mfma_f32_16x16x32_bf16 v[62:65], v[144:147], v[160:163], v[62:65]
	v_mfma_f32_16x16x32_bf16 v[58:61], v[152:155], v[160:163], v[58:61]
	v_mfma_f32_16x16x32_bf16 v[54:57], v[144:147], v[168:171], v[54:57]
	v_mfma_f32_16x16x32_bf16 v[50:53], v[152:155], v[168:171], v[50:53]
	v_mfma_f32_16x16x32_bf16 v[38:41], v[144:147], v[176:179], v[38:41]
	v_mfma_f32_16x16x32_bf16 v[34:37], v[152:155], v[176:179], v[34:37]
	v_mfma_f32_16x16x32_bf16 v[22:25], v[144:147], v[184:187], v[22:25]
	v_mfma_f32_16x16x32_bf16 v[18:21], v[152:155], v[184:187], v[18:21]
	v_mfma_f32_16x16x32_bf16 v[62:65], v[148:151], v[164:167], v[62:65]
	v_mfma_f32_16x16x32_bf16 v[58:61], v[156:159], v[164:167], v[58:61]
	v_mfma_f32_16x16x32_bf16 v[54:57], v[148:151], v[172:175], v[54:57]
	v_mfma_f32_16x16x32_bf16 v[50:53], v[156:159], v[172:175], v[50:53]
	v_mfma_f32_16x16x32_bf16 v[38:41], v[148:151], v[180:183], v[38:41]
	v_mfma_f32_16x16x32_bf16 v[34:37], v[156:159], v[180:183], v[34:37]
	v_mfma_f32_16x16x32_bf16 v[22:25], v[148:151], v[188:191], v[22:25]
	v_mfma_f32_16x16x32_bf16 v[18:21], v[156:159], v[188:191], v[18:21]
	s_setprio 0
	s_barrier
	s_add_u32 s56, s56, 0x80080
	s_addc_u32 s57, s57, 0
	s_add_i32 s58, s58, s64
	s_mov_b32 m0, s58
	s_nop 0
	global_load_lds_dwordx4 v0, s[56:57]
	s_add_i32 m0, s58, 0x2000
	s_nop 0
	global_load_lds_dwordx4 v130, s[56:57]
	s_waitcnt vmcnt(6)
	s_barrier
	s_setprio 1
	v_mfma_f32_16x16x32_bf16 v[46:49], v[192:195], v[160:163], v[46:49]
	v_mfma_f32_16x16x32_bf16 v[42:45], v[208:211], v[160:163], v[42:45]
	v_mfma_f32_16x16x32_bf16 v[30:33], v[192:195], v[168:171], v[30:33]
	v_mfma_f32_16x16x32_bf16 v[26:29], v[208:211], v[168:171], v[26:29]
	v_mfma_f32_16x16x32_bf16 v[14:17], v[192:195], v[176:179], v[14:17]
	v_mfma_f32_16x16x32_bf16 v[10:13], v[208:211], v[176:179], v[10:13]
	v_mfma_f32_16x16x32_bf16 v[6:9], v[192:195], v[184:187], v[6:9]
	v_mfma_f32_16x16x32_bf16 v[2:5], v[208:211], v[184:187], v[2:5]
	v_mfma_f32_16x16x32_bf16 v[46:49], v[196:199], v[164:167], v[46:49]
	v_mfma_f32_16x16x32_bf16 v[42:45], v[212:215], v[164:167], v[42:45]
	v_mfma_f32_16x16x32_bf16 v[30:33], v[196:199], v[172:175], v[30:33]
	v_mfma_f32_16x16x32_bf16 v[26:29], v[212:215], v[172:175], v[26:29]
	v_mfma_f32_16x16x32_bf16 v[14:17], v[196:199], v[180:183], v[14:17]
	v_mfma_f32_16x16x32_bf16 v[10:13], v[212:215], v[180:183], v[10:13]
	v_mfma_f32_16x16x32_bf16 v[6:9], v[196:199], v[188:191], v[6:9]
	v_mfma_f32_16x16x32_bf16 v[2:5], v[212:215], v[188:191], v[2:5]
	s_setprio 0
	s_add_i32 s80, s80, 2
	s_add_u32 s54, s54, 0x100
	s_addc_u32 s55, s55, 0
	s_add_u32 s78, s78, 0x100
	s_addc_u32 s79, s79, 0
	s_cmp_gt_u32 s80, 29
	s_barrier
	s_cbranch_scc0 .LBB0_77
; __device__ __forceinline__ unsigned pk2(float lo, float hi) { f32x2 v = {lo, hi}; bf16x2_t b = __builtin_convertvector(v, bf16x2_t); return __builtin_bit_cast(unsigned, b); }
; #define PG8_WAIT_V(n) asm volatile("s_waitcnt vmcnt(" #n ")" ::: "memory")
; #define PG8_BAR __builtin_amdgcn_s_barrier()
;     __device__ __forceinline__ void operator()(const AccT& acc, const Unit& u, int wr, int wc, int fr, int fq) const {
;     ...
;         for (int ai = 0; ai < 2; ++ai)
; #pragma unroll
;             for (int m = 0; m < 4; ++m) {
;                 const int row = row0 + ai * HALF + m * 16;
;                 const float rs = rsv[ai * 4 + m];
; #pragma unroll
;                 for (int bj = 0; bj < 2; ++bj) {
;                     const f32x4 v0 = acc[ai][bj][m][0] * rs, v1 = acc[ai][bj][m][1] * rs;
;                     u32x4 w; w.x = pk2(v0[0], v0[1]); w.y = pk2(v0[2], v0[3]); w.z = pk2(v1[0], v1[1]); w.w = pk2(v1[2], v1[3]);
;                     *(u32x4*)(out + (size_t)row * ldo + col0 + bj * HALF) = w;
;                 }
; template <class Epi>
; __device__ __forceinline__ void gemm_phase(LAS unsigned char* lds, const Gemm g, const StaticOrder& S, const Epi& E) {
;     ...
;         E(acc, cur, wr, wc, fr, fq);
;         if (!has_next) break;
; #pragma unroll
;         for (int a = 0; a < 2; ++a)
; #pragma unroll
;             for (int b = 0; b < 2; ++b)
; #pragma unroll
;                 for (int m = 0; m < 4; ++m)
; #pragma unroll
;                     for (int n = 0; n < 2; ++n) acc[a][b][m][n] = (f32x4){0.f, 0.f, 0.f, 0.f};
;         cur = nxt; cA = nA; cB = nB; ++ui;
;     }
;     PG8_WAIT_V(0);
;     if (wr == 0) PG8_BAR;
	v_lshl_add_u32 v146, s74, 8, v140
	v_lshl_or_b32 v144, s75, 8, v142
	v_ashrrev_i32_e32 v147, 31, v146
	v_ashrrev_i32_e32 v145, 31, v144
	v_cvt_pk_bf16_f32 v126, v126, v127
	v_cvt_pk_bf16_f32 v127, v128, v129
	v_cvt_pk_bf16_f32 v128, v122, v123
	v_lshlrev_b64 v[122:123], 11, v[146:147]
	v_cvt_pk_bf16_f32 v129, v124, v125
	v_lshl_add_u64 v[122:123], s[42:43], 0, v[122:123]
	v_lshlrev_b64 v[124:125], 1, v[144:145]
	v_lshl_add_u64 v[122:123], v[122:123], 0, v[124:125]
	v_cvt_pk_bf16_f32 v110, v110, v111
	v_cvt_pk_bf16_f32 v111, v112, v113
	v_cvt_pk_bf16_f32 v112, v106, v107
	v_cvt_pk_bf16_f32 v113, v108, v109
	global_store_dwordx4 v[122:123], v[110:113], off offset:256
	v_cvt_pk_bf16_f32 v94, v94, v95
	v_cvt_pk_bf16_f32 v95, v96, v97
	v_or_b32_e32 v110, 16, v146
	v_ashrrev_i32_e32 v111, 31, v110
	v_lshlrev_b64 v[110:111], 11, v[110:111]
	v_lshl_add_u64 v[110:111], s[42:43], 0, v[110:111]
	v_lshl_add_u64 v[110:111], v[110:111], 0, v[124:125]
	v_cvt_pk_bf16_f32 v96, v90, v91
	v_cvt_pk_bf16_f32 v97, v92, v93
	global_store_dwordx4 v[110:111], v[94:97], off offset:256
	s_mov_b32 s47, 0x40000
	v_cvt_pk_bf16_f32 v62, v62, v63
	v_or_b32_e32 v94, 32, v146
	v_ashrrev_i32_e32 v95, 31, v94
	v_cvt_pk_bf16_f32 v63, v64, v65
	v_cvt_pk_bf16_f32 v65, v60, v61
	s_mov_b64 s[54:55], 0x40000
	v_add_co_u32_e32 v60, vcc, s47, v122
	v_lshlrev_b64 v[94:95], 11, v[94:95]
	v_cvt_pk_bf16_f32 v64, v58, v59
	v_lshl_add_u64 v[58:59], v[122:123], 0, s[54:55]
	v_addc_co_u32_e32 v61, vcc, 0, v123, vcc
	v_cvt_pk_bf16_f32 v46, v46, v47
	v_cvt_pk_bf16_f32 v47, v48, v49
	v_cvt_pk_bf16_f32 v48, v42, v43
	v_cvt_pk_bf16_f32 v49, v44, v45
	s_mov_b32 s47, 0x48000
	v_lshl_add_u64 v[94:95], s[42:43], 0, v[94:95]
	global_store_dwordx4 v[58:59], v[46:49], off offset:256
	s_mov_b64 s[54:55], 0x48000
	v_lshl_add_u64 v[94:95], v[94:95], 0, v[124:125]
	v_add_co_u32_e32 v48, vcc, s47, v122
	v_cvt_pk_bf16_f32 v78, v78, v79
	v_cvt_pk_bf16_f32 v79, v80, v81
	v_cvt_pk_bf16_f32 v80, v74, v75
	v_cvt_pk_bf16_f32 v81, v76, v77
	v_lshl_add_u64 v[46:47], v[122:123], 0, s[54:55]
	v_addc_co_u32_e32 v49, vcc, 0, v123, vcc
	v_cvt_pk_bf16_f32 v30, v30, v31
	v_cvt_pk_bf16_f32 v31, v32, v33
	v_cvt_pk_bf16_f32 v32, v26, v27
	v_cvt_pk_bf16_f32 v33, v28, v29
	s_mov_b32 s47, 0x50000
	global_store_dwordx4 v[94:95], v[78:81], off offset:256
	global_store_dwordx4 v[46:47], v[30:33], off offset:256
	s_mov_b64 s[54:55], 0x50000
	v_or_b32_e32 v78, 48, v146
	v_add_co_u32_e32 v32, vcc, s47, v122
	v_ashrrev_i32_e32 v79, 31, v78
	v_lshl_add_u64 v[30:31], v[122:123], 0, s[54:55]
	v_addc_co_u32_e32 v33, vcc, 0, v123, vcc
	v_cvt_pk_bf16_f32 v14, v14, v15
	v_cvt_pk_bf16_f32 v15, v16, v17
	v_cvt_pk_bf16_f32 v16, v10, v11
	v_cvt_pk_bf16_f32 v17, v12, v13
	s_mov_b32 s47, 0x58000
	v_lshlrev_b64 v[78:79], 11, v[78:79]
	global_store_dwordx4 v[30:31], v[14:17], off offset:256
	v_lshl_add_u64 v[78:79], s[42:43], 0, v[78:79]
	s_mov_b64 s[54:55], 0x58000
	v_add_co_u32_e32 v16, vcc, s47, v122
	v_cvt_pk_bf16_f32 v106, v118, v119
	s_nop 0
	v_addc_co_u32_e32 v17, vcc, 0, v123, vcc
	v_cvt_pk_bf16_f32 v107, v120, v121
	v_cvt_pk_bf16_f32 v108, v114, v115
	v_cvt_pk_bf16_f32 v109, v116, v117
	v_cvt_pk_bf16_f32 v90, v102, v103
	v_cvt_pk_bf16_f32 v91, v104, v105
	v_cvt_pk_bf16_f32 v92, v98, v99
	v_cvt_pk_bf16_f32 v93, v100, v101
	v_cvt_pk_bf16_f32 v74, v86, v87
	v_cvt_pk_bf16_f32 v75, v88, v89
	v_cvt_pk_bf16_f32 v76, v82, v83
	v_cvt_pk_bf16_f32 v77, v84, v85
	v_lshl_add_u64 v[78:79], v[78:79], 0, v[124:125]
	v_cvt_pk_bf16_f32 v70, v70, v71
	v_cvt_pk_bf16_f32 v71, v72, v73
	v_cvt_pk_bf16_f32 v72, v66, v67
	v_cvt_pk_bf16_f32 v73, v68, v69
	v_cvt_pk_bf16_f32 v42, v54, v55
	v_cvt_pk_bf16_f32 v43, v56, v57
	v_cvt_pk_bf16_f32 v44, v50, v51
	v_cvt_pk_bf16_f32 v45, v52, v53
	v_cvt_pk_bf16_f32 v26, v38, v39
	v_cvt_pk_bf16_f32 v27, v40, v41
	v_cvt_pk_bf16_f32 v28, v34, v35
	v_cvt_pk_bf16_f32 v29, v36, v37
	v_cvt_pk_bf16_f32 v10, v22, v23
	v_cvt_pk_bf16_f32 v11, v24, v25
	v_cvt_pk_bf16_f32 v12, v18, v19
	v_cvt_pk_bf16_f32 v13, v20, v21
	v_lshl_add_u64 v[14:15], v[122:123], 0, s[54:55]
	v_cvt_pk_bf16_f32 v6, v6, v7
	v_cvt_pk_bf16_f32 v7, v8, v9
	v_cvt_pk_bf16_f32 v8, v2, v3
	v_cvt_pk_bf16_f32 v9, v4, v5
	s_and_b64 vcc, exec, s[44:45]
	s_mov_b32 s75, s46
	s_mov_b32 s74, s48
	s_mov_b64 s[56:57], s[52:53]
	s_mov_b64 s[54:55], s[50:51]
	global_store_dwordx4 v[122:123], v[126:129], off
	global_store_dwordx4 v[110:111], v[106:109], off
	global_store_dwordx4 v[94:95], v[90:93], off
	global_store_dwordx4 v[78:79], v[74:77], off
	global_store_dwordx4 v[78:79], v[70:73], off offset:256
	global_store_dwordx4 v[60:61], v[62:65], off
	global_store_dwordx4 v[48:49], v[42:45], off
	global_store_dwordx4 v[32:33], v[26:29], off
	global_store_dwordx4 v[16:17], v[10:13], off
	global_store_dwordx4 v[14:15], v[6:9], off offset:256
	s_cbranch_vccz .LBB0_74
	s_waitcnt vmcnt(0)
	s_cmpk_gt_u32 s60, 0xff
	s_cbranch_scc1 .LBB0_81
	s_barrier

; #define PG8_STAGE(bufoff, gbase, voff) do { _Pragma("unroll") for (int _i = 0; _i < 2; ++_i) \
;         __builtin_amdgcn_global_load_lds((const unsigned*)((const char*)(gbase) + (voff)[_i]), (LAS unsigned*)(lds + (bufoff) + ldsw + _i * 8192), 16, 0, 0); } while (0)
; #define PG8_LDA(dst, b, h) do { _Pragma("unroll") for (int m = 0; m < 4; ++m) _Pragma("unroll") for (int k = 0; k < 2; ++k) dst[m][k] = *(const LAS bf16x8*)(lds + PG8_SA(b, h) + aoff + m * 2048 + k * 1024); } while (0)
; #define PG8_LDB(dst, b, h) do { _Pragma("unroll") for (int n = 0; n < 2; ++n) _Pragma("unroll") for (int k = 0; k < 2; ++k) dst[n][k] = *(const LAS bf16x8*)(lds + PG8_SB(b, h) + boff + n * 2048 + k * 1024); } while (0)
; #define PG8_MMA(ai, bj, At, Bt) do { __builtin_amdgcn_s_setprio(1); _Pragma("unroll") for (int m = 0; m < 4; ++m) _Pragma("unroll") for (int n = 0; n < 2; ++n) _Pragma("unroll") for (int k = 0; k < 2; ++k) \
;         acc[ai][bj][m][n] = __builtin_amdgcn_mfma_f32_16x16x32_bf16(Bt[n][k], At[m][k], acc[ai][bj][m][n], 0, 0, 0); __builtin_amdgcn_s_setprio(0); } while (0)
; #define PG8_WAIT_V(n) asm volatile("s_waitcnt vmcnt(" #n ")" ::: "memory")
; #define PG8_WAIT_L(n) asm volatile("s_waitcnt lgkmcnt(" #n ")" ::: "memory")
; #define PG8_BAR __builtin_amdgcn_s_barrier()
; #define PG8_SCHED __builtin_amdgcn_sched_barrier(0)
; template <class Epi>
; __device__ __forceinline__ void gemm_phase(LAS unsigned char* lds, const Gemm g, const StaticOrder& S, const Epi& E) {
;     ...
;             PG8_LDB(B0, 0, 0); PG8_SCHED; PG8_LDA(At, 0, 0); PG8_STAGE(PG8_SA(1, 1), a1 + hstep, voffA);
;             PG8_WAIT_L(8); PG8_BAR; PG8_WAIT_L(0); PG8_MMA(0, 0, At, B0); PG8_BAR; PG8_SCHED;
;             PG8_LDB(B1, 0, 1); PG8_STAGE(PG8_SB(0, 0), b2, voffB);
;             PG8_BAR; PG8_WAIT_L(0); PG8_MMA(0, 1, At, B1); PG8_BAR;
;             PG8_LDA(At, 0, 1); PG8_STAGE(PG8_SA(0, 0), a2, voffA);
;             PG8_BAR; PG8_WAIT_L(0); PG8_MMA(1, 0, At, B0); PG8_BAR; PG8_SCHED;
;             PG8_STAGE(PG8_SB(0, 1), b2 + hstep, voffB);
;             PG8_WAIT_V(6); PG8_BAR; PG8_MMA(1, 1, At, B1); PG8_BAR;
.LBB0_90:
	s_add_u32 s48, s46, 0xfff80080
	s_addc_u32 s49, s47, -1
	s_add_i32 s74, 0, 0x10000
	v_add_u32_e32 v140, s74, v143
	ds_read_b128 v[152:155], v140
	ds_read_b128 v[156:159], v140 offset:1024
	ds_read_b128 v[160:163], v140 offset:2048
	ds_read_b128 v[164:167], v140 offset:3072
	s_cmp_eq_u32 s73, 28
	s_cselect_b32 s51, s41, s49
	s_cselect_b32 s50, s69, s48
	s_cselect_b32 s49, s39, s72
	s_cselect_b32 s48, s70, s71
	s_add_i32 m0, s56, 0xc000
	ds_read_b128 v[168:171], v151
	ds_read_b128 v[172:175], v151 offset:1024
	ds_read_b128 v[176:179], v151 offset:2048
	ds_read_b128 v[180:183], v151 offset:3072
	ds_read_b128 v[184:187], v151 offset:4096
	ds_read_b128 v[188:191], v151 offset:5120
	ds_read_b128 v[192:195], v151 offset:6144
	ds_read_b128 v[196:199], v151 offset:7168
	global_load_lds_dwordx4 v136, s[46:47]
	s_add_i32 m0, s56, 0xe000
	s_nop 0
	global_load_lds_dwordx4 v138, s[46:47]
	s_waitcnt lgkmcnt(8)
	s_barrier
	s_waitcnt lgkmcnt(0)
	s_setprio 1
	s_waitcnt lgkmcnt(0)
	v_mfma_f32_16x16x32_bf16 v[126:129], v[152:155], v[168:171], v[126:129]
	v_mfma_f32_16x16x32_bf16 v[122:125], v[160:163], v[168:171], v[122:125]
	v_mfma_f32_16x16x32_bf16 v[110:113], v[152:155], v[176:179], v[110:113]
	v_mfma_f32_16x16x32_bf16 v[102:105], v[160:163], v[176:179], v[102:105]
	v_mfma_f32_16x16x32_bf16 v[94:97], v[152:155], v[184:187], v[94:97]
	v_mfma_f32_16x16x32_bf16 v[86:89], v[160:163], v[184:187], v[86:89]
	v_mfma_f32_16x16x32_bf16 v[78:81], v[152:155], v[192:195], v[78:81]
	v_mfma_f32_16x16x32_bf16 v[70:73], v[160:163], v[192:195], v[70:73]
	v_mfma_f32_16x16x32_bf16 v[126:129], v[156:159], v[172:175], v[126:129]
	v_mfma_f32_16x16x32_bf16 v[122:125], v[164:167], v[172:175], v[122:125]
	v_mfma_f32_16x16x32_bf16 v[110:113], v[156:159], v[180:183], v[110:113]
	v_mfma_f32_16x16x32_bf16 v[102:105], v[164:167], v[180:183], v[102:105]
	v_mfma_f32_16x16x32_bf16 v[94:97], v[156:159], v[188:191], v[94:97]
	v_mfma_f32_16x16x32_bf16 v[86:89], v[164:167], v[188:191], v[86:89]
	v_mfma_f32_16x16x32_bf16 v[78:81], v[156:159], v[196:199], v[78:81]
	v_mfma_f32_16x16x32_bf16 v[70:73], v[164:167], v[196:199], v[70:73]
	s_setprio 0
	s_barrier
	s_add_i32 s76, 0, 0x14000
	s_add_i32 s74, s74, s55
	v_add_u32_e32 v140, s76, v143
	s_mov_b32 m0, s74
	ds_read_b128 v[208:211], v140
	ds_read_b128 v[212:215], v140 offset:1024
	ds_read_b128 v[216:219], v140 offset:2048
	ds_read_b128 v[220:223], v140 offset:3072
	global_load_lds_dwordx4 v0, s[48:49]
	s_add_i32 m0, s74, 0x2000
	s_add_u32 s98, s48, s22
	global_load_lds_dwordx4 v130, s[48:49]
	s_addc_u32 s99, s49, s23
	s_barrier
	s_waitcnt lgkmcnt(0)
	s_setprio 1
	s_waitcnt lgkmcnt(0)
	v_mfma_f32_16x16x32_bf16 v[118:121], v[208:211], v[168:171], v[118:121]
	v_mfma_f32_16x16x32_bf16 v[114:117], v[216:219], v[168:171], v[114:117]
	v_mfma_f32_16x16x32_bf16 v[106:109], v[208:211], v[176:179], v[106:109]
	v_mfma_f32_16x16x32_bf16 v[98:101], v[216:219], v[176:179], v[98:101]
	v_mfma_f32_16x16x32_bf16 v[90:93], v[208:211], v[184:187], v[90:93]
	v_mfma_f32_16x16x32_bf16 v[82:85], v[216:219], v[184:187], v[82:85]
	v_mfma_f32_16x16x32_bf16 v[74:77], v[208:211], v[192:195], v[74:77]
	v_mfma_f32_16x16x32_bf16 v[66:69], v[216:219], v[192:195], v[66:69]
	v_mfma_f32_16x16x32_bf16 v[118:121], v[212:215], v[172:175], v[118:121]
	v_mfma_f32_16x16x32_bf16 v[114:117], v[220:223], v[172:175], v[114:117]
	v_mfma_f32_16x16x32_bf16 v[106:109], v[212:215], v[180:183], v[106:109]
	v_mfma_f32_16x16x32_bf16 v[98:101], v[220:223], v[180:183], v[98:101]
	v_mfma_f32_16x16x32_bf16 v[90:93], v[212:215], v[188:191], v[90:93]
	v_mfma_f32_16x16x32_bf16 v[82:85], v[220:223], v[188:191], v[82:85]
	v_mfma_f32_16x16x32_bf16 v[74:77], v[212:215], v[196:199], v[74:77]
	v_mfma_f32_16x16x32_bf16 v[66:69], v[220:223], v[196:199], v[66:69]
	s_setprio 0
	s_mov_b32 m0, s56
	s_add_u32 s100, s50, s22
	s_addc_u32 s101, s51, s23
	s_barrier
	ds_read_b128 v[168:171], v151 offset:16384
	ds_read_b128 v[172:175], v151 offset:17408
	ds_read_b128 v[176:179], v151 offset:18432
	ds_read_b128 v[180:183], v151 offset:19456
	ds_read_b128 v[184:187], v151 offset:20480
	ds_read_b128 v[188:191], v151 offset:21504
	ds_read_b128 v[192:195], v151 offset:22528
	ds_read_b128 v[196:199], v151 offset:23552
	global_load_lds_dwordx4 v134, s[50:51]
	s_mov_b32 m0, s57
	s_nop 0
	global_load_lds_dwordx4 v132, s[50:51]
	s_barrier
	s_waitcnt lgkmcnt(0)
	s_setprio 1
	s_waitcnt lgkmcnt(0)
	v_mfma_f32_16x16x32_bf16 v[62:65], v[152:155], v[168:171], v[62:65]
	v_mfma_f32_16x16x32_bf16 v[54:57], v[160:163], v[168:171], v[54:57]
	v_mfma_f32_16x16x32_bf16 v[46:49], v[152:155], v[176:179], v[46:49]
	v_mfma_f32_16x16x32_bf16 v[38:41], v[160:163], v[176:179], v[38:41]
	v_mfma_f32_16x16x32_bf16 v[30:33], v[152:155], v[184:187], v[30:33]
	v_mfma_f32_16x16x32_bf16 v[22:25], v[160:163], v[184:187], v[22:25]
	v_mfma_f32_16x16x32_bf16 v[14:17], v[152:155], v[192:195], v[14:17]
	v_mfma_f32_16x16x32_bf16 v[6:9], v[160:163], v[192:195], v[6:9]
	v_mfma_f32_16x16x32_bf16 v[62:65], v[156:159], v[172:175], v[62:65]
	v_mfma_f32_16x16x32_bf16 v[54:57], v[164:167], v[172:175], v[54:57]
	v_mfma_f32_16x16x32_bf16 v[46:49], v[156:159], v[180:183], v[46:49]
	v_mfma_f32_16x16x32_bf16 v[38:41], v[164:167], v[180:183], v[38:41]
	v_mfma_f32_16x16x32_bf16 v[30:33], v[156:159], v[188:191], v[30:33]
	v_mfma_f32_16x16x32_bf16 v[22:25], v[164:167], v[188:191], v[22:25]
	v_mfma_f32_16x16x32_bf16 v[14:17], v[156:159], v[196:199], v[14:17]
	v_mfma_f32_16x16x32_bf16 v[6:9], v[164:167], v[196:199], v[6:9]
	s_setprio 0
	s_barrier
	s_add_u32 s74, s48, 0x80000
	s_addc_u32 s75, s49, 0
	s_add_i32 s76, s76, s55
	s_mov_b32 m0, s76
	s_nop 0
	global_load_lds_dwordx4 v0, s[74:75]
	s_add_i32 m0, s76, 0x2000
	s_nop 0
	global_load_lds_dwordx4 v130, s[74:75]
	s_waitcnt vmcnt(6)
	s_barrier
; #define PG8_STAGE(bufoff, gbase, voff) do { _Pragma("unroll") for (int _i = 0; _i < 2; ++_i) \
;         __builtin_amdgcn_global_load_lds((const unsigned*)((const char*)(gbase) + (voff)[_i]), (LAS unsigned*)(lds + (bufoff) + ldsw + _i * 8192), 16, 0, 0); } while (0)
; #define PG8_LDA(dst, b, h) do { _Pragma("unroll") for (int m = 0; m < 4; ++m) _Pragma("unroll") for (int k = 0; k < 2; ++k) dst[m][k] = *(const LAS bf16x8*)(lds + PG8_SA(b, h) + aoff + m * 2048 + k * 1024); } while (0)
; #define PG8_LDB(dst, b, h) do { _Pragma("unroll") for (int n = 0; n < 2; ++n) _Pragma("unroll") for (int k = 0; k < 2; ++k) dst[n][k] = *(const LAS bf16x8*)(lds + PG8_SB(b, h) + boff + n * 2048 + k * 1024); } while (0)
; #define PG8_MMA(ai, bj, At, Bt) do { __builtin_amdgcn_s_setprio(1); _Pragma("unroll") for (int m = 0; m < 4; ++m) _Pragma("unroll") for (int n = 0; n < 2; ++n) _Pragma("unroll") for (int k = 0; k < 2; ++k) \
;         acc[ai][bj][m][n] = __builtin_amdgcn_mfma_f32_16x16x32_bf16(Bt[n][k], At[m][k], acc[ai][bj][m][n], 0, 0, 0); __builtin_amdgcn_s_setprio(0); } while (0)
; #define PG8_WAIT_V(n) asm volatile("s_waitcnt vmcnt(" #n ")" ::: "memory")
; #define PG8_WAIT_L(n) asm volatile("s_waitcnt lgkmcnt(" #n ")" ::: "memory")
; #define PG8_BAR __builtin_amdgcn_s_barrier()
; #define PG8_SCHED __builtin_amdgcn_sched_barrier(0)
; template <class Epi>
; __device__ __forceinline__ void gemm_phase(LAS unsigned char* lds, const Gemm g, const StaticOrder& S, const Epi& E) {
;     ...
;             PG8_WAIT_V(6); PG8_BAR; PG8_MMA(1, 1, At, B1); PG8_BAR;
;             PG8_LDB(B0, 1, 0); PG8_SCHED; PG8_LDA(At, 1, 0); PG8_STAGE(PG8_SA(0, 1), a2 + hstep, voffA);
;             PG8_WAIT_L(8); PG8_BAR; PG8_WAIT_L(0); PG8_MMA(0, 0, At, B0); PG8_BAR; PG8_SCHED;
;             PG8_LDB(B1, 1, 1); PG8_STAGE(PG8_SB(1, 0), b3, voffB);
;             PG8_BAR; PG8_WAIT_L(0); PG8_MMA(0, 1, At, B1); PG8_BAR;
;             PG8_LDA(At, 1, 1); PG8_STAGE(PG8_SA(1, 0), a3, voffA);
;             PG8_BAR; PG8_WAIT_L(0); PG8_MMA(1, 0, At, B0); PG8_BAR; PG8_SCHED;
	s_setprio 1
	v_mfma_f32_16x16x32_bf16 v[58:61], v[208:211], v[168:171], v[58:61]
	v_mfma_f32_16x16x32_bf16 v[50:53], v[216:219], v[168:171], v[50:53]
	v_mfma_f32_16x16x32_bf16 v[42:45], v[208:211], v[176:179], v[42:45]
	v_mfma_f32_16x16x32_bf16 v[34:37], v[216:219], v[176:179], v[34:37]
	v_mfma_f32_16x16x32_bf16 v[26:29], v[208:211], v[184:187], v[26:29]
	v_mfma_f32_16x16x32_bf16 v[18:21], v[216:219], v[184:187], v[18:21]
	v_mfma_f32_16x16x32_bf16 v[10:13], v[208:211], v[192:195], v[10:13]
	v_mfma_f32_16x16x32_bf16 v[2:5], v[216:219], v[192:195], v[2:5]
	v_mfma_f32_16x16x32_bf16 v[58:61], v[212:215], v[172:175], v[58:61]
	v_mfma_f32_16x16x32_bf16 v[50:53], v[220:223], v[172:175], v[50:53]
	v_mfma_f32_16x16x32_bf16 v[42:45], v[212:215], v[180:183], v[42:45]
	v_mfma_f32_16x16x32_bf16 v[34:37], v[220:223], v[180:183], v[34:37]
	v_mfma_f32_16x16x32_bf16 v[26:29], v[212:215], v[188:191], v[26:29]
	v_mfma_f32_16x16x32_bf16 v[18:21], v[220:223], v[188:191], v[18:21]
	v_mfma_f32_16x16x32_bf16 v[10:13], v[212:215], v[196:199], v[10:13]
	v_mfma_f32_16x16x32_bf16 v[2:5], v[220:223], v[196:199], v[2:5]
	s_setprio 0
	s_add_i32 s74, 0, 0x18000
	v_add_u32_e32 v140, s74, v143
	s_barrier
	ds_read_b128 v[152:155], v140
	ds_read_b128 v[156:159], v140 offset:1024
	ds_read_b128 v[160:163], v140 offset:2048
	ds_read_b128 v[164:167], v140 offset:3072
	s_add_u32 s50, s50, 0x80000
	s_addc_u32 s51, s51, 0
	s_mov_b32 m0, s58
	ds_read_b128 v[168:171], v151 offset:32768
	ds_read_b128 v[172:175], v151 offset:33792
	ds_read_b128 v[176:179], v151 offset:34816
	ds_read_b128 v[180:183], v151 offset:35840
	ds_read_b128 v[184:187], v151 offset:36864
	ds_read_b128 v[188:191], v151 offset:37888
	ds_read_b128 v[192:195], v151 offset:38912
	ds_read_b128 v[196:199], v151 offset:39936
	global_load_lds_dwordx4 v134, s[50:51]
	s_mov_b32 m0, s59
	s_nop 0
	global_load_lds_dwordx4 v132, s[50:51]
	s_waitcnt lgkmcnt(8)
	s_barrier
	s_waitcnt lgkmcnt(0)
	s_setprio 1
	s_waitcnt lgkmcnt(0)
	v_mfma_f32_16x16x32_bf16 v[126:129], v[152:155], v[168:171], v[126:129]
	v_mfma_f32_16x16x32_bf16 v[122:125], v[160:163], v[168:171], v[122:125]
	v_mfma_f32_16x16x32_bf16 v[110:113], v[152:155], v[176:179], v[110:113]
	v_mfma_f32_16x16x32_bf16 v[102:105], v[160:163], v[176:179], v[102:105]
	v_mfma_f32_16x16x32_bf16 v[94:97], v[152:155], v[184:187], v[94:97]
	v_mfma_f32_16x16x32_bf16 v[86:89], v[160:163], v[184:187], v[86:89]
	v_mfma_f32_16x16x32_bf16 v[78:81], v[152:155], v[192:195], v[78:81]
	v_mfma_f32_16x16x32_bf16 v[70:73], v[160:163], v[192:195], v[70:73]
	v_mfma_f32_16x16x32_bf16 v[126:129], v[156:159], v[172:175], v[126:129]
	v_mfma_f32_16x16x32_bf16 v[122:125], v[164:167], v[172:175], v[122:125]
	v_mfma_f32_16x16x32_bf16 v[110:113], v[156:159], v[180:183], v[110:113]
	v_mfma_f32_16x16x32_bf16 v[102:105], v[164:167], v[180:183], v[102:105]
	v_mfma_f32_16x16x32_bf16 v[94:97], v[156:159], v[188:191], v[94:97]
	v_mfma_f32_16x16x32_bf16 v[86:89], v[164:167], v[188:191], v[86:89]
	v_mfma_f32_16x16x32_bf16 v[78:81], v[156:159], v[196:199], v[78:81]
	v_mfma_f32_16x16x32_bf16 v[70:73], v[164:167], v[196:199], v[70:73]
	s_setprio 0
	s_barrier
	s_add_i32 s50, 0, 0x1c000
	s_add_i32 s51, s74, s55
	v_add_u32_e32 v140, s50, v143
	s_mov_b32 m0, s51
	ds_read_b128 v[208:211], v140
	ds_read_b128 v[212:215], v140 offset:1024
	ds_read_b128 v[216:219], v140 offset:2048
	ds_read_b128 v[220:223], v140 offset:3072
	global_load_lds_dwordx4 v0, s[98:99]
	s_add_i32 m0, s51, 0x2000
	s_nop 0
	global_load_lds_dwordx4 v130, s[98:99]
	s_barrier
	s_waitcnt lgkmcnt(0)
	s_setprio 1
	s_waitcnt lgkmcnt(0)
	v_mfma_f32_16x16x32_bf16 v[118:121], v[208:211], v[168:171], v[118:121]
	v_mfma_f32_16x16x32_bf16 v[114:117], v[216:219], v[168:171], v[114:117]
	v_mfma_f32_16x16x32_bf16 v[106:109], v[208:211], v[176:179], v[106:109]
	v_mfma_f32_16x16x32_bf16 v[98:101], v[216:219], v[176:179], v[98:101]
	v_mfma_f32_16x16x32_bf16 v[90:93], v[208:211], v[184:187], v[90:93]
	v_mfma_f32_16x16x32_bf16 v[82:85], v[216:219], v[184:187], v[82:85]
	v_mfma_f32_16x16x32_bf16 v[74:77], v[208:211], v[192:195], v[74:77]
	v_mfma_f32_16x16x32_bf16 v[66:69], v[216:219], v[192:195], v[66:69]
	v_mfma_f32_16x16x32_bf16 v[118:121], v[212:215], v[172:175], v[118:121]
	v_mfma_f32_16x16x32_bf16 v[114:117], v[220:223], v[172:175], v[114:117]
	v_mfma_f32_16x16x32_bf16 v[106:109], v[212:215], v[180:183], v[106:109]
	v_mfma_f32_16x16x32_bf16 v[98:101], v[220:223], v[180:183], v[98:101]
	v_mfma_f32_16x16x32_bf16 v[90:93], v[212:215], v[188:191], v[90:93]
	v_mfma_f32_16x16x32_bf16 v[82:85], v[220:223], v[188:191], v[82:85]
	v_mfma_f32_16x16x32_bf16 v[74:77], v[212:215], v[196:199], v[74:77]
	v_mfma_f32_16x16x32_bf16 v[66:69], v[220:223], v[196:199], v[66:69]
	s_setprio 0
	s_mov_b32 m0, s61
	s_barrier
	ds_read_b128 v[168:171], v151 offset:49152
	ds_read_b128 v[172:175], v151 offset:50176
	ds_read_b128 v[176:179], v151 offset:51200
	ds_read_b128 v[180:183], v151 offset:52224
	ds_read_b128 v[184:187], v151 offset:53248
	ds_read_b128 v[188:191], v151 offset:54272
	ds_read_b128 v[192:195], v151 offset:55296
	ds_read_b128 v[196:199], v151 offset:56320
	global_load_lds_dwordx4 v134, s[100:101]
	s_mov_b32 m0, s63
	s_nop 0
	global_load_lds_dwordx4 v132, s[100:101]
	s_barrier
; #define PG8_STAGE(bufoff, gbase, voff) do { _Pragma("unroll") for (int _i = 0; _i < 2; ++_i) \
;         __builtin_amdgcn_global_load_lds((const unsigned*)((const char*)(gbase) + (voff)[_i]), (LAS unsigned*)(lds + (bufoff) + ldsw + _i * 8192), 16, 0, 0); } while (0)
; #define PG8_MMA(ai, bj, At, Bt) do { __builtin_amdgcn_s_setprio(1); _Pragma("unroll") for (int m = 0; m < 4; ++m) _Pragma("unroll") for (int n = 0; n < 2; ++n) _Pragma("unroll") for (int k = 0; k < 2; ++k) \
;         acc[ai][bj][m][n] = __builtin_amdgcn_mfma_f32_16x16x32_bf16(Bt[n][k], At[m][k], acc[ai][bj][m][n], 0, 0, 0); __builtin_amdgcn_s_setprio(0); } while (0)
; #define PG8_WAIT_V(n) asm volatile("s_waitcnt vmcnt(" #n ")" ::: "memory")
; #define PG8_WAIT_L(n) asm volatile("s_waitcnt lgkmcnt(" #n ")" ::: "memory")
;     __device__ __forceinline__ void operator()(const AccT& acc, const Unit& u, int wr, int wc, int fr, int fq) const {
;     ...
;         {
;             const int ln = (fq << 4) | fr;
;             float sa = ss[u.pm * BM + wr * 64 + ln], sb = ss[u.pm * BM + HALF + wr * 64 + ln];
;             sa = __builtin_amdgcn_rsqf(sa * (1.0f / DM) + EPS); sb = __builtin_amdgcn_rsqf(sb * (1.0f / DM) + EPS);
; #pragma unroll
;             for (int m = 0; m < 4; ++m) { rsv[m] = __shfl(sa, 16 * m + fr); rsv[4 + m] = __shfl(sb, 16 * m + fr); }
;         }
; #pragma unroll
;         for (int ai = 0; ai < 2; ++ai)
; #pragma unroll
;             for (int m = 0; m < 4; ++m) {
;                 const int row = row0 + ai * HALF + m * 16;
;                 const float rs = rsv[ai * 4 + m];
;                 float v[8];
; #pragma unroll
;                 for (int n = 0; n < 2; ++n)
; #pragma unroll
;                     for (int j = 0; j < 4; ++j) {
;                         const float g = acc[ai][0][m][n][j] * rs, up = acc[ai][1][m][n][j] * rs;
;                         const float sg = __builtin_amdgcn_rcpf(1.0f + __builtin_amdgcn_exp2f(-g * LOG2E));
;                         v[4 * n + j] = g * sg * up;
;                     }
; template <class Epi>
; __device__ __forceinline__ void gemm_phase(LAS unsigned char* lds, const Gemm g, const StaticOrder& S, const Epi& E) {
;     ...
;             PG8_BAR; PG8_WAIT_L(0); PG8_MMA(1, 0, At, B0); PG8_BAR; PG8_SCHED;
;             PG8_STAGE(PG8_SB(1, 1), b3 + hstep, voffB);
;             PG8_WAIT_V(6); PG8_BAR; PG8_MMA(1, 1, At, B1); PG8_BAR;
	s_waitcnt lgkmcnt(0)
	s_setprio 1
	s_waitcnt lgkmcnt(0)
	v_mfma_f32_16x16x32_bf16 v[62:65], v[152:155], v[168:171], v[62:65]
	v_mfma_f32_16x16x32_bf16 v[54:57], v[160:163], v[168:171], v[54:57]
	v_mfma_f32_16x16x32_bf16 v[46:49], v[152:155], v[176:179], v[46:49]
	v_mfma_f32_16x16x32_bf16 v[38:41], v[160:163], v[176:179], v[38:41]
	v_mfma_f32_16x16x32_bf16 v[30:33], v[152:155], v[184:187], v[30:33]
	v_mfma_f32_16x16x32_bf16 v[22:25], v[160:163], v[184:187], v[22:25]
	v_mfma_f32_16x16x32_bf16 v[14:17], v[152:155], v[192:195], v[14:17]
	v_mfma_f32_16x16x32_bf16 v[6:9], v[160:163], v[192:195], v[6:9]
	v_mfma_f32_16x16x32_bf16 v[62:65], v[156:159], v[172:175], v[62:65]
	v_mfma_f32_16x16x32_bf16 v[54:57], v[164:167], v[172:175], v[54:57]
	v_mfma_f32_16x16x32_bf16 v[46:49], v[156:159], v[180:183], v[46:49]
	v_mfma_f32_16x16x32_bf16 v[38:41], v[164:167], v[180:183], v[38:41]
	v_mfma_f32_16x16x32_bf16 v[30:33], v[156:159], v[188:191], v[30:33]
	v_mfma_f32_16x16x32_bf16 v[22:25], v[164:167], v[188:191], v[22:25]
	v_mfma_f32_16x16x32_bf16 v[14:17], v[156:159], v[196:199], v[14:17]
	v_mfma_f32_16x16x32_bf16 v[6:9], v[164:167], v[196:199], v[6:9]
	s_setprio 0
	s_barrier
	s_add_u32 s48, s48, 0x80080
	s_addc_u32 s49, s49, 0
	s_add_i32 s50, s50, s55
	s_mov_b32 m0, s50
	s_nop 0
	global_load_lds_dwordx4 v0, s[48:49]
	s_add_i32 m0, s50, 0x2000
	s_nop 0
	global_load_lds_dwordx4 v130, s[48:49]
	s_waitcnt vmcnt(6)
	s_barrier
	s_setprio 1
	v_mfma_f32_16x16x32_bf16 v[58:61], v[208:211], v[168:171], v[58:61]
	v_mfma_f32_16x16x32_bf16 v[50:53], v[216:219], v[168:171], v[50:53]
	v_mfma_f32_16x16x32_bf16 v[42:45], v[208:211], v[176:179], v[42:45]
	v_mfma_f32_16x16x32_bf16 v[34:37], v[216:219], v[176:179], v[34:37]
	v_mfma_f32_16x16x32_bf16 v[26:29], v[208:211], v[184:187], v[26:29]
	v_mfma_f32_16x16x32_bf16 v[18:21], v[216:219], v[184:187], v[18:21]
	v_mfma_f32_16x16x32_bf16 v[10:13], v[208:211], v[192:195], v[10:13]
	v_mfma_f32_16x16x32_bf16 v[2:5], v[216:219], v[192:195], v[2:5]
	v_mfma_f32_16x16x32_bf16 v[58:61], v[212:215], v[172:175], v[58:61]
	v_mfma_f32_16x16x32_bf16 v[50:53], v[220:223], v[172:175], v[50:53]
	v_mfma_f32_16x16x32_bf16 v[42:45], v[212:215], v[180:183], v[42:45]
	v_mfma_f32_16x16x32_bf16 v[34:37], v[220:223], v[180:183], v[34:37]
	v_mfma_f32_16x16x32_bf16 v[26:29], v[212:215], v[188:191], v[26:29]
	v_mfma_f32_16x16x32_bf16 v[18:21], v[220:223], v[188:191], v[18:21]
	v_mfma_f32_16x16x32_bf16 v[10:13], v[212:215], v[196:199], v[10:13]
	v_mfma_f32_16x16x32_bf16 v[2:5], v[220:223], v[196:199], v[2:5]
	s_setprio 0
	s_add_i32 s73, s73, 2
	s_add_u32 s46, s46, 0x100
	s_addc_u32 s47, s47, 0
	s_add_u32 s71, s71, 0x100
	s_addc_u32 s72, s72, 0
	s_cmp_gt_u32 s73, 29
	s_barrier
	s_cbranch_scc0 .LBB0_90
	s_lshl_b32 s39, s68, 8
	s_add_i32 s39, s39, s60
	v_or_b32_e32 v154, s39, v145
	v_ashrrev_i32_e32 v155, 31, v154
	v_lshl_add_u64 v[154:155], v[154:155], 2, s[2:3]
	global_load_dword v140, v[154:155], off
	v_add_u32_e32 v154, s39, v147
	v_ashrrev_i32_e32 v155, 31, v154
	v_lshl_add_u64 v[154:155], v[154:155], 2, s[2:3]
	global_load_dword v142, v[154:155], off
	v_readlane_b32 s46, v251, 58
	v_readlane_b32 s47, v251, 59
	v_or_b32_e32 v153, s39, v141
	s_movk_i32 s39, 0x2c00
	s_and_b64 vcc, exec, s[36:37]
	s_mov_b32 s68, s40
	s_mov_b64 s[48:49], s[44:45]
	s_waitcnt vmcnt(0)
	v_fmamk_f32 v140, v140, 0x3a000000, v233
	v_rsq_f32_e32 v140, v140
	v_fmamk_f32 v142, v142, 0x3a000000, v233
	v_rsq_f32_e32 v154, v142
	v_and_or_b32 v142, v234, 64, v141
	v_lshlrev_b32_e32 v155, 2, v142
	ds_bpermute_b32 v156, v155, v140
	ds_bpermute_b32 v152, v155, v140 offset:64
	ds_bpermute_b32 v146, v155, v154
	ds_bpermute_b32 v144, v155, v154 offset:64
	ds_bpermute_b32 v150, v155, v140 offset:128
	s_waitcnt lgkmcnt(0)
	v_pk_mul_f32 v[126:127], v[126:127], v[156:157] op_sel_hi:[1,0]
	ds_bpermute_b32 v142, v155, v154 offset:128
	v_mul_f32_e32 v157, 0xbfb8aa3b, v126
	v_exp_f32_e32 v157, v157
	ds_bpermute_b32 v148, v155, v140 offset:192
	ds_bpermute_b32 v140, v155, v154 offset:192
	v_lshl_or_b32 v154, s65, 7, v149
	v_add_f32_e32 v157, 1.0, v157
	v_rcp_f32_e32 v158, v157
	v_pk_mul_f32 v[118:119], v[118:119], v[156:157] op_sel_hi:[1,0]
	v_mul_f32_e32 v157, 0xbfb8aa3b, v127
	v_exp_f32_e32 v157, v157
	v_ashrrev_i32_e32 v155, 31, v154
	v_pk_mul_f32 v[110:111], v[110:111], v[152:153] op_sel_hi:[1,0]
	v_pk_mul_f32 v[106:107], v[106:107], v[152:153] op_sel_hi:[1,0]
	v_add_f32_e32 v157, 1.0, v157
	v_rcp_f32_e32 v159, v157
	v_pk_mul_f32 v[120:121], v[120:121], v[156:157] op_sel_hi:[1,0]
	v_pk_mul_f32 v[122:123], v[122:123], v[156:157] op_sel_hi:[1,0]
	v_pk_mul_f32 v[114:115], v[114:115], v[156:157] op_sel_hi:[1,0]
	v_pk_mul_f32 v[126:127], v[126:127], v[158:159]
	v_pk_mul_f32 v[116:117], v[116:117], v[156:157] op_sel_hi:[1,0]
	v_pk_mul_f32 v[118:119], v[118:119], v[126:127]
	v_pk_mul_f32 v[126:127], v[128:129], v[156:157] op_sel_hi:[1,0]
	v_pk_mul_f32 v[108:109], v[108:109], v[152:153] op_sel_hi:[1,0]
	v_mul_f32_e32 v128, 0xbfb8aa3b, v126
	v_mul_f32_e32 v129, 0xbfb8aa3b, v127
	v_exp_f32_e32 v128, v128
	v_exp_f32_e32 v129, v129
	v_pk_mul_f32 v[102:103], v[102:103], v[152:153] op_sel_hi:[1,0]
	v_pk_mul_f32 v[98:99], v[98:99], v[152:153] op_sel_hi:[1,0]
	v_add_f32_e32 v128, 1.0, v128
	v_add_f32_e32 v129, 1.0, v129
	v_rcp_f32_e32 v128, v128
	v_rcp_f32_e32 v129, v129
	v_pk_mul_f32 v[100:101], v[100:101], v[152:153] op_sel_hi:[1,0]
	v_pk_mul_f32 v[94:95], v[94:95], v[150:151] op_sel_hi:[1,0]
	v_pk_mul_f32 v[90:91], v[90:91], v[150:151] op_sel_hi:[1,0]
	v_pk_mul_f32 v[126:127], v[126:127], v[128:129]
	v_pk_mul_f32 v[92:93], v[92:93], v[150:151] op_sel_hi:[1,0]
	v_pk_mul_f32 v[120:121], v[120:121], v[126:127]
	v_mul_f32_e32 v126, 0xbfb8aa3b, v122
	v_mul_f32_e32 v127, 0xbfb8aa3b, v123
	v_exp_f32_e32 v126, v126
	v_exp_f32_e32 v127, v127
	v_pk_mul_f32 v[86:87], v[86:87], v[150:151] op_sel_hi:[1,0]
	v_pk_mul_f32 v[82:83], v[82:83], v[150:151] op_sel_hi:[1,0]
	v_add_f32_e32 v126, 1.0, v126
	v_add_f32_e32 v127, 1.0, v127
	v_rcp_f32_e32 v126, v126
	v_rcp_f32_e32 v127, v127
	v_pk_mul_f32 v[84:85], v[84:85], v[150:151] op_sel_hi:[1,0]
	s_waitcnt lgkmcnt(1)
; __device__ __forceinline__ unsigned pk2(float lo, float hi) { f32x2 v = {lo, hi}; bf16x2_t b = __builtin_convertvector(v, bf16x2_t); return __builtin_bit_cast(unsigned, b); }
;     __device__ __forceinline__ void operator()(const AccT& acc, const Unit& u, int wr, int wc, int fr, int fq) const {
;     ...
;         for (int ai = 0; ai < 2; ++ai)
; #pragma unroll
;             for (int m = 0; m < 4; ++m) {
;                 const int row = row0 + ai * HALF + m * 16;
;                 const float rs = rsv[ai * 4 + m];
;                 float v[8];
; #pragma unroll
;                 for (int n = 0; n < 2; ++n)
; #pragma unroll
;                     for (int j = 0; j < 4; ++j) {
;                         const float g = acc[ai][0][m][n][j] * rs, up = acc[ai][1][m][n][j] * rs;
;                         const float sg = __builtin_amdgcn_rcpf(1.0f + __builtin_amdgcn_exp2f(-g * LOG2E));
;                         v[4 * n + j] = g * sg * up;
;                     }
;                 u32x4 w; w.x = pk2(v[0], v[1]); w.y = pk2(v[2], v[3]); w.z = pk2(v[4], v[5]); w.w = pk2(v[6], v[7]);
;                 *(u32x4*)(mid + (size_t)row * FF + col0) = w;
	v_pk_mul_f32 v[78:79], v[78:79], v[148:149] op_sel_hi:[1,0]
	v_pk_mul_f32 v[74:75], v[74:75], v[148:149] op_sel_hi:[1,0]
	v_pk_mul_f32 v[122:123], v[122:123], v[126:127]
	v_pk_mul_f32 v[76:77], v[76:77], v[148:149] op_sel_hi:[1,0]
	v_pk_mul_f32 v[122:123], v[114:115], v[122:123]
	v_pk_mul_f32 v[114:115], v[124:125], v[156:157] op_sel_hi:[1,0]
	v_pk_mul_f32 v[70:71], v[70:71], v[148:149] op_sel_hi:[1,0]
	v_mul_f32_e32 v124, 0xbfb8aa3b, v114
	v_mul_f32_e32 v125, 0xbfb8aa3b, v115
	v_exp_f32_e32 v124, v124
	v_exp_f32_e32 v125, v125
	v_pk_mul_f32 v[66:67], v[66:67], v[148:149] op_sel_hi:[1,0]
	v_pk_mul_f32 v[68:69], v[68:69], v[148:149] op_sel_hi:[1,0]
	v_add_f32_e32 v124, 1.0, v124
	v_add_f32_e32 v125, 1.0, v125
	v_rcp_f32_e32 v124, v124
	v_rcp_f32_e32 v125, v125
	v_pk_mul_f32 v[62:63], v[62:63], v[146:147] op_sel_hi:[1,0]
	v_pk_mul_f32 v[58:59], v[58:59], v[146:147] op_sel_hi:[1,0]
	v_pk_mul_f32 v[60:61], v[60:61], v[146:147] op_sel_hi:[1,0]
	v_pk_mul_f32 v[114:115], v[114:115], v[124:125]
	v_pk_mul_f32 v[54:55], v[54:55], v[146:147] op_sel_hi:[1,0]
	v_pk_mul_f32 v[124:125], v[116:117], v[114:115]
	v_cvt_pk_bf16_f32 v114, v118, v119
	v_mov_b64_e32 v[118:119], s[46:47]
	v_cvt_pk_bf16_f32 v115, v120, v121
	v_cvt_pk_bf16_f32 v116, v122, v123
	v_mad_i64_i32 v[122:123], s[46:47], v153, s39, v[118:119]
	v_lshlrev_b64 v[120:121], 1, v[154:155]
	v_cvt_pk_bf16_f32 v117, v124, v125
	v_lshl_add_u64 v[122:123], v[122:123], 0, v[120:121]
	global_store_dwordx4 v[122:123], v[114:117], off
	v_pk_mul_f32 v[50:51], v[50:51], v[146:147] op_sel_hi:[1,0]
	v_pk_mul_f32 v[52:53], v[52:53], v[146:147] op_sel_hi:[1,0]
	v_mul_f32_e32 v114, 0xbfb8aa3b, v110
	v_mul_f32_e32 v115, 0xbfb8aa3b, v111
	v_exp_f32_e32 v114, v114
	v_exp_f32_e32 v115, v115
	v_pk_mul_f32 v[46:47], v[46:47], v[144:145] op_sel_hi:[1,0]
	v_pk_mul_f32 v[42:43], v[42:43], v[144:145] op_sel_hi:[1,0]
	v_add_f32_e32 v114, 1.0, v114
	v_add_f32_e32 v115, 1.0, v115
	v_rcp_f32_e32 v114, v114
	v_rcp_f32_e32 v115, v115
	v_pk_mul_f32 v[44:45], v[44:45], v[144:145] op_sel_hi:[1,0]
	v_pk_mul_f32 v[38:39], v[38:39], v[144:145] op_sel_hi:[1,0]
	v_pk_mul_f32 v[34:35], v[34:35], v[144:145] op_sel_hi:[1,0]
	v_pk_mul_f32 v[110:111], v[110:111], v[114:115]
	v_pk_mul_f32 v[36:37], v[36:37], v[144:145] op_sel_hi:[1,0]
	v_pk_mul_f32 v[106:107], v[106:107], v[110:111]
	v_pk_mul_f32 v[110:111], v[112:113], v[152:153] op_sel_hi:[1,0]
	v_pk_mul_f32 v[30:31], v[30:31], v[142:143] op_sel_hi:[1,0]
	v_mul_f32_e32 v112, 0xbfb8aa3b, v110
	v_mul_f32_e32 v113, 0xbfb8aa3b, v111
	v_exp_f32_e32 v112, v112
	v_exp_f32_e32 v113, v113
	v_pk_mul_f32 v[26:27], v[26:27], v[142:143] op_sel_hi:[1,0]
	v_pk_mul_f32 v[28:29], v[28:29], v[142:143] op_sel_hi:[1,0]
	v_add_f32_e32 v112, 1.0, v112
	v_add_f32_e32 v113, 1.0, v113
	v_rcp_f32_e32 v112, v112
	v_rcp_f32_e32 v113, v113
	v_pk_mul_f32 v[22:23], v[22:23], v[142:143] op_sel_hi:[1,0]
	v_pk_mul_f32 v[18:19], v[18:19], v[142:143] op_sel_hi:[1,0]
	v_pk_mul_f32 v[20:21], v[20:21], v[142:143] op_sel_hi:[1,0]
	v_pk_mul_f32 v[110:111], v[110:111], v[112:113]
	s_waitcnt lgkmcnt(0)
	v_pk_mul_f32 v[14:15], v[14:15], v[140:141] op_sel_hi:[1,0]
	v_pk_mul_f32 v[108:109], v[108:109], v[110:111]
	v_mul_f32_e32 v110, 0xbfb8aa3b, v102
	v_mul_f32_e32 v111, 0xbfb8aa3b, v103
	v_exp_f32_e32 v110, v110
	v_exp_f32_e32 v111, v111
	v_pk_mul_f32 v[10:11], v[10:11], v[140:141] op_sel_hi:[1,0]
	v_pk_mul_f32 v[12:13], v[12:13], v[140:141] op_sel_hi:[1,0]
	v_add_f32_e32 v110, 1.0, v110
	v_add_f32_e32 v111, 1.0, v111
	v_rcp_f32_e32 v110, v110
	v_rcp_f32_e32 v111, v111
	v_pk_mul_f32 v[6:7], v[6:7], v[140:141] op_sel_hi:[1,0]
	v_pk_mul_f32 v[2:3], v[2:3], v[140:141] op_sel_hi:[1,0]
	v_pk_mul_f32 v[4:5], v[4:5], v[140:141] op_sel_hi:[1,0]
	v_pk_mul_f32 v[102:103], v[102:103], v[110:111]
	v_or_b32_e32 v110, 16, v153
	v_pk_mul_f32 v[102:103], v[98:99], v[102:103]
	v_pk_mul_f32 v[98:99], v[104:105], v[152:153] op_sel_hi:[1,0]
	s_mov_b32 s65, s38
	v_mul_f32_e32 v104, 0xbfb8aa3b, v98
	v_mul_f32_e32 v105, 0xbfb8aa3b, v99
	v_exp_f32_e32 v104, v104
	v_exp_f32_e32 v105, v105
	v_add_f32_e32 v104, 1.0, v104
	v_add_f32_e32 v105, 1.0, v105
	v_rcp_f32_e32 v104, v104
	v_rcp_f32_e32 v105, v105
	s_nop 0
	v_pk_mul_f32 v[98:99], v[98:99], v[104:105]
	s_nop 0
	v_pk_mul_f32 v[104:105], v[100:101], v[98:99]
	v_cvt_pk_bf16_f32 v100, v102, v103
	v_mad_i64_i32 v[102:103], s[46:47], v110, s39, v[118:119]
	v_cvt_pk_bf16_f32 v98, v106, v107
	v_cvt_pk_bf16_f32 v99, v108, v109
	v_cvt_pk_bf16_f32 v101, v104, v105
	v_lshl_add_u64 v[102:103], v[102:103], 0, v[120:121]
	global_store_dwordx4 v[102:103], v[98:101], off
	s_nop 1
	v_mul_f32_e32 v98, 0xbfb8aa3b, v94
	v_mul_f32_e32 v99, 0xbfb8aa3b, v95
	v_exp_f32_e32 v98, v98
	v_exp_f32_e32 v99, v99
	v_add_f32_e32 v98, 1.0, v98
	v_add_f32_e32 v99, 1.0, v99
	v_rcp_f32_e32 v98, v98
	v_rcp_f32_e32 v99, v99
	s_nop 0
	v_pk_mul_f32 v[94:95], v[94:95], v[98:99]
	s_nop 0
	v_pk_mul_f32 v[90:91], v[90:91], v[94:95]
	v_pk_mul_f32 v[94:95], v[96:97], v[150:151] op_sel_hi:[1,0]
	s_nop 0
	v_mul_f32_e32 v96, 0xbfb8aa3b, v94
	v_mul_f32_e32 v97, 0xbfb8aa3b, v95
	v_exp_f32_e32 v96, v96
	v_exp_f32_e32 v97, v97
	v_add_f32_e32 v96, 1.0, v96
	v_add_f32_e32 v97, 1.0, v97
	v_rcp_f32_e32 v96, v96
	v_rcp_f32_e32 v97, v97
	s_nop 0
	v_pk_mul_f32 v[94:95], v[94:95], v[96:97]
	s_nop 0
	v_pk_mul_f32 v[92:93], v[92:93], v[94:95]
	v_mul_f32_e32 v94, 0xbfb8aa3b, v86
	v_mul_f32_e32 v95, 0xbfb8aa3b, v87
	v_exp_f32_e32 v94, v94
	v_exp_f32_e32 v95, v95
	v_add_f32_e32 v94, 1.0, v94
	v_add_f32_e32 v95, 1.0, v95
	v_rcp_f32_e32 v94, v94
	v_rcp_f32_e32 v95, v95
	s_nop 0
	v_pk_mul_f32 v[86:87], v[86:87], v[94:95]
	s_nop 0
	v_pk_mul_f32 v[86:87], v[82:83], v[86:87]
; __device__ __forceinline__ unsigned pk2(float lo, float hi) { f32x2 v = {lo, hi}; bf16x2_t b = __builtin_convertvector(v, bf16x2_t); return __builtin_bit_cast(unsigned, b); }
;     __device__ __forceinline__ void operator()(const AccT& acc, const Unit& u, int wr, int wc, int fr, int fq) const {
;     ...
;         for (int ai = 0; ai < 2; ++ai)
; #pragma unroll
;             for (int m = 0; m < 4; ++m) {
;                 const int row = row0 + ai * HALF + m * 16;
;                 const float rs = rsv[ai * 4 + m];
;                 float v[8];
; #pragma unroll
;                 for (int n = 0; n < 2; ++n)
; #pragma unroll
;                     for (int j = 0; j < 4; ++j) {
;                         const float g = acc[ai][0][m][n][j] * rs, up = acc[ai][1][m][n][j] * rs;
;                         const float sg = __builtin_amdgcn_rcpf(1.0f + __builtin_amdgcn_exp2f(-g * LOG2E));
;                         v[4 * n + j] = g * sg * up;
;                     }
;                 u32x4 w; w.x = pk2(v[0], v[1]); w.y = pk2(v[2], v[3]); w.z = pk2(v[4], v[5]); w.w = pk2(v[6], v[7]);
;                 *(u32x4*)(mid + (size_t)row * FF + col0) = w;
	v_pk_mul_f32 v[82:83], v[88:89], v[150:151] op_sel_hi:[1,0]
	v_or_b32_e32 v94, 32, v153
	v_mul_f32_e32 v88, 0xbfb8aa3b, v82
	v_mul_f32_e32 v89, 0xbfb8aa3b, v83
	v_exp_f32_e32 v88, v88
	v_exp_f32_e32 v89, v89
	v_add_f32_e32 v88, 1.0, v88
	v_add_f32_e32 v89, 1.0, v89
	v_rcp_f32_e32 v88, v88
	v_rcp_f32_e32 v89, v89
	s_nop 0
	v_pk_mul_f32 v[82:83], v[82:83], v[88:89]
	s_nop 0
	v_pk_mul_f32 v[88:89], v[84:85], v[82:83]
	v_cvt_pk_bf16_f32 v84, v86, v87
	v_mad_i64_i32 v[86:87], s[46:47], v94, s39, v[118:119]
	v_cvt_pk_bf16_f32 v82, v90, v91
	v_cvt_pk_bf16_f32 v83, v92, v93
	v_cvt_pk_bf16_f32 v85, v88, v89
	v_lshl_add_u64 v[86:87], v[86:87], 0, v[120:121]
	global_store_dwordx4 v[86:87], v[82:85], off
	s_nop 1
	v_mul_f32_e32 v82, 0xbfb8aa3b, v78
	v_mul_f32_e32 v83, 0xbfb8aa3b, v79
	v_exp_f32_e32 v82, v82
	v_exp_f32_e32 v83, v83
	v_add_f32_e32 v82, 1.0, v82
	v_add_f32_e32 v83, 1.0, v83
	v_rcp_f32_e32 v82, v82
	v_rcp_f32_e32 v83, v83
	s_nop 0
	v_pk_mul_f32 v[78:79], v[78:79], v[82:83]
	s_nop 0
	v_pk_mul_f32 v[74:75], v[74:75], v[78:79]
	v_pk_mul_f32 v[78:79], v[80:81], v[148:149] op_sel_hi:[1,0]
	s_nop 0
	v_mul_f32_e32 v80, 0xbfb8aa3b, v78
	v_mul_f32_e32 v81, 0xbfb8aa3b, v79
	v_exp_f32_e32 v80, v80
	v_exp_f32_e32 v81, v81
	v_add_f32_e32 v80, 1.0, v80
	v_add_f32_e32 v81, 1.0, v81
	v_rcp_f32_e32 v80, v80
	v_rcp_f32_e32 v81, v81
	s_nop 0
	v_pk_mul_f32 v[78:79], v[78:79], v[80:81]
	s_nop 0
	v_pk_mul_f32 v[76:77], v[76:77], v[78:79]
	v_mul_f32_e32 v78, 0xbfb8aa3b, v70
	v_mul_f32_e32 v79, 0xbfb8aa3b, v71
	v_exp_f32_e32 v78, v78
	v_exp_f32_e32 v79, v79
	v_add_f32_e32 v78, 1.0, v78
	v_add_f32_e32 v79, 1.0, v79
	v_rcp_f32_e32 v78, v78
	v_rcp_f32_e32 v79, v79
	s_nop 0
	v_pk_mul_f32 v[70:71], v[70:71], v[78:79]
	s_nop 0
	v_pk_mul_f32 v[70:71], v[66:67], v[70:71]
	v_pk_mul_f32 v[66:67], v[72:73], v[148:149] op_sel_hi:[1,0]
	v_or_b32_e32 v78, 48, v153
	v_mul_f32_e32 v72, 0xbfb8aa3b, v66
	v_mul_f32_e32 v73, 0xbfb8aa3b, v67
	v_exp_f32_e32 v72, v72
	v_exp_f32_e32 v73, v73
	v_add_f32_e32 v72, 1.0, v72
	v_add_f32_e32 v73, 1.0, v73
	v_rcp_f32_e32 v72, v72
	v_rcp_f32_e32 v73, v73
	s_nop 0
	v_pk_mul_f32 v[66:67], v[66:67], v[72:73]
	s_nop 0
	v_pk_mul_f32 v[72:73], v[68:69], v[66:67]
	v_cvt_pk_bf16_f32 v68, v70, v71
	v_mad_i64_i32 v[70:71], s[46:47], v78, s39, v[118:119]
	v_cvt_pk_bf16_f32 v66, v74, v75
	v_cvt_pk_bf16_f32 v67, v76, v77
	v_cvt_pk_bf16_f32 v69, v72, v73
	v_lshl_add_u64 v[70:71], v[70:71], 0, v[120:121]
	global_store_dwordx4 v[70:71], v[66:69], off
	s_nop 1
	v_mul_f32_e32 v66, 0xbfb8aa3b, v62
	v_mul_f32_e32 v67, 0xbfb8aa3b, v63
	v_exp_f32_e32 v66, v66
	v_exp_f32_e32 v67, v67
	v_add_u32_e32 v68, 0x80, v153
	v_add_f32_e32 v66, 1.0, v66
	v_add_f32_e32 v67, 1.0, v67
	v_rcp_f32_e32 v66, v66
	v_rcp_f32_e32 v67, v67
	s_nop 0
	v_pk_mul_f32 v[62:63], v[62:63], v[66:67]
	s_nop 0
	v_pk_mul_f32 v[58:59], v[58:59], v[62:63]
	v_pk_mul_f32 v[62:63], v[64:65], v[146:147] op_sel_hi:[1,0]
	s_nop 0
	v_mul_f32_e32 v64, 0xbfb8aa3b, v62
	v_mul_f32_e32 v65, 0xbfb8aa3b, v63
	v_exp_f32_e32 v64, v64
	v_exp_f32_e32 v65, v65
	v_add_f32_e32 v64, 1.0, v64
	v_add_f32_e32 v65, 1.0, v65
	v_rcp_f32_e32 v64, v64
	v_rcp_f32_e32 v65, v65
	s_nop 0
	v_pk_mul_f32 v[62:63], v[62:63], v[64:65]
	s_nop 0
	v_pk_mul_f32 v[60:61], v[60:61], v[62:63]
	v_mul_f32_e32 v62, 0xbfb8aa3b, v54
	v_mul_f32_e32 v63, 0xbfb8aa3b, v55
	v_exp_f32_e32 v62, v62
	v_exp_f32_e32 v63, v63
	v_add_f32_e32 v62, 1.0, v62
	v_add_f32_e32 v63, 1.0, v63
	v_rcp_f32_e32 v62, v62
	v_rcp_f32_e32 v63, v63
	s_nop 0
	v_pk_mul_f32 v[54:55], v[54:55], v[62:63]
	s_nop 0
	v_pk_mul_f32 v[54:55], v[50:51], v[54:55]
	v_pk_mul_f32 v[50:51], v[56:57], v[146:147] op_sel_hi:[1,0]
	s_nop 0
	v_mul_f32_e32 v56, 0xbfb8aa3b, v50
	v_mul_f32_e32 v57, 0xbfb8aa3b, v51
	v_exp_f32_e32 v56, v56
	v_exp_f32_e32 v57, v57
	v_add_f32_e32 v56, 1.0, v56
	v_add_f32_e32 v57, 1.0, v57
	v_rcp_f32_e32 v56, v56
	v_rcp_f32_e32 v57, v57
	s_nop 0
	v_pk_mul_f32 v[50:51], v[50:51], v[56:57]
	s_nop 0
	v_pk_mul_f32 v[56:57], v[52:53], v[50:51]
	v_cvt_pk_bf16_f32 v52, v54, v55
	v_mad_i64_i32 v[54:55], s[46:47], v68, s39, v[118:119]
	v_cvt_pk_bf16_f32 v50, v58, v59
	v_cvt_pk_bf16_f32 v51, v60, v61
	v_cvt_pk_bf16_f32 v53, v56, v57
	v_lshl_add_u64 v[54:55], v[54:55], 0, v[120:121]
	global_store_dwordx4 v[54:55], v[50:53], off
	s_nop 1
	v_mul_f32_e32 v50, 0xbfb8aa3b, v46
	v_mul_f32_e32 v51, 0xbfb8aa3b, v47
	v_exp_f32_e32 v50, v50
	v_exp_f32_e32 v51, v51
	v_add_f32_e32 v50, 1.0, v50
	v_add_f32_e32 v51, 1.0, v51
	v_rcp_f32_e32 v50, v50
	v_rcp_f32_e32 v51, v51
	s_nop 0
	v_pk_mul_f32 v[46:47], v[46:47], v[50:51]
	s_nop 0
	v_pk_mul_f32 v[42:43], v[42:43], v[46:47]
	v_pk_mul_f32 v[46:47], v[48:49], v[144:145] op_sel_hi:[1,0]
	s_nop 0
	v_mul_f32_e32 v48, 0xbfb8aa3b, v46
	v_mul_f32_e32 v49, 0xbfb8aa3b, v47
	v_exp_f32_e32 v48, v48
	v_exp_f32_e32 v49, v49
	v_add_f32_e32 v48, 1.0, v48
; __device__ __forceinline__ unsigned pk2(float lo, float hi) { f32x2 v = {lo, hi}; bf16x2_t b = __builtin_convertvector(v, bf16x2_t); return __builtin_bit_cast(unsigned, b); }
; #define PG8_WAIT_V(n) asm volatile("s_waitcnt vmcnt(" #n ")" ::: "memory")
; #define PG8_BAR __builtin_amdgcn_s_barrier()
;     __device__ __forceinline__ void operator()(const AccT& acc, const Unit& u, int wr, int wc, int fr, int fq) const {
;     ...
;         for (int ai = 0; ai < 2; ++ai)
; #pragma unroll
;             for (int m = 0; m < 4; ++m) {
;                 const int row = row0 + ai * HALF + m * 16;
;                 const float rs = rsv[ai * 4 + m];
;                 float v[8];
; #pragma unroll
;                 for (int n = 0; n < 2; ++n)
; #pragma unroll
;                     for (int j = 0; j < 4; ++j) {
;                         const float g = acc[ai][0][m][n][j] * rs, up = acc[ai][1][m][n][j] * rs;
;                         const float sg = __builtin_amdgcn_rcpf(1.0f + __builtin_amdgcn_exp2f(-g * LOG2E));
;                         v[4 * n + j] = g * sg * up;
;                     }
;                 u32x4 w; w.x = pk2(v[0], v[1]); w.y = pk2(v[2], v[3]); w.z = pk2(v[4], v[5]); w.w = pk2(v[6], v[7]);
;                 *(u32x4*)(mid + (size_t)row * FF + col0) = w;
;             }
; template <class Epi>
; __device__ __forceinline__ void gemm_phase(LAS unsigned char* lds, const Gemm g, const StaticOrder& S, const Epi& E) {
;     ...
;         E(acc, cur, wr, wc, fr, fq);
;         if (!has_next) break;
; #pragma unroll
;         for (int a = 0; a < 2; ++a)
; #pragma unroll
;             for (int b = 0; b < 2; ++b)
; #pragma unroll
;                 for (int m = 0; m < 4; ++m)
; #pragma unroll
;                     for (int n = 0; n < 2; ++n) acc[a][b][m][n] = (f32x4){0.f, 0.f, 0.f, 0.f};
;         cur = nxt; cA = nA; cB = nB; ++ui;
;     }
;     PG8_WAIT_V(0);
;     if (wr == 0) PG8_BAR;
	v_add_f32_e32 v49, 1.0, v49
	v_rcp_f32_e32 v48, v48
	v_rcp_f32_e32 v49, v49
	s_nop 0
	v_pk_mul_f32 v[46:47], v[46:47], v[48:49]
	s_nop 0
	v_pk_mul_f32 v[44:45], v[44:45], v[46:47]
	v_mul_f32_e32 v46, 0xbfb8aa3b, v38
	v_mul_f32_e32 v47, 0xbfb8aa3b, v39
	v_exp_f32_e32 v46, v46
	v_exp_f32_e32 v47, v47
	v_add_f32_e32 v46, 1.0, v46
	v_add_f32_e32 v47, 1.0, v47
	v_rcp_f32_e32 v46, v46
	v_rcp_f32_e32 v47, v47
	s_nop 0
	v_pk_mul_f32 v[38:39], v[38:39], v[46:47]
	s_nop 0
	v_pk_mul_f32 v[38:39], v[34:35], v[38:39]
	v_pk_mul_f32 v[34:35], v[40:41], v[144:145] op_sel_hi:[1,0]
	v_add_u32_e32 v46, 0x90, v153
	v_mul_f32_e32 v40, 0xbfb8aa3b, v34
	v_mul_f32_e32 v41, 0xbfb8aa3b, v35
	v_exp_f32_e32 v40, v40
	v_exp_f32_e32 v41, v41
	v_add_f32_e32 v40, 1.0, v40
	v_add_f32_e32 v41, 1.0, v41
	v_rcp_f32_e32 v40, v40
	v_rcp_f32_e32 v41, v41
	s_nop 0
	v_pk_mul_f32 v[34:35], v[34:35], v[40:41]
	s_nop 0
	v_pk_mul_f32 v[40:41], v[36:37], v[34:35]
	v_cvt_pk_bf16_f32 v36, v38, v39
	v_mad_i64_i32 v[38:39], s[46:47], v46, s39, v[118:119]
	v_cvt_pk_bf16_f32 v34, v42, v43
	v_cvt_pk_bf16_f32 v35, v44, v45
	v_cvt_pk_bf16_f32 v37, v40, v41
	v_lshl_add_u64 v[38:39], v[38:39], 0, v[120:121]
	global_store_dwordx4 v[38:39], v[34:37], off
	s_nop 1
	v_mul_f32_e32 v34, 0xbfb8aa3b, v30
	v_mul_f32_e32 v35, 0xbfb8aa3b, v31
	v_exp_f32_e32 v34, v34
	v_exp_f32_e32 v35, v35
	v_add_f32_e32 v34, 1.0, v34
	v_add_f32_e32 v35, 1.0, v35
	v_rcp_f32_e32 v34, v34
	v_rcp_f32_e32 v35, v35
	s_nop 0
	v_pk_mul_f32 v[30:31], v[30:31], v[34:35]
	s_nop 0
	v_pk_mul_f32 v[26:27], v[26:27], v[30:31]
	v_pk_mul_f32 v[30:31], v[32:33], v[142:143] op_sel_hi:[1,0]
	s_nop 0
	v_mul_f32_e32 v32, 0xbfb8aa3b, v30
	v_mul_f32_e32 v33, 0xbfb8aa3b, v31
	v_exp_f32_e32 v32, v32
	v_exp_f32_e32 v33, v33
	v_add_f32_e32 v32, 1.0, v32
	v_add_f32_e32 v33, 1.0, v33
	v_rcp_f32_e32 v32, v32
	v_rcp_f32_e32 v33, v33
	s_nop 0
	v_pk_mul_f32 v[30:31], v[30:31], v[32:33]
	s_nop 0
	v_pk_mul_f32 v[28:29], v[28:29], v[30:31]
	v_mul_f32_e32 v30, 0xbfb8aa3b, v22
	v_mul_f32_e32 v31, 0xbfb8aa3b, v23
	v_exp_f32_e32 v30, v30
	v_exp_f32_e32 v31, v31
	v_add_f32_e32 v30, 1.0, v30
	v_add_f32_e32 v31, 1.0, v31
	v_rcp_f32_e32 v30, v30
	v_rcp_f32_e32 v31, v31
	s_nop 0
	v_pk_mul_f32 v[22:23], v[22:23], v[30:31]
	s_nop 0
	v_pk_mul_f32 v[22:23], v[18:19], v[22:23]
	v_pk_mul_f32 v[18:19], v[24:25], v[142:143] op_sel_hi:[1,0]
	v_add_u32_e32 v30, 0xa0, v153
	v_mul_f32_e32 v24, 0xbfb8aa3b, v18
	v_mul_f32_e32 v25, 0xbfb8aa3b, v19
	v_exp_f32_e32 v24, v24
	v_exp_f32_e32 v25, v25
	v_add_f32_e32 v24, 1.0, v24
	v_add_f32_e32 v25, 1.0, v25
	v_rcp_f32_e32 v24, v24
	v_rcp_f32_e32 v25, v25
	s_nop 0
	v_pk_mul_f32 v[18:19], v[18:19], v[24:25]
	s_nop 0
	v_pk_mul_f32 v[24:25], v[20:21], v[18:19]
	v_cvt_pk_bf16_f32 v20, v22, v23
	v_mad_i64_i32 v[22:23], s[46:47], v30, s39, v[118:119]
	v_cvt_pk_bf16_f32 v18, v26, v27
	v_cvt_pk_bf16_f32 v19, v28, v29
	v_cvt_pk_bf16_f32 v21, v24, v25
	v_lshl_add_u64 v[22:23], v[22:23], 0, v[120:121]
	global_store_dwordx4 v[22:23], v[18:21], off
	s_nop 1
	v_mul_f32_e32 v18, 0xbfb8aa3b, v14
	v_mul_f32_e32 v19, 0xbfb8aa3b, v15
	v_exp_f32_e32 v18, v18
	v_exp_f32_e32 v19, v19
	v_add_f32_e32 v18, 1.0, v18
	v_add_f32_e32 v19, 1.0, v19
	v_rcp_f32_e32 v18, v18
	v_rcp_f32_e32 v19, v19
	s_nop 0
	v_pk_mul_f32 v[14:15], v[14:15], v[18:19]
	s_nop 0
	v_pk_mul_f32 v[10:11], v[10:11], v[14:15]
	v_pk_mul_f32 v[14:15], v[16:17], v[140:141] op_sel_hi:[1,0]
	s_nop 0
	v_mul_f32_e32 v16, 0xbfb8aa3b, v14
	v_mul_f32_e32 v17, 0xbfb8aa3b, v15
	v_exp_f32_e32 v16, v16
	v_exp_f32_e32 v17, v17
	v_add_f32_e32 v16, 1.0, v16
	v_add_f32_e32 v17, 1.0, v17
	v_rcp_f32_e32 v16, v16
	v_rcp_f32_e32 v17, v17
	s_nop 0
	v_pk_mul_f32 v[14:15], v[14:15], v[16:17]
	s_nop 0
	v_pk_mul_f32 v[12:13], v[12:13], v[14:15]
	v_mul_f32_e32 v14, 0xbfb8aa3b, v6
	v_mul_f32_e32 v15, 0xbfb8aa3b, v7
	v_exp_f32_e32 v14, v14
	v_exp_f32_e32 v15, v15
	v_add_f32_e32 v14, 1.0, v14
	v_add_f32_e32 v15, 1.0, v15
	v_rcp_f32_e32 v14, v14
	v_rcp_f32_e32 v15, v15
	s_nop 0
	v_pk_mul_f32 v[6:7], v[6:7], v[14:15]
	s_nop 0
	v_pk_mul_f32 v[6:7], v[2:3], v[6:7]
	v_pk_mul_f32 v[2:3], v[8:9], v[140:141] op_sel_hi:[1,0]
	v_add_u32_e32 v14, 0xb0, v153
	v_mul_f32_e32 v8, 0xbfb8aa3b, v2
	v_mul_f32_e32 v9, 0xbfb8aa3b, v3
	v_exp_f32_e32 v8, v8
	v_exp_f32_e32 v9, v9
	v_add_f32_e32 v8, 1.0, v8
	v_add_f32_e32 v9, 1.0, v9
	v_rcp_f32_e32 v8, v8
	v_rcp_f32_e32 v9, v9
	s_nop 0
	v_pk_mul_f32 v[2:3], v[2:3], v[8:9]
	s_nop 0
	v_pk_mul_f32 v[8:9], v[4:5], v[2:3]
	v_cvt_pk_bf16_f32 v4, v6, v7
	v_mad_i64_i32 v[6:7], s[46:47], v14, s39, v[118:119]
	v_cvt_pk_bf16_f32 v2, v10, v11
	v_cvt_pk_bf16_f32 v3, v12, v13
	v_cvt_pk_bf16_f32 v5, v8, v9
	v_lshl_add_u64 v[6:7], v[6:7], 0, v[120:121]
	s_mov_b64 s[46:47], s[42:43]
	global_store_dwordx4 v[6:7], v[2:5], off
	s_cbranch_vccz .LBB0_87
	s_waitcnt vmcnt(0)
	s_cmpk_gt_u32 s52, 0xff
	s_cbranch_scc1 .LBB0_94
	s_barrier

; #define PG8_STAGE(bufoff, gbase, voff) do { _Pragma("unroll") for (int _i = 0; _i < 2; ++_i) \
;         __builtin_amdgcn_global_load_lds((const unsigned*)((const char*)(gbase) + (voff)[_i]), (LAS unsigned*)(lds + (bufoff) + ldsw + _i * 8192), 16, 0, 0); } while (0)
; #define PG8_LDA(dst, b, h) do { _Pragma("unroll") for (int m = 0; m < 4; ++m) _Pragma("unroll") for (int k = 0; k < 2; ++k) dst[m][k] = *(const LAS bf16x8*)(lds + PG8_SA(b, h) + aoff + m * 2048 + k * 1024); } while (0)
; #define PG8_LDB(dst, b, h) do { _Pragma("unroll") for (int n = 0; n < 2; ++n) _Pragma("unroll") for (int k = 0; k < 2; ++k) dst[n][k] = *(const LAS bf16x8*)(lds + PG8_SB(b, h) + boff + n * 2048 + k * 1024); } while (0)
; #define PG8_MMA(ai, bj, At, Bt) do { __builtin_amdgcn_s_setprio(1); _Pragma("unroll") for (int m = 0; m < 4; ++m) _Pragma("unroll") for (int n = 0; n < 2; ++n) _Pragma("unroll") for (int k = 0; k < 2; ++k) \
;         acc[ai][bj][m][n] = __builtin_amdgcn_mfma_f32_16x16x32_bf16(Bt[n][k], At[m][k], acc[ai][bj][m][n], 0, 0, 0); __builtin_amdgcn_s_setprio(0); } while (0)
; #define PG8_WAIT_L(n) asm volatile("s_waitcnt lgkmcnt(" #n ")" ::: "memory")
; #define PG8_BAR __builtin_amdgcn_s_barrier()
; #define PG8_SCHED __builtin_amdgcn_sched_barrier(0)
; template <class Epi>
; __device__ __forceinline__ void gemm_phase(LAS unsigned char* lds, const Gemm g, const StaticOrder& S, const Epi& E) {
;     ...
;         for (int t = 0; t < nt; t += 2) {
;             const bool last = (t == nt - 2);
;             const char* a1 = cA + (size_t)(t + 1) * kstep;
;             const char* a2 = last ? nA : cA + (size_t)(t + 2) * kstep; const char* b2 = last ? nB : cB + (size_t)(t + 2) * kstep;
;             const char* a3 = a2 + kstep; const char* b3 = b2 + kstep;
;             PG8_LDB(B0, 0, 0); PG8_SCHED; PG8_LDA(At, 0, 0); PG8_STAGE(PG8_SA(1, 1), a1 + hstep, voffA);
;             PG8_WAIT_L(8); PG8_BAR; PG8_WAIT_L(0); PG8_MMA(0, 0, At, B0); PG8_BAR; PG8_SCHED;
;             PG8_LDB(B1, 0, 1); PG8_STAGE(PG8_SB(0, 0), b2, voffB);
;             PG8_BAR; PG8_WAIT_L(0); PG8_MMA(0, 1, At, B1); PG8_BAR;
;             PG8_LDA(At, 0, 1); PG8_STAGE(PG8_SA(0, 0), a2, voffA);
;             PG8_BAR; PG8_WAIT_L(0); PG8_MMA(1, 0, At, B0); PG8_BAR; PG8_SCHED;
.LBB0_654:
	s_add_i32 s84, s62, 2
	s_add_u32 s64, s60, 0x80
	s_addc_u32 s63, s61, 0
	s_add_i32 s85, 0, 0x10000
	v_add_u32_e32 v70, s85, v241
	ds_read_b128 v[58:61], v70
	ds_read_b128 v[62:65], v70 offset:1024
	ds_read_b128 v[66:69], v70 offset:2048
	ds_read_b128 v[70:73], v70 offset:3072
	s_cmp_eq_u32 s77, s62
	s_cselect_b32 s62, s2, s64
	s_cselect_b32 s63, s3, s63
	s_cselect_b32 s65, s41, s83
	s_cselect_b32 s64, s40, s82
	s_add_i32 m0, s70, 0xc000
	ds_read_b128 v[146:149], v243
	ds_read_b128 v[150:153], v243 offset:1024
	ds_read_b128 v[154:157], v243 offset:2048
	ds_read_b128 v[158:161], v243 offset:3072
	ds_read_b128 v[162:165], v243 offset:4096
	ds_read_b128 v[166:169], v243 offset:5120
	ds_read_b128 v[170:173], v243 offset:6144
	ds_read_b128 v[174:177], v243 offset:7168
	global_load_lds_dwordx4 v214, s[60:61]
	s_add_i32 m0, s70, 0xe000
	s_nop 0
	global_load_lds_dwordx4 v216, s[60:61]
	s_waitcnt lgkmcnt(8)
	s_barrier
	s_waitcnt lgkmcnt(0)
	s_setprio 1
	s_waitcnt lgkmcnt(0)
	v_mfma_f32_16x16x32_bf16 v[142:145], v[58:61], v[146:149], v[142:145]
	v_mfma_f32_16x16x32_bf16 v[138:141], v[66:69], v[146:149], v[138:141]
	v_mfma_f32_16x16x32_bf16 v[126:129], v[58:61], v[154:157], v[126:129]
	v_mfma_f32_16x16x32_bf16 v[122:125], v[66:69], v[154:157], v[122:125]
	v_mfma_f32_16x16x32_bf16 v[110:113], v[58:61], v[162:165], v[110:113]
	v_mfma_f32_16x16x32_bf16 v[106:109], v[66:69], v[162:165], v[106:109]
	v_mfma_f32_16x16x32_bf16 v[94:97], v[58:61], v[170:173], v[94:97]
	v_mfma_f32_16x16x32_bf16 v[90:93], v[66:69], v[170:173], v[90:93]
	v_mfma_f32_16x16x32_bf16 v[142:145], v[62:65], v[150:153], v[142:145]
	v_mfma_f32_16x16x32_bf16 v[138:141], v[70:73], v[150:153], v[138:141]
	v_mfma_f32_16x16x32_bf16 v[126:129], v[62:65], v[158:161], v[126:129]
	v_mfma_f32_16x16x32_bf16 v[122:125], v[70:73], v[158:161], v[122:125]
	v_mfma_f32_16x16x32_bf16 v[110:113], v[62:65], v[166:169], v[110:113]
	v_mfma_f32_16x16x32_bf16 v[106:109], v[70:73], v[166:169], v[106:109]
	v_mfma_f32_16x16x32_bf16 v[94:97], v[62:65], v[174:177], v[94:97]
	v_mfma_f32_16x16x32_bf16 v[90:93], v[70:73], v[174:177], v[90:93]
	s_setprio 0
	s_barrier
	s_add_i32 s86, 0, 0x14000
	s_add_i32 s85, s85, s69
	v_add_u32_e32 v190, s86, v241
	s_add_u32 s98, s64, s22
	s_addc_u32 s99, s65, s23
	s_mov_b32 m0, s85
	ds_read_b128 v[178:181], v190
	ds_read_b128 v[182:185], v190 offset:1024
	ds_read_b128 v[186:189], v190 offset:2048
	ds_read_b128 v[190:193], v190 offset:3072
	global_load_lds_dwordx4 v0, s[64:65]
	s_add_i32 m0, s85, 0x2000
	s_nop 0
	global_load_lds_dwordx4 v208, s[64:65]
	s_barrier
	s_waitcnt lgkmcnt(0)
	s_setprio 1
	s_waitcnt lgkmcnt(0)
	v_mfma_f32_16x16x32_bf16 v[134:137], v[178:181], v[146:149], v[134:137]
	v_mfma_f32_16x16x32_bf16 v[130:133], v[186:189], v[146:149], v[130:133]
	v_mfma_f32_16x16x32_bf16 v[118:121], v[178:181], v[154:157], v[118:121]
	v_mfma_f32_16x16x32_bf16 v[114:117], v[186:189], v[154:157], v[114:117]
	v_mfma_f32_16x16x32_bf16 v[102:105], v[178:181], v[162:165], v[102:105]
	v_mfma_f32_16x16x32_bf16 v[98:101], v[186:189], v[162:165], v[98:101]
	v_mfma_f32_16x16x32_bf16 v[86:89], v[178:181], v[170:173], v[86:89]
	v_mfma_f32_16x16x32_bf16 v[82:85], v[186:189], v[170:173], v[82:85]
	v_mfma_f32_16x16x32_bf16 v[134:137], v[182:185], v[150:153], v[134:137]
	v_mfma_f32_16x16x32_bf16 v[130:133], v[190:193], v[150:153], v[130:133]
	v_mfma_f32_16x16x32_bf16 v[118:121], v[182:185], v[158:161], v[118:121]
	v_mfma_f32_16x16x32_bf16 v[114:117], v[190:193], v[158:161], v[114:117]
	v_mfma_f32_16x16x32_bf16 v[102:105], v[182:185], v[166:169], v[102:105]
	v_mfma_f32_16x16x32_bf16 v[98:101], v[190:193], v[166:169], v[98:101]
	v_mfma_f32_16x16x32_bf16 v[86:89], v[182:185], v[174:177], v[86:89]
	v_mfma_f32_16x16x32_bf16 v[82:85], v[190:193], v[174:177], v[82:85]
	s_setprio 0
	s_mov_b32 m0, s70
	s_add_u32 s100, s62, s22
	s_addc_u32 s101, s63, s23
	s_barrier
	ds_read_b128 v[146:149], v243 offset:16384
	ds_read_b128 v[150:153], v243 offset:17408
	ds_read_b128 v[154:157], v243 offset:18432
	ds_read_b128 v[158:161], v243 offset:19456
	ds_read_b128 v[162:165], v243 offset:20480
	ds_read_b128 v[166:169], v243 offset:21504
	ds_read_b128 v[170:173], v243 offset:22528
	ds_read_b128 v[174:177], v243 offset:23552
	global_load_lds_dwordx4 v212, s[62:63]
	s_mov_b32 m0, s71
	s_nop 0
	global_load_lds_dwordx4 v210, s[62:63]
	s_barrier
	s_waitcnt lgkmcnt(0)
	s_setprio 1
	s_waitcnt lgkmcnt(0)
	v_mfma_f32_16x16x32_bf16 v[78:81], v[58:61], v[146:149], v[78:81]
	v_mfma_f32_16x16x32_bf16 v[74:77], v[66:69], v[146:149], v[74:77]
	v_mfma_f32_16x16x32_bf16 v[46:49], v[58:61], v[154:157], v[46:49]
	v_mfma_f32_16x16x32_bf16 v[42:45], v[66:69], v[154:157], v[42:45]
	v_mfma_f32_16x16x32_bf16 v[30:33], v[58:61], v[162:165], v[30:33]
	v_mfma_f32_16x16x32_bf16 v[26:29], v[66:69], v[162:165], v[26:29]
	v_mfma_f32_16x16x32_bf16 v[14:17], v[58:61], v[170:173], v[14:17]
	v_mfma_f32_16x16x32_bf16 v[10:13], v[66:69], v[170:173], v[10:13]
	v_mfma_f32_16x16x32_bf16 v[78:81], v[62:65], v[150:153], v[78:81]
	v_mfma_f32_16x16x32_bf16 v[74:77], v[70:73], v[150:153], v[74:77]
	v_mfma_f32_16x16x32_bf16 v[46:49], v[62:65], v[158:161], v[46:49]
	v_mfma_f32_16x16x32_bf16 v[42:45], v[70:73], v[158:161], v[42:45]
	v_mfma_f32_16x16x32_bf16 v[30:33], v[62:65], v[166:169], v[30:33]
	v_mfma_f32_16x16x32_bf16 v[26:29], v[70:73], v[166:169], v[26:29]
	v_mfma_f32_16x16x32_bf16 v[14:17], v[62:65], v[174:177], v[14:17]
	v_mfma_f32_16x16x32_bf16 v[10:13], v[70:73], v[174:177], v[10:13]
	s_setprio 0
	s_barrier
; #define PG8_STAGE(bufoff, gbase, voff) do { _Pragma("unroll") for (int _i = 0; _i < 2; ++_i) \
;         __builtin_amdgcn_global_load_lds((const unsigned*)((const char*)(gbase) + (voff)[_i]), (LAS unsigned*)(lds + (bufoff) + ldsw + _i * 8192), 16, 0, 0); } while (0)
; #define PG8_LDA(dst, b, h) do { _Pragma("unroll") for (int m = 0; m < 4; ++m) _Pragma("unroll") for (int k = 0; k < 2; ++k) dst[m][k] = *(const LAS bf16x8*)(lds + PG8_SA(b, h) + aoff + m * 2048 + k * 1024); } while (0)
; #define PG8_LDB(dst, b, h) do { _Pragma("unroll") for (int n = 0; n < 2; ++n) _Pragma("unroll") for (int k = 0; k < 2; ++k) dst[n][k] = *(const LAS bf16x8*)(lds + PG8_SB(b, h) + boff + n * 2048 + k * 1024); } while (0)
; #define PG8_MMA(ai, bj, At, Bt) do { __builtin_amdgcn_s_setprio(1); _Pragma("unroll") for (int m = 0; m < 4; ++m) _Pragma("unroll") for (int n = 0; n < 2; ++n) _Pragma("unroll") for (int k = 0; k < 2; ++k) \
;         acc[ai][bj][m][n] = __builtin_amdgcn_mfma_f32_16x16x32_bf16(Bt[n][k], At[m][k], acc[ai][bj][m][n], 0, 0, 0); __builtin_amdgcn_s_setprio(0); } while (0)
; #define PG8_WAIT_V(n) asm volatile("s_waitcnt vmcnt(" #n ")" ::: "memory")
; #define PG8_WAIT_L(n) asm volatile("s_waitcnt lgkmcnt(" #n ")" ::: "memory")
; #define PG8_BAR __builtin_amdgcn_s_barrier()
; #define PG8_SCHED __builtin_amdgcn_sched_barrier(0)
; template <class Epi>
; __device__ __forceinline__ void gemm_phase(LAS unsigned char* lds, const Gemm g, const StaticOrder& S, const Epi& E) {
;     ...
;             PG8_STAGE(PG8_SB(0, 1), b2 + hstep, voffB);
;             PG8_WAIT_V(6); PG8_BAR; PG8_MMA(1, 1, At, B1); PG8_BAR;
;             PG8_LDB(B0, 1, 0); PG8_SCHED; PG8_LDA(At, 1, 0); PG8_STAGE(PG8_SA(0, 1), a2 + hstep, voffA);
;             PG8_WAIT_L(8); PG8_BAR; PG8_WAIT_L(0); PG8_MMA(0, 0, At, B0); PG8_BAR; PG8_SCHED;
;             PG8_LDB(B1, 1, 1); PG8_STAGE(PG8_SB(1, 0), b3, voffB);
;             PG8_BAR; PG8_WAIT_L(0); PG8_MMA(0, 1, At, B1); PG8_BAR;
;             PG8_LDA(At, 1, 1); PG8_STAGE(PG8_SA(1, 0), a3, voffA);
;             PG8_BAR; PG8_WAIT_L(0); PG8_MMA(1, 0, At, B0); PG8_BAR; PG8_SCHED;
	s_add_u32 s64, s64, s50
	s_addc_u32 s65, s65, 0
	s_add_i32 s85, s86, s69
	s_mov_b32 m0, s85
	s_add_u32 vcc_lo, s64, s22
	s_addc_u32 vcc_hi, s65, s23
	global_load_lds_dwordx4 v0, s[64:65]
	s_add_i32 m0, s85, 0x2000
	s_nop 0
	global_load_lds_dwordx4 v208, s[64:65]
	s_waitcnt vmcnt(6)
	s_barrier
	s_setprio 1
	v_mfma_f32_16x16x32_bf16 v[54:57], v[178:181], v[146:149], v[54:57]
	v_mfma_f32_16x16x32_bf16 v[50:53], v[186:189], v[146:149], v[50:53]
	v_mfma_f32_16x16x32_bf16 v[38:41], v[178:181], v[154:157], v[38:41]
	v_mfma_f32_16x16x32_bf16 v[34:37], v[186:189], v[154:157], v[34:37]
	v_mfma_f32_16x16x32_bf16 v[22:25], v[178:181], v[162:165], v[22:25]
	v_mfma_f32_16x16x32_bf16 v[18:21], v[186:189], v[162:165], v[18:21]
	v_mfma_f32_16x16x32_bf16 v[6:9], v[178:181], v[170:173], v[6:9]
	v_mfma_f32_16x16x32_bf16 v[2:5], v[186:189], v[170:173], v[2:5]
	v_mfma_f32_16x16x32_bf16 v[54:57], v[182:185], v[150:153], v[54:57]
	v_mfma_f32_16x16x32_bf16 v[50:53], v[190:193], v[150:153], v[50:53]
	v_mfma_f32_16x16x32_bf16 v[38:41], v[182:185], v[158:161], v[38:41]
	v_mfma_f32_16x16x32_bf16 v[34:37], v[190:193], v[158:161], v[34:37]
	v_mfma_f32_16x16x32_bf16 v[22:25], v[182:185], v[166:169], v[22:25]
	v_mfma_f32_16x16x32_bf16 v[18:21], v[190:193], v[166:169], v[18:21]
	v_mfma_f32_16x16x32_bf16 v[6:9], v[182:185], v[174:177], v[6:9]
	v_mfma_f32_16x16x32_bf16 v[2:5], v[190:193], v[174:177], v[2:5]
	s_setprio 0
	s_add_i32 s64, 0, 0x18000
	v_add_u32_e32 v70, s64, v241
	s_barrier
	ds_read_b128 v[58:61], v70
	ds_read_b128 v[62:65], v70 offset:1024
	ds_read_b128 v[66:69], v70 offset:2048
	ds_read_b128 v[70:73], v70 offset:3072
	s_add_u32 s62, s62, s50
	s_addc_u32 s63, s63, 0
	s_mov_b32 m0, s72
	ds_read_b128 v[146:149], v243 offset:32768
	ds_read_b128 v[150:153], v243 offset:33792
	ds_read_b128 v[154:157], v243 offset:34816
	ds_read_b128 v[158:161], v243 offset:35840
	ds_read_b128 v[162:165], v243 offset:36864
	ds_read_b128 v[166:169], v243 offset:37888
	ds_read_b128 v[170:173], v243 offset:38912
	ds_read_b128 v[174:177], v243 offset:39936
	global_load_lds_dwordx4 v212, s[62:63]
	s_mov_b32 m0, s73
	s_nop 0
	global_load_lds_dwordx4 v210, s[62:63]
	s_waitcnt lgkmcnt(8)
	s_barrier
	s_waitcnt lgkmcnt(0)
	s_setprio 1
	s_waitcnt lgkmcnt(0)
	v_mfma_f32_16x16x32_bf16 v[142:145], v[58:61], v[146:149], v[142:145]
	v_mfma_f32_16x16x32_bf16 v[138:141], v[66:69], v[146:149], v[138:141]
	v_mfma_f32_16x16x32_bf16 v[126:129], v[58:61], v[154:157], v[126:129]
	v_mfma_f32_16x16x32_bf16 v[122:125], v[66:69], v[154:157], v[122:125]
	v_mfma_f32_16x16x32_bf16 v[110:113], v[58:61], v[162:165], v[110:113]
	v_mfma_f32_16x16x32_bf16 v[106:109], v[66:69], v[162:165], v[106:109]
	v_mfma_f32_16x16x32_bf16 v[94:97], v[58:61], v[170:173], v[94:97]
	v_mfma_f32_16x16x32_bf16 v[90:93], v[66:69], v[170:173], v[90:93]
	v_mfma_f32_16x16x32_bf16 v[142:145], v[62:65], v[150:153], v[142:145]
	v_mfma_f32_16x16x32_bf16 v[138:141], v[70:73], v[150:153], v[138:141]
	v_mfma_f32_16x16x32_bf16 v[126:129], v[62:65], v[158:161], v[126:129]
	v_mfma_f32_16x16x32_bf16 v[122:125], v[70:73], v[158:161], v[122:125]
	v_mfma_f32_16x16x32_bf16 v[110:113], v[62:65], v[166:169], v[110:113]
	v_mfma_f32_16x16x32_bf16 v[106:109], v[70:73], v[166:169], v[106:109]
	v_mfma_f32_16x16x32_bf16 v[94:97], v[62:65], v[174:177], v[94:97]
	v_mfma_f32_16x16x32_bf16 v[90:93], v[70:73], v[174:177], v[90:93]
	s_setprio 0
	s_barrier
	s_add_i32 s62, 0, 0x1c000
	s_add_i32 s63, s64, s69
	v_add_u32_e32 v190, s62, v241
	s_mov_b32 m0, s63
	ds_read_b128 v[178:181], v190
	ds_read_b128 v[182:185], v190 offset:1024
	ds_read_b128 v[186:189], v190 offset:2048
	ds_read_b128 v[190:193], v190 offset:3072
	global_load_lds_dwordx4 v0, s[98:99]
	s_add_i32 m0, s63, 0x2000
	s_nop 0
	global_load_lds_dwordx4 v208, s[98:99]
	s_barrier
	s_waitcnt lgkmcnt(0)
	s_setprio 1
	s_waitcnt lgkmcnt(0)
	v_mfma_f32_16x16x32_bf16 v[134:137], v[178:181], v[146:149], v[134:137]
	v_mfma_f32_16x16x32_bf16 v[130:133], v[186:189], v[146:149], v[130:133]
	v_mfma_f32_16x16x32_bf16 v[118:121], v[178:181], v[154:157], v[118:121]
	v_mfma_f32_16x16x32_bf16 v[114:117], v[186:189], v[154:157], v[114:117]
	v_mfma_f32_16x16x32_bf16 v[102:105], v[178:181], v[162:165], v[102:105]
	v_mfma_f32_16x16x32_bf16 v[98:101], v[186:189], v[162:165], v[98:101]
	v_mfma_f32_16x16x32_bf16 v[86:89], v[178:181], v[170:173], v[86:89]
	v_mfma_f32_16x16x32_bf16 v[82:85], v[186:189], v[170:173], v[82:85]
	v_mfma_f32_16x16x32_bf16 v[134:137], v[182:185], v[150:153], v[134:137]
	v_mfma_f32_16x16x32_bf16 v[130:133], v[190:193], v[150:153], v[130:133]
	v_mfma_f32_16x16x32_bf16 v[118:121], v[182:185], v[158:161], v[118:121]
	v_mfma_f32_16x16x32_bf16 v[114:117], v[190:193], v[158:161], v[114:117]
	v_mfma_f32_16x16x32_bf16 v[102:105], v[182:185], v[166:169], v[102:105]
	v_mfma_f32_16x16x32_bf16 v[98:101], v[190:193], v[166:169], v[98:101]
	v_mfma_f32_16x16x32_bf16 v[86:89], v[182:185], v[174:177], v[86:89]
	v_mfma_f32_16x16x32_bf16 v[82:85], v[190:193], v[174:177], v[82:85]
	s_setprio 0
	s_mov_b32 m0, s75
	s_barrier
	ds_read_b128 v[146:149], v243 offset:49152
	ds_read_b128 v[150:153], v243 offset:50176
	ds_read_b128 v[154:157], v243 offset:51200
	ds_read_b128 v[158:161], v243 offset:52224
	ds_read_b128 v[162:165], v243 offset:53248
	ds_read_b128 v[166:169], v243 offset:54272
	ds_read_b128 v[170:173], v243 offset:55296
	ds_read_b128 v[174:177], v243 offset:56320
	global_load_lds_dwordx4 v212, s[100:101]
	s_mov_b32 m0, s76
	s_nop 0
	global_load_lds_dwordx4 v210, s[100:101]
	s_barrier
; #define PG8_STAGE(bufoff, gbase, voff) do { _Pragma("unroll") for (int _i = 0; _i < 2; ++_i) \
;         __builtin_amdgcn_global_load_lds((const unsigned*)((const char*)(gbase) + (voff)[_i]), (LAS unsigned*)(lds + (bufoff) + ldsw + _i * 8192), 16, 0, 0); } while (0)
; #define PG8_MMA(ai, bj, At, Bt) do { __builtin_amdgcn_s_setprio(1); _Pragma("unroll") for (int m = 0; m < 4; ++m) _Pragma("unroll") for (int n = 0; n < 2; ++n) _Pragma("unroll") for (int k = 0; k < 2; ++k) \
;         acc[ai][bj][m][n] = __builtin_amdgcn_mfma_f32_16x16x32_bf16(Bt[n][k], At[m][k], acc[ai][bj][m][n], 0, 0, 0); __builtin_amdgcn_s_setprio(0); } while (0)
; #define PG8_WAIT_V(n) asm volatile("s_waitcnt vmcnt(" #n ")" ::: "memory")
; #define PG8_WAIT_L(n) asm volatile("s_waitcnt lgkmcnt(" #n ")" ::: "memory")
; #define PG8_BAR __builtin_amdgcn_s_barrier()
; #define PG8_SCHED __builtin_amdgcn_sched_barrier(0)
; template <class Epi>
; __device__ __forceinline__ void gemm_phase(LAS unsigned char* lds, const Gemm g, const StaticOrder& S, const Epi& E) {
;     ...
;             PG8_BAR; PG8_WAIT_L(0); PG8_MMA(1, 0, At, B0); PG8_BAR; PG8_SCHED;
;             PG8_STAGE(PG8_SB(1, 1), b3 + hstep, voffB);
;             PG8_WAIT_V(6); PG8_BAR; PG8_MMA(1, 1, At, B1); PG8_BAR;
;         }
	s_waitcnt lgkmcnt(0)
	s_setprio 1
	s_waitcnt lgkmcnt(0)
	v_mfma_f32_16x16x32_bf16 v[78:81], v[58:61], v[146:149], v[78:81]
	v_mfma_f32_16x16x32_bf16 v[74:77], v[66:69], v[146:149], v[74:77]
	v_mfma_f32_16x16x32_bf16 v[46:49], v[58:61], v[154:157], v[46:49]
	v_mfma_f32_16x16x32_bf16 v[42:45], v[66:69], v[154:157], v[42:45]
	v_mfma_f32_16x16x32_bf16 v[30:33], v[58:61], v[162:165], v[30:33]
	v_mfma_f32_16x16x32_bf16 v[26:29], v[66:69], v[162:165], v[26:29]
	v_mfma_f32_16x16x32_bf16 v[14:17], v[58:61], v[170:173], v[14:17]
	v_mfma_f32_16x16x32_bf16 v[10:13], v[66:69], v[170:173], v[10:13]
	v_mfma_f32_16x16x32_bf16 v[78:81], v[62:65], v[150:153], v[78:81]
	v_mfma_f32_16x16x32_bf16 v[74:77], v[70:73], v[150:153], v[74:77]
	v_mfma_f32_16x16x32_bf16 v[46:49], v[62:65], v[158:161], v[46:49]
	v_mfma_f32_16x16x32_bf16 v[42:45], v[70:73], v[158:161], v[42:45]
	v_mfma_f32_16x16x32_bf16 v[30:33], v[62:65], v[166:169], v[30:33]
	v_mfma_f32_16x16x32_bf16 v[26:29], v[70:73], v[166:169], v[26:29]
	v_mfma_f32_16x16x32_bf16 v[14:17], v[62:65], v[174:177], v[14:17]
	v_mfma_f32_16x16x32_bf16 v[10:13], v[70:73], v[174:177], v[10:13]
	s_setprio 0
	s_barrier
	s_add_i32 s62, s62, s69
	s_mov_b32 m0, s62
	s_nop 0
	global_load_lds_dwordx4 v0, vcc
	s_add_i32 m0, s62, 0x2000
	s_nop 0
	global_load_lds_dwordx4 v208, vcc
	s_waitcnt vmcnt(6)
	s_barrier
	s_setprio 1
	v_mfma_f32_16x16x32_bf16 v[54:57], v[178:181], v[146:149], v[54:57]
	v_mfma_f32_16x16x32_bf16 v[50:53], v[186:189], v[146:149], v[50:53]
	v_mfma_f32_16x16x32_bf16 v[38:41], v[178:181], v[154:157], v[38:41]
	v_mfma_f32_16x16x32_bf16 v[34:37], v[186:189], v[154:157], v[34:37]
	v_mfma_f32_16x16x32_bf16 v[22:25], v[178:181], v[162:165], v[22:25]
	v_mfma_f32_16x16x32_bf16 v[18:21], v[186:189], v[162:165], v[18:21]
	v_mfma_f32_16x16x32_bf16 v[6:9], v[178:181], v[170:173], v[6:9]
	v_mfma_f32_16x16x32_bf16 v[2:5], v[186:189], v[170:173], v[2:5]
	v_mfma_f32_16x16x32_bf16 v[54:57], v[182:185], v[150:153], v[54:57]
	v_mfma_f32_16x16x32_bf16 v[50:53], v[190:193], v[150:153], v[50:53]
	v_mfma_f32_16x16x32_bf16 v[38:41], v[182:185], v[158:161], v[38:41]
	v_mfma_f32_16x16x32_bf16 v[34:37], v[190:193], v[158:161], v[34:37]
	v_mfma_f32_16x16x32_bf16 v[22:25], v[182:185], v[166:169], v[22:25]
	v_mfma_f32_16x16x32_bf16 v[18:21], v[190:193], v[166:169], v[18:21]
	v_mfma_f32_16x16x32_bf16 v[6:9], v[182:185], v[174:177], v[6:9]
	v_mfma_f32_16x16x32_bf16 v[2:5], v[190:193], v[174:177], v[2:5]
	s_setprio 0
	s_add_u32 s60, s60, 0x100
	s_addc_u32 s61, s61, 0
	s_add_u32 s82, s82, 0x100
	s_addc_u32 s83, s83, 0
	s_cmp_ge_u32 s84, s74
	s_mov_b32 s62, s84
	s_barrier
	s_cbranch_scc0 .LBB0_654
; __device__ __forceinline__ unsigned pk2(float lo, float hi) { f32x2 v = {lo, hi}; bf16x2_t b = __builtin_convertvector(v, bf16x2_t); return __builtin_bit_cast(unsigned, b); }
;     __device__ __forceinline__ void operator()(const AccT& acc, const Unit& u, int wr, int wc, int fr, int fq) const {
;         const int row0 = u.pm * BM + wr * 64 + fr, col0 = u.pn * BM + wc * 32 + 8 * fq;
;         f32x4 gv[2][2];
; #pragma unroll
;         for (int bj = 0; bj < 2; ++bj)
; #pragma unroll
;             for (int n = 0; n < 2; ++n) gv[bj][n] = *(const f32x4*)(g + col0 + bj * HALF + 4 * n);
; #pragma unroll
;         for (int ai = 0; ai < 2; ++ai) {
;             f32x4 xv[4][2][2];
; #pragma unroll
;             for (int m = 0; m < 4; ++m)
; #pragma unroll
;                 for (int bj = 0; bj < 2; ++bj) {
;                     const size_t p = (size_t)(row0 + ai * HALF + m * 16) * DM + col0 + bj * HALF;
;                     xv[m][bj][0] = __builtin_nontemporal_load((const f32x4*)(xin + p)); xv[m][bj][1] = __builtin_nontemporal_load((const f32x4*)(xin + p + 4));
;                 }
; #pragma unroll
;             for (int m = 0; m < 4; ++m) {
;                 const int row = row0 + ai * HALF + m * 16;
;                 float ssa = 0.f;
; #pragma unroll
;                 for (int bj = 0; bj < 2; ++bj) {
;                     const size_t p = (size_t)row * DM + col0 + bj * HALF;
;                     const f32x4 x0 = xv[m][bj][0] + acc[ai][bj][m][0] * alpha, x1 = xv[m][bj][1] + acc[ai][bj][m][1] * alpha;
;                     __builtin_nontemporal_store(x0, (f32x4*)(xout + p)); __builtin_nontemporal_store(x1, (f32x4*)(xout + p + 4));
;                     ssa += (x0[0] * x0[0] + x0[1] * x0[1]) + (x0[2] * x0[2] + x0[3] * x0[3]) + (x1[0] * x1[0] + x1[1] * x1[1]) + (x1[2] * x1[2] + x1[3] * x1[3]);
;                     const f32x4 h0 = x0 * gv[bj][0], h1 = x1 * gv[bj][1];
;                     u32x4 w; w.x = pk2(h0[0], h0[1]); w.y = pk2(h0[2], h0[3]); w.z = pk2(h1[0], h1[1]); w.w = pk2(h1[2], h1[3]);
;                     *(u32x4*)(h + p) = w;
;                 }
;                 ssa += __shfl_xor(ssa, 16); ssa += __shfl_xor(ssa, 32);
;                 if (fq == 0) unsafeAtomicAdd(ssout + row, ssa);
	v_lshl_or_b32 v218, s81, 8, v242
	v_ashrrev_i32_e32 v219, 31, v218
	v_lshl_add_u32 v220, s80, 8, v240
	v_lshlrev_b64 v[146:147], 2, v[218:219]
	v_ashrrev_i32_e32 v221, 31, v220
	v_lshl_add_u64 v[62:63], s[44:45], 0, v[146:147]
	v_lshl_add_u64 v[222:223], s[54:55], 0, v[146:147]
	v_lshlrev_b64 v[146:147], 13, v[220:221]
	v_lshl_add_u64 v[146:147], v[222:223], 0, v[146:147]
	global_load_dwordx4 v[66:69], v[62:63], off offset:16
	global_load_dwordx4 v[70:73], v[62:63], off
	global_load_dwordx4 v[58:61], v[62:63], off offset:528
	s_nop 0
	global_load_dwordx4 v[62:65], v[62:63], off offset:512
	s_nop 0
	global_load_dwordx4 v[246:249], v[146:147], off offset:16 nt
	global_load_dwordx4 v[202:205], v[146:147], off nt
	global_load_dwordx4 v[194:197], v[146:147], off offset:528 nt
	global_load_dwordx4 v[198:201], v[146:147], off offset:512 nt
	v_or_b32_e32 v228, 16, v220
	v_and_b32_e32 v149, 64, v234
	v_ashrrev_i32_e32 v229, 31, v228
	v_xor_b32_e32 v148, 16, v234
	v_add_u32_e32 v149, 64, v149
	v_lshlrev_b64 v[146:147], 13, v[228:229]
	v_or_b32_e32 v226, 32, v220
	v_cmp_lt_i32_e32 vcc, v148, v149
	v_lshl_add_u64 v[146:147], v[222:223], 0, v[146:147]
	v_ashrrev_i32_e32 v227, 31, v226
	v_cndmask_b32_e32 v148, v234, v148, vcc
	global_load_dwordx4 v[186:189], v[146:147], off offset:16 nt
	global_load_dwordx4 v[190:193], v[146:147], off nt
	global_load_dwordx4 v[178:181], v[146:147], off offset:528 nt
	global_load_dwordx4 v[182:185], v[146:147], off offset:512 nt
	v_lshlrev_b64 v[146:147], 13, v[226:227]
	v_or_b32_e32 v224, 48, v220
	v_lshlrev_b32_e32 v245, 2, v148
	v_xor_b32_e32 v148, 32, v234
	v_lshl_add_u64 v[146:147], v[222:223], 0, v[146:147]
	v_ashrrev_i32_e32 v225, 31, v224
	v_cmp_lt_i32_e32 vcc, v148, v149
	global_load_dwordx4 v[170:173], v[146:147], off offset:16 nt
	global_load_dwordx4 v[174:177], v[146:147], off nt
	global_load_dwordx4 v[154:157], v[146:147], off offset:528 nt
	global_load_dwordx4 v[158:161], v[146:147], off offset:512 nt
	v_lshlrev_b64 v[146:147], 13, v[224:225]
	v_cndmask_b32_e32 v148, v234, v148, vcc
	v_lshl_add_u64 v[150:151], v[222:223], 0, v[146:147]
	v_lshlrev_b32_e32 v244, 2, v148
	global_load_dwordx4 v[162:165], v[150:151], off offset:16 nt
	global_load_dwordx4 v[166:169], v[150:151], off nt
	global_load_dwordx4 v[146:149], v[150:151], off offset:528 nt
	s_nop 0
	global_load_dwordx4 v[150:153], v[150:151], off offset:512 nt
	v_lshlrev_b64 v[230:231], 11, v[220:221]
	v_readlane_b32 s60, v251, 56
	v_lshl_add_u64 v[230:231], v[230:231], 0, v[218:219]
	v_readlane_b32 s61, v251, 57
	v_readlane_b32 s62, v254, 8
	v_readlane_b32 s63, v254, 9
	s_waitcnt vmcnt(0)
	v_pk_fma_f32 v[140:141], s[58:59], v[140:141], v[248:249]
	v_pk_fma_f32 v[144:145], s[58:59], v[144:145], v[204:205]
	v_pk_fma_f32 v[142:143], s[46:47], v[142:143], v[202:203]
	v_lshl_add_u64 v[202:203], v[230:231], 2, s[60:61]
	v_pk_fma_f32 v[138:139], s[46:47], v[138:139], v[246:247]
	global_store_dwordx4 v[202:203], v[142:145], off nt
	global_store_dwordx4 v[202:203], v[138:141], off offset:16 nt
	v_mul_f32_e32 v202, v143, v143
	v_mul_f32_e32 v203, v145, v145
	v_fmac_f32_e32 v202, v142, v142
	v_fmac_f32_e32 v203, v144, v144
	v_add_f32_e32 v202, v202, v203
	v_mul_f32_e32 v203, v139, v139
	v_fmac_f32_e32 v203, v138, v138
	v_add_f32_e32 v202, v203, v202
	v_mul_f32_e32 v203, v141, v141
	v_fmac_f32_e32 v203, v140, v140
	v_add_f32_e32 v204, v203, v202
	v_pk_mul_f32 v[144:145], v[72:73], v[144:145]
	v_pk_mul_f32 v[142:143], v[70:71], v[142:143]
	v_pk_mul_f32 v[202:203], v[68:69], v[140:141]
	v_pk_mul_f32 v[140:141], v[66:67], v[138:139]
	v_cvt_pk_bf16_f32 v138, v142, v143
	v_cvt_pk_bf16_f32 v139, v144, v145
	v_cvt_pk_bf16_f32 v140, v140, v141
	v_cvt_pk_bf16_f32 v141, v202, v203
	v_lshl_add_u64 v[142:143], v[230:231], 1, s[62:63]
	v_or_b32_e32 v230, 0x80, v230
	global_store_dwordx4 v[142:143], v[138:141], off
	v_pk_fma_f32 v[136:137], s[58:59], v[136:137], v[200:201]
	v_pk_fma_f32 v[134:135], s[46:47], v[134:135], v[198:199]
	v_lshl_add_u64 v[138:139], v[230:231], 2, s[60:61]
	v_pk_fma_f32 v[132:133], s[58:59], v[132:133], v[196:197]
	v_pk_fma_f32 v[130:131], s[46:47], v[130:131], v[194:195]
	global_store_dwordx4 v[138:139], v[134:137], off nt
	global_store_dwordx4 v[138:139], v[130:133], off offset:16 nt
	v_mul_f32_e32 v138, v135, v135
	v_mul_f32_e32 v139, v137, v137
	v_fmac_f32_e32 v138, v134, v134
	v_fmac_f32_e32 v139, v136, v136
	v_add_f32_e32 v138, v138, v139
	v_mul_f32_e32 v139, v131, v131
	v_fmac_f32_e32 v139, v130, v130
	v_add_f32_e32 v138, v139, v138
	v_mul_f32_e32 v139, v133, v133
	v_fmac_f32_e32 v139, v132, v132
	v_add_f32_e32 v138, v139, v138
	v_add_f32_e32 v140, v204, v138
	v_pk_mul_f32 v[136:137], v[64:65], v[136:137]
	v_pk_mul_f32 v[134:135], v[62:63], v[134:135]
	v_pk_mul_f32 v[138:139], v[60:61], v[132:133]
	v_pk_mul_f32 v[132:133], v[58:59], v[130:131]
	v_cvt_pk_bf16_f32 v130, v134, v135
	v_cvt_pk_bf16_f32 v131, v136, v137
	v_cvt_pk_bf16_f32 v132, v132, v133
	v_cvt_pk_bf16_f32 v133, v138, v139
	v_lshl_add_u64 v[134:135], v[230:231], 1, s[62:63]
	global_store_dwordx4 v[134:135], v[130:133], off
	ds_bpermute_b32 v130, v245, v140
	v_lshl_add_u64 v[138:139], v[220:221], 2, s[56:57]
	s_waitcnt lgkmcnt(0)
	v_add_f32_e32 v130, v140, v130
	ds_bpermute_b32 v131, v244, v130
	s_and_saveexec_b64 s[60:61], s[36:37]
	s_cbranch_execz .LBB0_657
	s_waitcnt lgkmcnt(0)
	v_add_f32_e32 v130, v130, v131
	global_atomic_add_f32 v[138:139], v130, off

; __global__ void __launch_bounds__(NWAVES * 64, 2) fwd_megakernel(Args args) {
	.amdhsa_kernel _Z14fwd_megakernel4Args
		.amdhsa_group_segment_fixed_size 0
		.amdhsa_private_segment_fixed_size 0
		.amdhsa_kernarg_size 472
		.amdhsa_user_sgpr_count 2
		.amdhsa_user_sgpr_dispatch_ptr 0
		.amdhsa_user_sgpr_queue_ptr 0
		.amdhsa_user_sgpr_kernarg_segment_ptr 1
		.amdhsa_user_sgpr_dispatch_id 0
		.amdhsa_user_sgpr_kernarg_preload_length 0
		.amdhsa_user_sgpr_kernarg_preload_offset 0
		.amdhsa_user_sgpr_private_segment_size 0
		.amdhsa_uses_dynamic_stack 0
		.amdhsa_enable_private_segment 0
		.amdhsa_system_sgpr_workgroup_id_x 1
		.amdhsa_system_sgpr_workgroup_id_y 0
		.amdhsa_system_sgpr_workgroup_id_z 0
		.amdhsa_system_sgpr_workgroup_info 0
		.amdhsa_system_vgpr_workitem_id 2
		.amdhsa_next_free_vgpr 255
		.amdhsa_next_free_sgpr 102
		.amdhsa_accum_offset 256
		.amdhsa_reserve_vcc 1
		.amdhsa_float_round_mode_32 0
		.amdhsa_float_round_mode_16_64 0
		.amdhsa_float_denorm_mode_32 3
		.amdhsa_float_denorm_mode_16_64 3
		.amdhsa_dx10_clamp 1
		.amdhsa_ieee_mode 1
		.amdhsa_fp16_overflow 0
		.amdhsa_tg_split 0
		.amdhsa_exception_fp_ieee_invalid_op 0
		.amdhsa_exception_fp_denorm_src 0
		.amdhsa_exception_fp_ieee_div_zero 0
		.amdhsa_exception_fp_ieee_overflow 0
		.amdhsa_exception_fp_ieee_underflow 0
		.amdhsa_exception_fp_ieee_inexact 0
		.amdhsa_exception_int_div_zero 0
	.end_amdhsa_kernel

; __global__ void __launch_bounds__(NWAVES * 64, 2) fwd_megakernel(Args args) {
.Lfunc_end0:
	.size	_Z14fwd_megakernel4Args, .Lfunc_end0-_Z14fwd_megakernel4Args
	.set _Z14fwd_megakernel4Args.num_vgpr, 255
	.set _Z14fwd_megakernel4Args.num_agpr, 0
	.set _Z14fwd_megakernel4Args.numbered_sgpr, 102
	.set _Z14fwd_megakernel4Args.num_named_barrier, 0
	.set _Z14fwd_megakernel4Args.private_seg_size, 0
	.set _Z14fwd_megakernel4Args.uses_vcc, 1
	.set _Z14fwd_megakernel4Args.uses_flat_scratch, 0
	.set _Z14fwd_megakernel4Args.has_dyn_sized_stack, 0
	.set _Z14fwd_megakernel4Args.has_recursion, 0
	.set _Z14fwd_megakernel4Args.has_indirect_call, 0

; __global__ void __launch_bounds__(NWAVES * 64, 2) fwd_megakernel(Args args) {
amdhsa.kernels:
  - .agpr_count:     0
    .args:
      - .offset:         0
        .size:           216
        .value_kind:     by_value
      - .offset:         216
        .size:           4
        .value_kind:     hidden_block_count_x
      - .offset:         220
        .size:           4
        .value_kind:     hidden_block_count_y
      - .offset:         224
        .size:           4
        .value_kind:     hidden_block_count_z
      - .offset:         228
        .size:           2
        .value_kind:     hidden_group_size_x
      - .offset:         230
        .size:           2
        .value_kind:     hidden_group_size_y
      - .offset:         232
        .size:           2
        .value_kind:     hidden_group_size_z
      - .offset:         234
        .size:           2
        .value_kind:     hidden_remainder_x
      - .offset:         236
        .size:           2
        .value_kind:     hidden_remainder_y
      - .offset:         238
        .size:           2
        .value_kind:     hidden_remainder_z
      - .offset:         256
        .size:           8
        .value_kind:     hidden_global_offset_x
      - .offset:         264
        .size:           8
        .value_kind:     hidden_global_offset_y
      - .offset:         272
        .size:           8
        .value_kind:     hidden_global_offset_z
      - .offset:         280
        .size:           2
        .value_kind:     hidden_grid_dims
      - .offset:         304
        .size:           8
        .value_kind:     hidden_multigrid_sync_arg
      - .offset:         336
        .size:           4
        .value_kind:     hidden_dynamic_lds_size
    .group_segment_fixed_size: 0
    .kernarg_segment_align: 8
    .kernarg_segment_size: 472
    .language:       OpenCL C
    .language_version:
      - 2
      - 0
    .max_flat_workgroup_size: 512
    .name:           _Z14fwd_megakernel4Args
    .private_segment_fixed_size: 0
    .sgpr_count:     108
    .sgpr_spill_count: 273
    .symbol:         _Z14fwd_megakernel4Args.kd
    .uniform_work_group_size: 1
    .uses_dynamic_stack: false
    .vgpr_count:     255
    .vgpr_spill_count: 0
    .wavefront_size: 64
